# K-loop load segments: the leading half-workgroup skips the pre-barrier lgkmcnt(0) (only the trailing half's reads are restaged right after that barrier)
# speedup vs baseline: 1.0069x; 1.0015x over previous
; #define PG8_STAGE(bufoff, gbase, voff) do { _Pragma("unroll") for (int _i = 0; _i < 2; ++_i) \
;         __builtin_amdgcn_global_load_lds((const unsigned*)((const char*)(gbase) + (voff)[_i]), (PG8_LAS unsigned*)(lds + (bufoff) + ldsw + _i * 8192), 16, 0, 0); } while (0)
; #define PG8_LDA(dst, b, h) do { _Pragma("unroll") for (int m = 0; m < 4; ++m) _Pragma("unroll") for (int k = 0; k < 2; ++k) dst[m][k] = *(const PG8_LAS bf16x8*)(lds + PG8_SA(b, h) + aoff + m * 2048 + k * 1024); } while (0)
; #define PG8_LDB(dst, b, h) do { _Pragma("unroll") for (int n = 0; n < 2; ++n) _Pragma("unroll") for (int k = 0; k < 2; ++k) dst[n][k] = *(const PG8_LAS bf16x8*)(lds + PG8_SB(b, h) + boff + n * 2048 + k * 1024); } while (0)
; #define PG8_MMA(ai, bj, At, Bt) do { __builtin_amdgcn_s_setprio(1); _Pragma("unroll") for (int m = 0; m < 4; ++m) _Pragma("unroll") for (int n = 0; n < 2; ++n) _Pragma("unroll") for (int k = 0; k < 2; ++k) \
;         acc[ai][bj][m][n] = __builtin_amdgcn_mfma_f32_16x16x32_bf16(Bt[n][k], At[m][k], acc[ai][bj][m][n], 0, 0, 0); __builtin_amdgcn_s_setprio(0); } while (0)
; #define PG8_WAIT_V(n) asm volatile("s_waitcnt vmcnt(" #n ")" ::: "memory")
; #define PG8_WAIT_L(n) asm volatile("s_waitcnt lgkmcnt(" #n ")" ::: "memory")
; #define PG8_BAR __builtin_amdgcn_s_barrier()
; #define PG8_SCHED __builtin_amdgcn_sched_barrier(0)
; template <class Epi, class Sched, bool ALIGN_EPI = false, bool SP2 = false>
; __device__ __forceinline__ void gemm_phase(PG8_LAS unsigned char* lds, const Gemm g, const Sched& S, const Epi& E) {
;     ...
;             PG8_LDB(B0, 0, 0); PG8_LDB(B1, 0, 1); PG8_SCHED; PG8_LDA(At, 0, 0); PG8_STAGE(PG8_SA(1, 1), a1 + hstep, voffA);
;             PG8_WAIT_V(8); PG8_WAIT_L(0); PG8_BAR; PG8_MMA(0, 0, At, B0); PG8_MMA(0, 1, At, B1); PG8_BAR; PG8_SCHED;
;             PG8_LDA(At, 0, 1); PG8_STAGE(PG8_SB(0, 0), b2, voffB); PG8_STAGE(PG8_SB(0, 1), b2 + hstep, voffB); PG8_STAGE(PG8_SA(0, 0), a2, voffA);
;             PG8_WAIT_V(8); PG8_WAIT_L(0); PG8_BAR; PG8_MMA(1, 0, At, B0); PG8_MMA(1, 1, At, B1); PG8_BAR; PG8_SCHED;
.Lpw_110_0:
	s_bitcmp1_b32 s68, 0
	s_cbranch_scc1 .Lnl_110_0
	s_waitcnt lgkmcnt(0)
.Lnl_110_0:
	s_barrier
	s_waitcnt lgkmcnt(0)
	v_mfma_f32_16x16x32_bf16 v[126:129], v[146:149], v[186:189], 0
	v_mfma_f32_16x16x32_bf16 v[122:125], v[154:157], v[186:189], 0
	v_mfma_f32_16x16x32_bf16 v[118:121], v[146:149], v[194:197], 0
	v_mfma_f32_16x16x32_bf16 v[114:117], v[154:157], v[194:197], 0
	v_mfma_f32_16x16x32_bf16 v[110:113], v[146:149], v[202:205], 0
	v_mfma_f32_16x16x32_bf16 v[106:109], v[154:157], v[202:205], 0
	v_mfma_f32_16x16x32_bf16 v[102:105], v[146:149], v[212:215], 0
	v_mfma_f32_16x16x32_bf16 v[98:101], v[154:157], v[212:215], 0
	v_mfma_f32_16x16x32_bf16 v[126:129], v[150:153], v[190:193], v[126:129]
	v_mfma_f32_16x16x32_bf16 v[122:125], v[166:169], v[190:193], v[122:125]
	v_mfma_f32_16x16x32_bf16 v[118:121], v[150:153], v[198:201], v[118:121]
	v_mfma_f32_16x16x32_bf16 v[114:117], v[166:169], v[198:201], v[114:117]
	v_mfma_f32_16x16x32_bf16 v[110:113], v[150:153], v[208:211], v[110:113]
	v_mfma_f32_16x16x32_bf16 v[106:109], v[166:169], v[208:211], v[106:109]
	v_mfma_f32_16x16x32_bf16 v[102:105], v[150:153], v[216:219], v[102:105]
	v_mfma_f32_16x16x32_bf16 v[98:101], v[166:169], v[216:219], v[98:101]
	v_mfma_f32_16x16x32_bf16 v[62:65], v[170:173], v[186:189], 0
	v_mfma_f32_16x16x32_bf16 v[58:61], v[178:181], v[186:189], 0
	v_mfma_f32_16x16x32_bf16 v[54:57], v[170:173], v[194:197], 0
	v_mfma_f32_16x16x32_bf16 v[50:53], v[178:181], v[194:197], 0
	v_mfma_f32_16x16x32_bf16 v[46:49], v[170:173], v[202:205], 0
	v_mfma_f32_16x16x32_bf16 v[42:45], v[178:181], v[202:205], 0
	v_mfma_f32_16x16x32_bf16 v[38:41], v[170:173], v[212:215], 0
	v_mfma_f32_16x16x32_bf16 v[34:37], v[178:181], v[212:215], 0
	v_mfma_f32_16x16x32_bf16 v[62:65], v[174:177], v[190:193], v[62:65]
	v_mfma_f32_16x16x32_bf16 v[58:61], v[182:185], v[190:193], v[58:61]
	v_mfma_f32_16x16x32_bf16 v[54:57], v[174:177], v[198:201], v[54:57]
	v_mfma_f32_16x16x32_bf16 v[50:53], v[182:185], v[198:201], v[50:53]
	v_mfma_f32_16x16x32_bf16 v[46:49], v[174:177], v[208:211], v[46:49]
	v_mfma_f32_16x16x32_bf16 v[42:45], v[182:185], v[208:211], v[42:45]
	v_mfma_f32_16x16x32_bf16 v[38:41], v[174:177], v[216:219], v[38:41]
	v_mfma_f32_16x16x32_bf16 v[34:37], v[182:185], v[216:219], v[34:37]
	s_barrier
	s_add_i32 s85, s30, s87
	s_mov_b32 m0, s85
	ds_read_b128 v[186:189], v162 offset:16384
	ds_read_b128 v[190:193], v162 offset:17408
	ds_read_b128 v[194:197], v162 offset:18432
	ds_read_b128 v[198:201], v162 offset:19456
	ds_read_b128 v[202:205], v162 offset:20480
	ds_read_b128 v[208:211], v162 offset:21504
	ds_read_b128 v[212:215], v162 offset:22528
	ds_read_b128 v[216:219], v162 offset:23552
	global_load_lds_dwordx4 v132, s[8:9]
	s_add_i32 m0, s85, 0x2000
	s_add_u32 vcc_lo, s8, 0x40000
	v_lshl_add_u64 v[222:223], s[8:9], 0, v[136:137]
	s_addc_u32 vcc_hi, s9, 0
	s_add_i32 s85, s31, s87
	global_load_lds_dwordx4 v136, s[8:9]
	s_mov_b32 m0, s85
	v_lshl_add_u64 v[226:227], s[82:83], 0, v[134:135]
	global_load_lds_dwordx4 v132, vcc
	s_add_i32 m0, s85, 0x2000
	s_nop 0
	global_load_lds_dwordx4 v136, vcc
	v_lshl_add_u64 v[224:225], s[82:83], 0, v[130:131]
	s_mov_b32 m0, s81
	s_nop 0
	global_load_lds_dwordx4 v130, s[82:83]
	s_mov_b32 m0, s88
	s_nop 0
	global_load_lds_dwordx4 v134, s[82:83]
	s_waitcnt vmcnt(24)
	s_cmp_gt_u32 s91, 1
	s_cbranch_scc1 .Lpw_110_1
	s_waitcnt vmcnt(8)

; #define PG8_STAGE(bufoff, gbase, voff) do { _Pragma("unroll") for (int _i = 0; _i < 2; ++_i) \
;         __builtin_amdgcn_global_load_lds((const unsigned*)((const char*)(gbase) + (voff)[_i]), (PG8_LAS unsigned*)(lds + (bufoff) + ldsw + _i * 8192), 16, 0, 0); } while (0)
; #define PG8_LDA(dst, b, h) do { _Pragma("unroll") for (int m = 0; m < 4; ++m) _Pragma("unroll") for (int k = 0; k < 2; ++k) dst[m][k] = *(const PG8_LAS bf16x8*)(lds + PG8_SA(b, h) + aoff + m * 2048 + k * 1024); } while (0)
; #define PG8_LDB(dst, b, h) do { _Pragma("unroll") for (int n = 0; n < 2; ++n) _Pragma("unroll") for (int k = 0; k < 2; ++k) dst[n][k] = *(const PG8_LAS bf16x8*)(lds + PG8_SB(b, h) + boff + n * 2048 + k * 1024); } while (0)
; #define PG8_MMA(ai, bj, At, Bt) do { __builtin_amdgcn_s_setprio(1); _Pragma("unroll") for (int m = 0; m < 4; ++m) _Pragma("unroll") for (int n = 0; n < 2; ++n) _Pragma("unroll") for (int k = 0; k < 2; ++k) \
;         acc[ai][bj][m][n] = __builtin_amdgcn_mfma_f32_16x16x32_bf16(Bt[n][k], At[m][k], acc[ai][bj][m][n], 0, 0, 0); __builtin_amdgcn_s_setprio(0); } while (0)
; #define PG8_WAIT_V(n) asm volatile("s_waitcnt vmcnt(" #n ")" ::: "memory")
; #define PG8_WAIT_L(n) asm volatile("s_waitcnt lgkmcnt(" #n ")" ::: "memory")
; #define PG8_BAR __builtin_amdgcn_s_barrier()
; #define PG8_SCHED __builtin_amdgcn_sched_barrier(0)
; template <class Epi, class Sched, bool ALIGN_EPI = false, bool SP2 = false>
; __device__ __forceinline__ void gemm_phase(PG8_LAS unsigned char* lds, const Gemm g, const Sched& S, const Epi& E) {
;     ...
;             PG8_WAIT_V(8); PG8_WAIT_L(0); PG8_BAR; PG8_MMA(0, 0, At, B0); PG8_MMA(0, 1, At, B1); PG8_BAR; PG8_SCHED;
;             PG8_LDA(At, 0, 1); PG8_STAGE(PG8_SB(0, 0), b2, voffB); PG8_STAGE(PG8_SB(0, 1), b2 + hstep, voffB); PG8_STAGE(PG8_SA(0, 0), a2, voffA);
;             PG8_WAIT_V(8); PG8_WAIT_L(0); PG8_BAR; PG8_MMA(1, 0, At, B0); PG8_MMA(1, 1, At, B1); PG8_BAR; PG8_SCHED;
;             PG8_LDB(B0, 1, 0); PG8_LDB(B1, 1, 1); PG8_SCHED; PG8_LDA(At, 1, 0); PG8_STAGE(PG8_SA(0, 1), a2 + hstep, voffA);
;             PG8_WAIT_V(8); PG8_WAIT_L(0); PG8_BAR; PG8_MMA(0, 0, At, B0); PG8_MMA(0, 1, At, B1); PG8_BAR; PG8_SCHED;
.Lnl_110_1:
	s_barrier
	s_waitcnt lgkmcnt(0)
	v_mfma_f32_16x16x32_bf16 v[94:97], v[146:149], v[186:189], 0
	v_mfma_f32_16x16x32_bf16 v[90:93], v[154:157], v[186:189], 0
	v_mfma_f32_16x16x32_bf16 v[86:89], v[146:149], v[194:197], 0
	v_mfma_f32_16x16x32_bf16 v[82:85], v[154:157], v[194:197], 0
	v_mfma_f32_16x16x32_bf16 v[78:81], v[146:149], v[202:205], 0
	v_mfma_f32_16x16x32_bf16 v[74:77], v[154:157], v[202:205], 0
	v_mfma_f32_16x16x32_bf16 v[70:73], v[146:149], v[212:215], 0
	v_mfma_f32_16x16x32_bf16 v[66:69], v[154:157], v[212:215], 0
	v_mfma_f32_16x16x32_bf16 v[94:97], v[150:153], v[190:193], v[94:97]
	v_mfma_f32_16x16x32_bf16 v[90:93], v[166:169], v[190:193], v[90:93]
	v_mfma_f32_16x16x32_bf16 v[86:89], v[150:153], v[198:201], v[86:89]
	v_mfma_f32_16x16x32_bf16 v[82:85], v[166:169], v[198:201], v[82:85]
	v_mfma_f32_16x16x32_bf16 v[78:81], v[150:153], v[208:211], v[78:81]
	v_mfma_f32_16x16x32_bf16 v[74:77], v[166:169], v[208:211], v[74:77]
	v_mfma_f32_16x16x32_bf16 v[70:73], v[150:153], v[216:219], v[70:73]
	v_mfma_f32_16x16x32_bf16 v[66:69], v[166:169], v[216:219], v[66:69]
	v_mfma_f32_16x16x32_bf16 v[30:33], v[170:173], v[186:189], 0
	v_mfma_f32_16x16x32_bf16 v[26:29], v[178:181], v[186:189], 0
	v_mfma_f32_16x16x32_bf16 v[22:25], v[170:173], v[194:197], 0
	v_mfma_f32_16x16x32_bf16 v[18:21], v[178:181], v[194:197], 0
	v_mfma_f32_16x16x32_bf16 v[14:17], v[170:173], v[202:205], 0
	v_mfma_f32_16x16x32_bf16 v[10:13], v[178:181], v[202:205], 0
	v_mfma_f32_16x16x32_bf16 v[6:9], v[170:173], v[212:215], 0
	v_mfma_f32_16x16x32_bf16 v[2:5], v[178:181], v[212:215], 0
	v_mfma_f32_16x16x32_bf16 v[30:33], v[174:177], v[190:193], v[30:33]
	v_mfma_f32_16x16x32_bf16 v[26:29], v[182:185], v[190:193], v[26:29]
	v_mfma_f32_16x16x32_bf16 v[22:25], v[174:177], v[198:201], v[22:25]
	v_mfma_f32_16x16x32_bf16 v[18:21], v[182:185], v[198:201], v[18:21]
	v_mfma_f32_16x16x32_bf16 v[14:17], v[174:177], v[208:211], v[14:17]
	v_mfma_f32_16x16x32_bf16 v[10:13], v[182:185], v[208:211], v[10:13]
	v_mfma_f32_16x16x32_bf16 v[6:9], v[174:177], v[216:219], v[6:9]
	v_mfma_f32_16x16x32_bf16 v[2:5], v[182:185], v[216:219], v[2:5]
	s_barrier
	s_add_i32 s85, 0, 0x18000
	v_add_u32_e32 v165, s85, v158
	s_add_i32 vcc_lo, 0, 0x1c000
	ds_read_b128 v[146:149], v165
	ds_read_b128 v[150:153], v165 offset:1024
	ds_read_b128 v[154:157], v165 offset:2048
	ds_read_b128 v[166:169], v165 offset:3072
	v_add_u32_e32 v165, vcc_lo, v158
	ds_read_b128 v[170:173], v165
	ds_read_b128 v[174:177], v165 offset:1024
	ds_read_b128 v[178:181], v165 offset:2048
	ds_read_b128 v[182:185], v165 offset:3072
	s_add_u32 s82, s82, 0x40000
	s_addc_u32 s83, s83, 0
	s_mov_b32 m0, s89
	ds_read_b128 v[186:189], v162 offset:32768
	ds_read_b128 v[190:193], v162 offset:33792
	ds_read_b128 v[194:197], v162 offset:34816
	ds_read_b128 v[198:201], v162 offset:35840
	ds_read_b128 v[202:205], v162 offset:36864
	ds_read_b128 v[208:211], v162 offset:37888
	ds_read_b128 v[212:215], v162 offset:38912
	ds_read_b128 v[216:219], v162 offset:39936
	global_load_lds_dwordx4 v130, s[82:83]
	s_mov_b32 m0, s90
	s_nop 0
	global_load_lds_dwordx4 v134, s[82:83]
	s_waitcnt vmcnt(8)
	s_bitcmp1_b32 s68, 0
	s_cbranch_scc1 .Lnl_110_2
	s_waitcnt lgkmcnt(0)
.Lnl_110_2:
	s_barrier
	s_waitcnt lgkmcnt(0)
	v_mfma_f32_16x16x32_bf16 v[126:129], v[146:149], v[186:189], v[126:129]
	v_mfma_f32_16x16x32_bf16 v[122:125], v[154:157], v[186:189], v[122:125]
	v_mfma_f32_16x16x32_bf16 v[118:121], v[146:149], v[194:197], v[118:121]
	v_mfma_f32_16x16x32_bf16 v[114:117], v[154:157], v[194:197], v[114:117]
	v_mfma_f32_16x16x32_bf16 v[110:113], v[146:149], v[202:205], v[110:113]
	v_mfma_f32_16x16x32_bf16 v[106:109], v[154:157], v[202:205], v[106:109]
	v_mfma_f32_16x16x32_bf16 v[102:105], v[146:149], v[212:215], v[102:105]
	v_mfma_f32_16x16x32_bf16 v[98:101], v[154:157], v[212:215], v[98:101]
	v_mfma_f32_16x16x32_bf16 v[126:129], v[150:153], v[190:193], v[126:129]
	v_mfma_f32_16x16x32_bf16 v[122:125], v[166:169], v[190:193], v[122:125]
	v_mfma_f32_16x16x32_bf16 v[118:121], v[150:153], v[198:201], v[118:121]
	v_mfma_f32_16x16x32_bf16 v[114:117], v[166:169], v[198:201], v[114:117]
	v_mfma_f32_16x16x32_bf16 v[110:113], v[150:153], v[208:211], v[110:113]
	v_mfma_f32_16x16x32_bf16 v[106:109], v[166:169], v[208:211], v[106:109]
	v_mfma_f32_16x16x32_bf16 v[102:105], v[150:153], v[216:219], v[102:105]
	v_mfma_f32_16x16x32_bf16 v[98:101], v[166:169], v[216:219], v[98:101]
	v_mfma_f32_16x16x32_bf16 v[62:65], v[170:173], v[186:189], v[62:65]
	v_mfma_f32_16x16x32_bf16 v[58:61], v[178:181], v[186:189], v[58:61]
	v_mfma_f32_16x16x32_bf16 v[54:57], v[170:173], v[194:197], v[54:57]
	v_mfma_f32_16x16x32_bf16 v[50:53], v[178:181], v[194:197], v[50:53]
	v_mfma_f32_16x16x32_bf16 v[46:49], v[170:173], v[202:205], v[46:49]
	v_mfma_f32_16x16x32_bf16 v[42:45], v[178:181], v[202:205], v[42:45]
	v_mfma_f32_16x16x32_bf16 v[38:41], v[170:173], v[212:215], v[38:41]
	v_mfma_f32_16x16x32_bf16 v[34:37], v[178:181], v[212:215], v[34:37]
	v_mfma_f32_16x16x32_bf16 v[62:65], v[174:177], v[190:193], v[62:65]
	v_mfma_f32_16x16x32_bf16 v[58:61], v[182:185], v[190:193], v[58:61]
	v_mfma_f32_16x16x32_bf16 v[54:57], v[174:177], v[198:201], v[54:57]
	v_mfma_f32_16x16x32_bf16 v[50:53], v[182:185], v[198:201], v[50:53]
	v_mfma_f32_16x16x32_bf16 v[46:49], v[174:177], v[208:211], v[46:49]
	v_mfma_f32_16x16x32_bf16 v[42:45], v[182:185], v[208:211], v[42:45]
	v_mfma_f32_16x16x32_bf16 v[38:41], v[174:177], v[216:219], v[38:41]
	v_mfma_f32_16x16x32_bf16 v[34:37], v[182:185], v[216:219], v[34:37]
	s_barrier
	s_add_i32 s82, s85, s87
	s_mov_b32 m0, s82
	ds_read_b128 v[186:189], v162 offset:49152
	ds_read_b128 v[190:193], v162 offset:50176
	ds_read_b128 v[194:197], v162 offset:51200
	ds_read_b128 v[198:201], v162 offset:52224
	ds_read_b128 v[202:205], v162 offset:53248
	ds_read_b128 v[208:211], v162 offset:54272
	ds_read_b128 v[212:215], v162 offset:55296
	ds_read_b128 v[216:219], v162 offset:56320
	s_add_u32 s98, s8, s26
	s_addc_u32 s99, s9, s27
	global_load_lds_dwordx4 v132, s[98:99]
	s_add_i32 m0, s82, 0x2000
	s_add_u32 s8, s8, 0x40080
	v_lshl_add_u64 v[220:221], v[222:223], 0, s[26:27]
	s_addc_u32 s9, s9, 0
	s_add_i32 s82, vcc_lo, s87
	global_load_lds_dwordx4 v[220:221], off
	s_mov_b32 m0, s82
	s_nop 0
	global_load_lds_dwordx4 v132, s[8:9]
	s_add_i32 m0, s82, 0x2000
	s_nop 0
	global_load_lds_dwordx4 v136, s[8:9]
	v_lshl_add_u64 v[220:221], v[224:225], 0, s[26:27]
	s_mov_b32 m0, s92
	s_nop 0
	global_load_lds_dwordx4 v[220:221], off
	v_lshl_add_u64 v[220:221], v[226:227], 0, s[26:27]
	s_mov_b32 m0, s93
	s_nop 0
	global_load_lds_dwordx4 v[220:221], off
	s_waitcnt vmcnt(8)
	s_bitcmp1_b32 s68, 0
	s_cbranch_scc1 .Lnl_110_3
	s_waitcnt lgkmcnt(0)
; #define PG8_STAGE(bufoff, gbase, voff) do { _Pragma("unroll") for (int _i = 0; _i < 2; ++_i) \
;         __builtin_amdgcn_global_load_lds((const unsigned*)((const char*)(gbase) + (voff)[_i]), (PG8_LAS unsigned*)(lds + (bufoff) + ldsw + _i * 8192), 16, 0, 0); } while (0)
; #define PG8_LDA(dst, b, h) do { _Pragma("unroll") for (int m = 0; m < 4; ++m) _Pragma("unroll") for (int k = 0; k < 2; ++k) dst[m][k] = *(const PG8_LAS bf16x8*)(lds + PG8_SA(b, h) + aoff + m * 2048 + k * 1024); } while (0)
; #define PG8_LDB(dst, b, h) do { _Pragma("unroll") for (int n = 0; n < 2; ++n) _Pragma("unroll") for (int k = 0; k < 2; ++k) dst[n][k] = *(const PG8_LAS bf16x8*)(lds + PG8_SB(b, h) + boff + n * 2048 + k * 1024); } while (0)
; #define PG8_MMA(ai, bj, At, Bt) do { __builtin_amdgcn_s_setprio(1); _Pragma("unroll") for (int m = 0; m < 4; ++m) _Pragma("unroll") for (int n = 0; n < 2; ++n) _Pragma("unroll") for (int k = 0; k < 2; ++k) \
;         acc[ai][bj][m][n] = __builtin_amdgcn_mfma_f32_16x16x32_bf16(Bt[n][k], At[m][k], acc[ai][bj][m][n], 0, 0, 0); __builtin_amdgcn_s_setprio(0); } while (0)
; #define PG8_WAIT_V(n) asm volatile("s_waitcnt vmcnt(" #n ")" ::: "memory")
; #define PG8_WAIT_L(n) asm volatile("s_waitcnt lgkmcnt(" #n ")" ::: "memory")
; #define PG8_BAR __builtin_amdgcn_s_barrier()
; #define PG8_SCHED __builtin_amdgcn_sched_barrier(0)
; template <class Epi, class Sched, bool ALIGN_EPI = false, bool SP2 = false>
; __device__ __forceinline__ void gemm_phase(PG8_LAS unsigned char* lds, const Gemm g, const Sched& S, const Epi& E) {
;     ...
;             PG8_LDB(B0, 0, 0); PG8_LDB(B1, 0, 1); PG8_SCHED; PG8_LDA(At, 0, 0); PG8_STAGE(PG8_SA(1, 1), a1 + hstep, voffA);
;             PG8_WAIT_V(8); PG8_WAIT_L(0); PG8_BAR; PG8_MMA(0, 0, At, B0); PG8_MMA(0, 1, At, B1); PG8_BAR; PG8_SCHED;
;     ...
;             PG8_LDA(At, 1, 1); PG8_STAGE(PG8_SB(1, 0), b3, voffB); PG8_STAGE(PG8_SB(1, 1), b3 + hstep, voffB); PG8_STAGE(PG8_SA(1, 0), a3, voffA);
;             PG8_WAIT_V(8); PG8_WAIT_L(0); PG8_BAR; PG8_MMA(1, 0, At, B0); PG8_MMA(1, 1, At, B1); PG8_BAR; PG8_SCHED;
.Lnl_110_3:
	s_barrier
	s_waitcnt lgkmcnt(0)
	v_mfma_f32_16x16x32_bf16 v[94:97], v[146:149], v[186:189], v[94:97]
	v_mfma_f32_16x16x32_bf16 v[90:93], v[154:157], v[186:189], v[90:93]
	v_mfma_f32_16x16x32_bf16 v[86:89], v[146:149], v[194:197], v[86:89]
	v_mfma_f32_16x16x32_bf16 v[82:85], v[154:157], v[194:197], v[82:85]
	v_mfma_f32_16x16x32_bf16 v[78:81], v[146:149], v[202:205], v[78:81]
	v_mfma_f32_16x16x32_bf16 v[74:77], v[154:157], v[202:205], v[74:77]
	v_mfma_f32_16x16x32_bf16 v[70:73], v[146:149], v[212:215], v[70:73]
	v_mfma_f32_16x16x32_bf16 v[66:69], v[154:157], v[212:215], v[66:69]
	v_mfma_f32_16x16x32_bf16 v[94:97], v[150:153], v[190:193], v[94:97]
	v_mfma_f32_16x16x32_bf16 v[90:93], v[166:169], v[190:193], v[90:93]
	v_mfma_f32_16x16x32_bf16 v[86:89], v[150:153], v[198:201], v[86:89]
	v_mfma_f32_16x16x32_bf16 v[82:85], v[166:169], v[198:201], v[82:85]
	v_mfma_f32_16x16x32_bf16 v[78:81], v[150:153], v[208:211], v[78:81]
	v_mfma_f32_16x16x32_bf16 v[74:77], v[166:169], v[208:211], v[74:77]
	v_mfma_f32_16x16x32_bf16 v[70:73], v[150:153], v[216:219], v[70:73]
	v_mfma_f32_16x16x32_bf16 v[66:69], v[166:169], v[216:219], v[66:69]
	v_mfma_f32_16x16x32_bf16 v[30:33], v[170:173], v[186:189], v[30:33]
	v_mfma_f32_16x16x32_bf16 v[26:29], v[178:181], v[186:189], v[26:29]
	v_mfma_f32_16x16x32_bf16 v[22:25], v[170:173], v[194:197], v[22:25]
	v_mfma_f32_16x16x32_bf16 v[18:21], v[178:181], v[194:197], v[18:21]
	v_mfma_f32_16x16x32_bf16 v[14:17], v[170:173], v[202:205], v[14:17]
	v_mfma_f32_16x16x32_bf16 v[10:13], v[178:181], v[202:205], v[10:13]
	v_mfma_f32_16x16x32_bf16 v[6:9], v[170:173], v[212:215], v[6:9]
	v_mfma_f32_16x16x32_bf16 v[2:5], v[178:181], v[212:215], v[2:5]
	v_mfma_f32_16x16x32_bf16 v[30:33], v[174:177], v[190:193], v[30:33]
	v_mfma_f32_16x16x32_bf16 v[26:29], v[182:185], v[190:193], v[26:29]
	v_mfma_f32_16x16x32_bf16 v[22:25], v[174:177], v[198:201], v[22:25]
	v_mfma_f32_16x16x32_bf16 v[18:21], v[182:185], v[198:201], v[18:21]
	v_mfma_f32_16x16x32_bf16 v[14:17], v[174:177], v[208:211], v[14:17]
	v_mfma_f32_16x16x32_bf16 v[10:13], v[182:185], v[208:211], v[10:13]
	v_mfma_f32_16x16x32_bf16 v[6:9], v[174:177], v[216:219], v[6:9]
	v_mfma_f32_16x16x32_bf16 v[2:5], v[182:185], v[216:219], v[2:5]
	s_add_i32 s84, s84, 2
	s_add_u32 s6, s6, 0x100
	s_addc_u32 s7, s7, 0
	s_add_u32 s73, s73, 0x100
	s_addc_u32 s75, s75, 0
	s_cmp_gt_u32 s84, 13
	s_barrier
.LBB0_110:
	ds_read_b128 v[146:149], v160
	ds_read_b128 v[150:153], v160 offset:1024
	ds_read_b128 v[154:157], v160 offset:2048
	ds_read_b128 v[166:169], v160 offset:3072
	ds_read_b128 v[170:173], v161
	ds_read_b128 v[174:177], v161 offset:1024
	ds_read_b128 v[178:181], v161 offset:2048
	ds_read_b128 v[182:185], v161 offset:3072
	s_add_u32 s8, s6, 0xfffc0080
	s_addc_u32 s9, s7, -1
	s_cmp_eq_u32 s84, 12
	s_cselect_b32 s83, s1, s9
	s_cselect_b32 s82, s33, s8
	s_cselect_b32 s9, s60, s75
	s_cselect_b32 s8, s61, s73
	v_lshl_add_u64 v[220:221], s[6:7], 0, v[138:139]
	s_add_i32 m0, s81, 0xc000
	ds_read_b128 v[186:189], v162
	ds_read_b128 v[190:193], v162 offset:1024
	ds_read_b128 v[194:197], v162 offset:2048
	ds_read_b128 v[198:201], v162 offset:3072
	ds_read_b128 v[202:205], v162 offset:4096
	ds_read_b128 v[208:211], v162 offset:5120
	ds_read_b128 v[212:215], v162 offset:6144
	ds_read_b128 v[216:219], v162 offset:7168
	global_load_lds_dwordx4 v[220:221], off
	v_lshl_add_u64 v[220:221], s[6:7], 0, v[140:141]
	s_add_i32 m0, s81, 0xe000
	s_nop 0
	global_load_lds_dwordx4 v[220:221], off
	s_waitcnt vmcnt(8)
	s_bitcmp1_b32 s68, 0
	s_cbranch_scc1 .Lnl_110_4
	s_waitcnt lgkmcnt(0)
; #define PG8_STAGE(bufoff, gbase, voff) do { _Pragma("unroll") for (int _i = 0; _i < 2; ++_i) \
;         __builtin_amdgcn_global_load_lds((const unsigned*)((const char*)(gbase) + (voff)[_i]), (PG8_LAS unsigned*)(lds + (bufoff) + ldsw + _i * 8192), 16, 0, 0); } while (0)
; #define PG8_LDA(dst, b, h) do { _Pragma("unroll") for (int m = 0; m < 4; ++m) _Pragma("unroll") for (int k = 0; k < 2; ++k) dst[m][k] = *(const PG8_LAS bf16x8*)(lds + PG8_SA(b, h) + aoff + m * 2048 + k * 1024); } while (0)
; #define PG8_LDB(dst, b, h) do { _Pragma("unroll") for (int n = 0; n < 2; ++n) _Pragma("unroll") for (int k = 0; k < 2; ++k) dst[n][k] = *(const PG8_LAS bf16x8*)(lds + PG8_SB(b, h) + boff + n * 2048 + k * 1024); } while (0)
; #define PG8_MMA(ai, bj, At, Bt) do { __builtin_amdgcn_s_setprio(1); _Pragma("unroll") for (int m = 0; m < 4; ++m) _Pragma("unroll") for (int n = 0; n < 2; ++n) _Pragma("unroll") for (int k = 0; k < 2; ++k) \
;         acc[ai][bj][m][n] = __builtin_amdgcn_mfma_f32_16x16x32_bf16(Bt[n][k], At[m][k], acc[ai][bj][m][n], 0, 0, 0); __builtin_amdgcn_s_setprio(0); } while (0)
; #define PG8_WAIT_V(n) asm volatile("s_waitcnt vmcnt(" #n ")" ::: "memory")
; #define PG8_WAIT_L(n) asm volatile("s_waitcnt lgkmcnt(" #n ")" ::: "memory")
; #define PG8_BAR __builtin_amdgcn_s_barrier()
; #define PG8_SCHED __builtin_amdgcn_sched_barrier(0)
; template <class Epi, class Sched, bool ALIGN_EPI = false, bool SP2 = false>
; __device__ __forceinline__ void gemm_phase(PG8_LAS unsigned char* lds, const Gemm g, const Sched& S, const Epi& E) {
;     ...
;             PG8_WAIT_V(8); PG8_WAIT_L(0); PG8_BAR; PG8_MMA(0, 0, At, B0); PG8_MMA(0, 1, At, B1); PG8_BAR; PG8_SCHED;
;             PG8_LDA(At, 0, 1); PG8_STAGE(PG8_SB(0, 0), b2, voffB); PG8_STAGE(PG8_SB(0, 1), b2 + hstep, voffB); PG8_STAGE(PG8_SA(0, 0), a2, voffA);
;             PG8_WAIT_V(8); PG8_WAIT_L(0); PG8_BAR; PG8_MMA(1, 0, At, B0); PG8_MMA(1, 1, At, B1); PG8_BAR; PG8_SCHED;
;             PG8_LDB(B0, 1, 0); PG8_LDB(B1, 1, 1); PG8_SCHED; PG8_LDA(At, 1, 0); PG8_STAGE(PG8_SA(0, 1), a2 + hstep, voffA);
;             PG8_WAIT_V(8); PG8_WAIT_L(0); PG8_BAR; PG8_MMA(0, 0, At, B0); PG8_MMA(0, 1, At, B1); PG8_BAR; PG8_SCHED;
.Lnl_110_4:
	s_barrier
	s_waitcnt lgkmcnt(0)
	v_mfma_f32_16x16x32_bf16 v[126:129], v[146:149], v[186:189], v[126:129]
	v_mfma_f32_16x16x32_bf16 v[122:125], v[154:157], v[186:189], v[122:125]
	v_mfma_f32_16x16x32_bf16 v[118:121], v[146:149], v[194:197], v[118:121]
	v_mfma_f32_16x16x32_bf16 v[114:117], v[154:157], v[194:197], v[114:117]
	v_mfma_f32_16x16x32_bf16 v[110:113], v[146:149], v[202:205], v[110:113]
	v_mfma_f32_16x16x32_bf16 v[106:109], v[154:157], v[202:205], v[106:109]
	v_mfma_f32_16x16x32_bf16 v[102:105], v[146:149], v[212:215], v[102:105]
	v_mfma_f32_16x16x32_bf16 v[98:101], v[154:157], v[212:215], v[98:101]
	v_mfma_f32_16x16x32_bf16 v[126:129], v[150:153], v[190:193], v[126:129]
	v_mfma_f32_16x16x32_bf16 v[122:125], v[166:169], v[190:193], v[122:125]
	v_mfma_f32_16x16x32_bf16 v[118:121], v[150:153], v[198:201], v[118:121]
	v_mfma_f32_16x16x32_bf16 v[114:117], v[166:169], v[198:201], v[114:117]
	v_mfma_f32_16x16x32_bf16 v[110:113], v[150:153], v[208:211], v[110:113]
	v_mfma_f32_16x16x32_bf16 v[106:109], v[166:169], v[208:211], v[106:109]
	v_mfma_f32_16x16x32_bf16 v[102:105], v[150:153], v[216:219], v[102:105]
	v_mfma_f32_16x16x32_bf16 v[98:101], v[166:169], v[216:219], v[98:101]
	v_mfma_f32_16x16x32_bf16 v[62:65], v[170:173], v[186:189], v[62:65]
	v_mfma_f32_16x16x32_bf16 v[58:61], v[178:181], v[186:189], v[58:61]
	v_mfma_f32_16x16x32_bf16 v[54:57], v[170:173], v[194:197], v[54:57]
	v_mfma_f32_16x16x32_bf16 v[50:53], v[178:181], v[194:197], v[50:53]
	v_mfma_f32_16x16x32_bf16 v[46:49], v[170:173], v[202:205], v[46:49]
	v_mfma_f32_16x16x32_bf16 v[42:45], v[178:181], v[202:205], v[42:45]
	v_mfma_f32_16x16x32_bf16 v[38:41], v[170:173], v[212:215], v[38:41]
	v_mfma_f32_16x16x32_bf16 v[34:37], v[178:181], v[212:215], v[34:37]
	v_mfma_f32_16x16x32_bf16 v[62:65], v[174:177], v[190:193], v[62:65]
	v_mfma_f32_16x16x32_bf16 v[58:61], v[182:185], v[190:193], v[58:61]
	v_mfma_f32_16x16x32_bf16 v[54:57], v[174:177], v[198:201], v[54:57]
	v_mfma_f32_16x16x32_bf16 v[50:53], v[182:185], v[198:201], v[50:53]
	v_mfma_f32_16x16x32_bf16 v[46:49], v[174:177], v[208:211], v[46:49]
	v_mfma_f32_16x16x32_bf16 v[42:45], v[182:185], v[208:211], v[42:45]
	v_mfma_f32_16x16x32_bf16 v[38:41], v[174:177], v[216:219], v[38:41]
	v_mfma_f32_16x16x32_bf16 v[34:37], v[182:185], v[216:219], v[34:37]
	s_barrier
	s_add_i32 s85, s30, s87
	s_mov_b32 m0, s85
	ds_read_b128 v[186:189], v162 offset:16384
	ds_read_b128 v[190:193], v162 offset:17408
	ds_read_b128 v[194:197], v162 offset:18432
	ds_read_b128 v[198:201], v162 offset:19456
	ds_read_b128 v[202:205], v162 offset:20480
	ds_read_b128 v[208:211], v162 offset:21504
	ds_read_b128 v[212:215], v162 offset:22528
	ds_read_b128 v[216:219], v162 offset:23552
	global_load_lds_dwordx4 v132, s[8:9]
	s_add_i32 m0, s85, 0x2000
	s_add_u32 vcc_lo, s8, 0x40000
	v_lshl_add_u64 v[222:223], s[8:9], 0, v[136:137]
	s_addc_u32 vcc_hi, s9, 0
	s_add_i32 s85, s31, s87
	global_load_lds_dwordx4 v136, s[8:9]
	s_mov_b32 m0, s85
	v_lshl_add_u64 v[226:227], s[82:83], 0, v[134:135]
	global_load_lds_dwordx4 v132, vcc
	s_add_i32 m0, s85, 0x2000
	s_nop 0
	global_load_lds_dwordx4 v136, vcc
	v_lshl_add_u64 v[224:225], s[82:83], 0, v[130:131]
	s_mov_b32 m0, s81
	s_nop 0
	global_load_lds_dwordx4 v130, s[82:83]
	s_mov_b32 m0, s88
	s_nop 0
	global_load_lds_dwordx4 v134, s[82:83]
	s_waitcnt vmcnt(8)
	s_bitcmp1_b32 s68, 0
	s_cbranch_scc1 .Lnl_110_5
	s_waitcnt lgkmcnt(0)
.Lnl_110_5:
	s_barrier
	s_waitcnt lgkmcnt(0)
	v_mfma_f32_16x16x32_bf16 v[94:97], v[146:149], v[186:189], v[94:97]
	v_mfma_f32_16x16x32_bf16 v[90:93], v[154:157], v[186:189], v[90:93]
	v_mfma_f32_16x16x32_bf16 v[86:89], v[146:149], v[194:197], v[86:89]
	v_mfma_f32_16x16x32_bf16 v[82:85], v[154:157], v[194:197], v[82:85]
	v_mfma_f32_16x16x32_bf16 v[78:81], v[146:149], v[202:205], v[78:81]
	v_mfma_f32_16x16x32_bf16 v[74:77], v[154:157], v[202:205], v[74:77]
	v_mfma_f32_16x16x32_bf16 v[70:73], v[146:149], v[212:215], v[70:73]
	v_mfma_f32_16x16x32_bf16 v[66:69], v[154:157], v[212:215], v[66:69]
	v_mfma_f32_16x16x32_bf16 v[94:97], v[150:153], v[190:193], v[94:97]
	v_mfma_f32_16x16x32_bf16 v[90:93], v[166:169], v[190:193], v[90:93]
	v_mfma_f32_16x16x32_bf16 v[86:89], v[150:153], v[198:201], v[86:89]
	v_mfma_f32_16x16x32_bf16 v[82:85], v[166:169], v[198:201], v[82:85]
	v_mfma_f32_16x16x32_bf16 v[78:81], v[150:153], v[208:211], v[78:81]
	v_mfma_f32_16x16x32_bf16 v[74:77], v[166:169], v[208:211], v[74:77]
	v_mfma_f32_16x16x32_bf16 v[70:73], v[150:153], v[216:219], v[70:73]
	v_mfma_f32_16x16x32_bf16 v[66:69], v[166:169], v[216:219], v[66:69]
	v_mfma_f32_16x16x32_bf16 v[30:33], v[170:173], v[186:189], v[30:33]
	v_mfma_f32_16x16x32_bf16 v[26:29], v[178:181], v[186:189], v[26:29]
	v_mfma_f32_16x16x32_bf16 v[22:25], v[170:173], v[194:197], v[22:25]
	v_mfma_f32_16x16x32_bf16 v[18:21], v[178:181], v[194:197], v[18:21]
	v_mfma_f32_16x16x32_bf16 v[14:17], v[170:173], v[202:205], v[14:17]
	v_mfma_f32_16x16x32_bf16 v[10:13], v[178:181], v[202:205], v[10:13]
	v_mfma_f32_16x16x32_bf16 v[6:9], v[170:173], v[212:215], v[6:9]
	v_mfma_f32_16x16x32_bf16 v[2:5], v[178:181], v[212:215], v[2:5]
	v_mfma_f32_16x16x32_bf16 v[30:33], v[174:177], v[190:193], v[30:33]
	v_mfma_f32_16x16x32_bf16 v[26:29], v[182:185], v[190:193], v[26:29]
	v_mfma_f32_16x16x32_bf16 v[22:25], v[174:177], v[198:201], v[22:25]
	v_mfma_f32_16x16x32_bf16 v[18:21], v[182:185], v[198:201], v[18:21]
	v_mfma_f32_16x16x32_bf16 v[14:17], v[174:177], v[208:211], v[14:17]
	v_mfma_f32_16x16x32_bf16 v[10:13], v[182:185], v[208:211], v[10:13]
	v_mfma_f32_16x16x32_bf16 v[6:9], v[174:177], v[216:219], v[6:9]
	v_mfma_f32_16x16x32_bf16 v[2:5], v[182:185], v[216:219], v[2:5]
	s_barrier
	s_add_i32 s85, 0, 0x18000
	v_add_u32_e32 v165, s85, v158
	s_add_i32 vcc_lo, 0, 0x1c000
	ds_read_b128 v[146:149], v165
	ds_read_b128 v[150:153], v165 offset:1024
	ds_read_b128 v[154:157], v165 offset:2048
	ds_read_b128 v[166:169], v165 offset:3072
	v_add_u32_e32 v165, vcc_lo, v158
	ds_read_b128 v[170:173], v165
	ds_read_b128 v[174:177], v165 offset:1024
	ds_read_b128 v[178:181], v165 offset:2048
	ds_read_b128 v[182:185], v165 offset:3072
	s_add_u32 s82, s82, 0x40000
	s_addc_u32 s83, s83, 0
	s_mov_b32 m0, s89
	ds_read_b128 v[186:189], v162 offset:32768
	ds_read_b128 v[190:193], v162 offset:33792
	ds_read_b128 v[194:197], v162 offset:34816
	ds_read_b128 v[198:201], v162 offset:35840
	ds_read_b128 v[202:205], v162 offset:36864
	ds_read_b128 v[208:211], v162 offset:37888
	ds_read_b128 v[212:215], v162 offset:38912
	ds_read_b128 v[216:219], v162 offset:39936
	global_load_lds_dwordx4 v130, s[82:83]
	s_mov_b32 m0, s90
	s_nop 0
	global_load_lds_dwordx4 v134, s[82:83]
	s_waitcnt vmcnt(8)
	s_bitcmp1_b32 s68, 0
	s_cbranch_scc1 .Lnl_110_6
	s_waitcnt lgkmcnt(0)

; #define PG8_STAGE(bufoff, gbase, voff) do { _Pragma("unroll") for (int _i = 0; _i < 2; ++_i) \
;         __builtin_amdgcn_global_load_lds((const unsigned*)((const char*)(gbase) + (voff)[_i]), (PG8_LAS unsigned*)(lds + (bufoff) + ldsw + _i * 8192), 16, 0, 0); } while (0)
; #define PG8_LDA(dst, b, h) do { _Pragma("unroll") for (int m = 0; m < 4; ++m) _Pragma("unroll") for (int k = 0; k < 2; ++k) dst[m][k] = *(const PG8_LAS bf16x8*)(lds + PG8_SA(b, h) + aoff + m * 2048 + k * 1024); } while (0)
; #define PG8_MMA(ai, bj, At, Bt) do { __builtin_amdgcn_s_setprio(1); _Pragma("unroll") for (int m = 0; m < 4; ++m) _Pragma("unroll") for (int n = 0; n < 2; ++n) _Pragma("unroll") for (int k = 0; k < 2; ++k) \
;         acc[ai][bj][m][n] = __builtin_amdgcn_mfma_f32_16x16x32_bf16(Bt[n][k], At[m][k], acc[ai][bj][m][n], 0, 0, 0); __builtin_amdgcn_s_setprio(0); } while (0)
; #define PG8_WAIT_V(n) asm volatile("s_waitcnt vmcnt(" #n ")" ::: "memory")
; #define PG8_WAIT_L(n) asm volatile("s_waitcnt lgkmcnt(" #n ")" ::: "memory")
; #define PG8_BAR __builtin_amdgcn_s_barrier()
; #define PG8_SCHED __builtin_amdgcn_sched_barrier(0)
; template <class Epi, class Sched, bool ALIGN_EPI = false, bool SP2 = false>
; __device__ __forceinline__ void gemm_phase(PG8_LAS unsigned char* lds, const Gemm g, const Sched& S, const Epi& E) {
;     ...
;             PG8_LDA(At, 1, 1); PG8_STAGE(PG8_SB(1, 0), b3, voffB); PG8_STAGE(PG8_SB(1, 1), b3 + hstep, voffB); PG8_STAGE(PG8_SA(1, 0), a3, voffA);
;             PG8_WAIT_V(8); PG8_WAIT_L(0); PG8_BAR; PG8_MMA(1, 0, At, B0); PG8_MMA(1, 1, At, B1); PG8_BAR; PG8_SCHED;
;     ...
;         if constexpr (ALIGN_EPI) { if (wr == 0) PG8_BAR; }
.Lnl_110_7:
	s_barrier
	s_waitcnt lgkmcnt(0)
	v_mfma_f32_16x16x32_bf16 v[94:97], v[146:149], v[186:189], v[94:97]
	v_mfma_f32_16x16x32_bf16 v[90:93], v[154:157], v[186:189], v[90:93]
	v_mfma_f32_16x16x32_bf16 v[86:89], v[146:149], v[194:197], v[86:89]
	v_mfma_f32_16x16x32_bf16 v[82:85], v[154:157], v[194:197], v[82:85]
	v_mfma_f32_16x16x32_bf16 v[78:81], v[146:149], v[202:205], v[78:81]
	v_mfma_f32_16x16x32_bf16 v[74:77], v[154:157], v[202:205], v[74:77]
	v_mfma_f32_16x16x32_bf16 v[70:73], v[146:149], v[212:215], v[70:73]
	v_mfma_f32_16x16x32_bf16 v[66:69], v[154:157], v[212:215], v[66:69]
	v_mfma_f32_16x16x32_bf16 v[94:97], v[150:153], v[190:193], v[94:97]
	v_mfma_f32_16x16x32_bf16 v[90:93], v[166:169], v[190:193], v[90:93]
	v_mfma_f32_16x16x32_bf16 v[86:89], v[150:153], v[198:201], v[86:89]
	v_mfma_f32_16x16x32_bf16 v[82:85], v[166:169], v[198:201], v[82:85]
	v_mfma_f32_16x16x32_bf16 v[78:81], v[150:153], v[208:211], v[78:81]
	v_mfma_f32_16x16x32_bf16 v[74:77], v[166:169], v[208:211], v[74:77]
	v_mfma_f32_16x16x32_bf16 v[70:73], v[150:153], v[216:219], v[70:73]
	v_mfma_f32_16x16x32_bf16 v[66:69], v[166:169], v[216:219], v[66:69]
	v_mfma_f32_16x16x32_bf16 v[30:33], v[170:173], v[186:189], v[30:33]
	v_mfma_f32_16x16x32_bf16 v[26:29], v[178:181], v[186:189], v[26:29]
	v_mfma_f32_16x16x32_bf16 v[22:25], v[170:173], v[194:197], v[22:25]
	v_mfma_f32_16x16x32_bf16 v[18:21], v[178:181], v[194:197], v[18:21]
	v_mfma_f32_16x16x32_bf16 v[14:17], v[170:173], v[202:205], v[14:17]
	v_mfma_f32_16x16x32_bf16 v[10:13], v[178:181], v[202:205], v[10:13]
	v_mfma_f32_16x16x32_bf16 v[6:9], v[170:173], v[212:215], v[6:9]
	v_mfma_f32_16x16x32_bf16 v[2:5], v[178:181], v[212:215], v[2:5]
	v_mfma_f32_16x16x32_bf16 v[30:33], v[174:177], v[190:193], v[30:33]
	v_mfma_f32_16x16x32_bf16 v[26:29], v[182:185], v[190:193], v[26:29]
	v_mfma_f32_16x16x32_bf16 v[22:25], v[174:177], v[198:201], v[22:25]
	v_mfma_f32_16x16x32_bf16 v[18:21], v[182:185], v[198:201], v[18:21]
	v_mfma_f32_16x16x32_bf16 v[14:17], v[174:177], v[208:211], v[14:17]
	v_mfma_f32_16x16x32_bf16 v[10:13], v[182:185], v[208:211], v[10:13]
	v_mfma_f32_16x16x32_bf16 v[6:9], v[174:177], v[216:219], v[6:9]
	v_mfma_f32_16x16x32_bf16 v[2:5], v[182:185], v[216:219], v[2:5]
	s_add_i32 s84, s84, 2
	s_add_u32 s6, s6, 0x100
	s_addc_u32 s7, s7, 0
	s_add_u32 s73, s73, 0x100
	s_addc_u32 s75, s75, 0
	s_cmp_gt_u32 s84, 13
	s_barrier
	s_cbranch_scc0 .LBB0_110
	s_mov_b32 s100, 0xbfb8aa3b
	s_mov_b32 s98, 1.0
	s_and_b64 vcc, exec, s[68:69]
	s_cbranch_vccz .LBB0_113
	s_barrier

; #define PG8_STAGE(bufoff, gbase, voff) do { _Pragma("unroll") for (int _i = 0; _i < 2; ++_i) \
;         __builtin_amdgcn_global_load_lds((const unsigned*)((const char*)(gbase) + (voff)[_i]), (PG8_LAS unsigned*)(lds + (bufoff) + ldsw + _i * 8192), 16, 0, 0); } while (0)
; #define PG8_LDA(dst, b, h) do { _Pragma("unroll") for (int m = 0; m < 4; ++m) _Pragma("unroll") for (int k = 0; k < 2; ++k) dst[m][k] = *(const PG8_LAS bf16x8*)(lds + PG8_SA(b, h) + aoff + m * 2048 + k * 1024); } while (0)
; #define PG8_LDB(dst, b, h) do { _Pragma("unroll") for (int n = 0; n < 2; ++n) _Pragma("unroll") for (int k = 0; k < 2; ++k) dst[n][k] = *(const PG8_LAS bf16x8*)(lds + PG8_SB(b, h) + boff + n * 2048 + k * 1024); } while (0)
; #define PG8_WAIT_V(n) asm volatile("s_waitcnt vmcnt(" #n ")" ::: "memory")
; #define PG8_WAIT_L(n) asm volatile("s_waitcnt lgkmcnt(" #n ")" ::: "memory")
; #define PG8_BAR __builtin_amdgcn_s_barrier()
; #define PG8_SCHED __builtin_amdgcn_sched_barrier(0)
; template <class Epi, class Sched, bool ALIGN_EPI = false, bool SP2 = false>
; __device__ __forceinline__ void gemm_phase(PG8_LAS unsigned char* lds, const Gemm g, const Sched& S, const Epi& E) {
;     ...
;         const bool has_next = S.next(ui + 1, nxt);
;         const char* nA = has_next ? (const char*)g.A + (size_t)nxt.pm * tstep : cA; const char* nB = has_next ? (const char*)g.Bt + (size_t)nxt.pn * tstep : cB;
;         for (int t = 0; t < nt; t += 2) {
;             const bool last = (t == nt - 2);
;             const char* a1 = cA + (size_t)(t + 1) * kstep;
;             const char* a2 = last ? nA : cA + (size_t)(t + 2) * kstep; const char* b2 = last ? nB : cB + (size_t)(t + 2) * kstep;
;             const char* a3 = a2 + kstep; const char* b3 = b2 + kstep;
;             if (last && has_next) S.a_ready(nxt);
;             if constexpr (SP2) {
;             PG8_LDB(B0, 0, 0); PG8_LDB(B1, 0, 1); PG8_SCHED; PG8_LDA(At, 0, 0); PG8_STAGE(PG8_SA(1, 1), a1 + hstep, voffA);
;             PG8_WAIT_V(8); PG8_WAIT_L(0); PG8_BAR; PG8_MMA(0, 0, At, B0); PG8_MMA(0, 1, At, B1); PG8_BAR; PG8_SCHED;
;             PG8_LDA(At, 0, 1); PG8_STAGE(PG8_SB(0, 0), b2, voffB); PG8_STAGE(PG8_SB(0, 1), b2 + hstep, voffB); PG8_STAGE(PG8_SA(0, 0), a2, voffA);
;             PG8_WAIT_V(8); PG8_WAIT_L(0); PG8_BAR; PG8_MMA(1, 0, At, B0); PG8_MMA(1, 1, At, B1); PG8_BAR; PG8_SCHED;
.LBB0_645:
	s_ashr_i32 s21, s20, 31
	s_lshl_b64 s[22:23], s[20:21], 19
	s_add_u32 s22, s0, s22
	s_addc_u32 s23, s1, s23
	s_and_b64 s[24:25], s[6:7], exec
	s_cselect_b32 s21, s23, s45
	s_cselect_b32 s27, s22, s44
	s_ashr_i32 s19, s18, 31
	s_lshl_b64 s[24:25], s[18:19], 19
	s_add_u32 s24, s64, s24
	s_addc_u32 s25, s65, s25
	s_and_b64 s[48:49], s[6:7], exec
	s_cselect_b32 s19, s25, s47
	s_cselect_b32 s33, s24, s46
	s_add_u32 s44, s44, 0x40080
	s_addc_u32 s45, s45, 0
	s_add_u32 s71, s46, 0x100
	s_addc_u32 s72, s47, 0
	s_mov_b32 s73, -2
	s_waitcnt lgkmcnt(0)
	ds_read_b128 v[148:151], v152
	ds_read_b128 v[156:159], v152 offset:1024
	ds_read_b128 v[160:163], v152 offset:2048
	ds_read_b128 v[164:167], v152 offset:3072
	ds_read_b128 v[168:171], v153
	ds_read_b128 v[172:175], v153 offset:1024
	ds_read_b128 v[176:179], v153 offset:2048
	ds_read_b128 v[180:183], v153 offset:3072
	s_add_u32 s46, s44, 0xfffc0080
	s_addc_u32 s47, s45, -1
	s_cmp_eq_u32 s73, 12
	s_cselect_b32 s49, s21, s47
	s_cselect_b32 s48, s27, s46
	s_cselect_b32 s47, s19, s72
	s_cselect_b32 s46, s33, s71
	v_lshl_add_u64 v[204:205], s[44:45], 0, v[140:141]
	s_add_i32 m0, s31, 0xc000
	ds_read_b128 v[184:187], v154
	ds_read_b128 v[188:191], v154 offset:1024
	ds_read_b128 v[192:195], v154 offset:2048
	ds_read_b128 v[196:199], v154 offset:3072
	ds_read_b128 v[200:203], v154 offset:4096
	ds_read_b128 v[208:211], v154 offset:5120
	ds_read_b128 v[212:215], v154 offset:6144
	ds_read_b128 v[216:219], v154 offset:7168
	global_load_lds_dwordx4 v[204:205], off
	v_lshl_add_u64 v[204:205], s[44:45], 0, v[142:143]
	s_add_i32 m0, s31, 0xe000
	s_nop 0
	global_load_lds_dwordx4 v[204:205], off
	s_waitcnt vmcnt(8)
	s_bitcmp1_b32 s16, 0
	s_cbranch_scc1 .Lnl_646_0
	s_waitcnt lgkmcnt(0)
.Lnl_646_0:
	s_barrier
	s_waitcnt lgkmcnt(0)
	v_mfma_f32_16x16x32_bf16 v[126:129], v[148:151], v[184:187], 0
	v_mfma_f32_16x16x32_bf16 v[122:125], v[160:163], v[184:187], 0
	v_mfma_f32_16x16x32_bf16 v[110:113], v[148:151], v[192:195], 0
	v_mfma_f32_16x16x32_bf16 v[106:109], v[160:163], v[192:195], 0
	v_mfma_f32_16x16x32_bf16 v[94:97], v[148:151], v[200:203], 0
	v_mfma_f32_16x16x32_bf16 v[90:93], v[160:163], v[200:203], 0
	v_mfma_f32_16x16x32_bf16 v[78:81], v[148:151], v[212:215], 0
	v_mfma_f32_16x16x32_bf16 v[74:77], v[160:163], v[212:215], 0
	v_mfma_f32_16x16x32_bf16 v[126:129], v[156:159], v[188:191], v[126:129]
	v_mfma_f32_16x16x32_bf16 v[122:125], v[164:167], v[188:191], v[122:125]
	v_mfma_f32_16x16x32_bf16 v[110:113], v[156:159], v[196:199], v[110:113]
	v_mfma_f32_16x16x32_bf16 v[106:109], v[164:167], v[196:199], v[106:109]
	v_mfma_f32_16x16x32_bf16 v[94:97], v[156:159], v[208:211], v[94:97]
	v_mfma_f32_16x16x32_bf16 v[90:93], v[164:167], v[208:211], v[90:93]
	v_mfma_f32_16x16x32_bf16 v[78:81], v[156:159], v[216:219], v[78:81]
	v_mfma_f32_16x16x32_bf16 v[74:77], v[164:167], v[216:219], v[74:77]
	v_mfma_f32_16x16x32_bf16 v[118:121], v[168:171], v[184:187], 0
	v_mfma_f32_16x16x32_bf16 v[114:117], v[176:179], v[184:187], 0
	v_mfma_f32_16x16x32_bf16 v[102:105], v[168:171], v[192:195], 0
	v_mfma_f32_16x16x32_bf16 v[98:101], v[176:179], v[192:195], 0
	v_mfma_f32_16x16x32_bf16 v[86:89], v[168:171], v[200:203], 0
	v_mfma_f32_16x16x32_bf16 v[82:85], v[176:179], v[200:203], 0
	v_mfma_f32_16x16x32_bf16 v[70:73], v[168:171], v[212:215], 0
	v_mfma_f32_16x16x32_bf16 v[66:69], v[176:179], v[212:215], 0
	v_mfma_f32_16x16x32_bf16 v[118:121], v[172:175], v[188:191], v[118:121]
	v_mfma_f32_16x16x32_bf16 v[114:117], v[180:183], v[188:191], v[114:117]
	v_mfma_f32_16x16x32_bf16 v[102:105], v[172:175], v[196:199], v[102:105]
	v_mfma_f32_16x16x32_bf16 v[98:101], v[180:183], v[196:199], v[98:101]
	v_mfma_f32_16x16x32_bf16 v[86:89], v[172:175], v[208:211], v[86:89]
	v_mfma_f32_16x16x32_bf16 v[82:85], v[180:183], v[208:211], v[82:85]
	v_mfma_f32_16x16x32_bf16 v[70:73], v[172:175], v[216:219], v[70:73]
	v_mfma_f32_16x16x32_bf16 v[66:69], v[180:183], v[216:219], v[66:69]
	s_barrier
	s_add_i32 s74, s68, s30
	s_mov_b32 m0, s74
	ds_read_b128 v[184:187], v154 offset:16384
	ds_read_b128 v[188:191], v154 offset:17408
	ds_read_b128 v[192:195], v154 offset:18432
	ds_read_b128 v[196:199], v154 offset:19456
	ds_read_b128 v[200:203], v154 offset:20480
	ds_read_b128 v[208:211], v154 offset:21504
	ds_read_b128 v[212:215], v154 offset:22528
	ds_read_b128 v[216:219], v154 offset:23552
	global_load_lds_dwordx4 v132, s[46:47]
	s_add_i32 m0, s74, 0x2000
	s_add_u32 s74, s46, 0x40000
	v_lshl_add_u64 v[220:221], s[46:47], 0, v[136:137]
	s_addc_u32 s75, s47, 0
	s_add_i32 s76, s69, s30
	global_load_lds_dwordx4 v136, s[46:47]
	s_mov_b32 m0, s76
	v_lshl_add_u64 v[224:225], s[48:49], 0, v[134:135]
	global_load_lds_dwordx4 v132, s[74:75]
	s_add_i32 m0, s76, 0x2000
	s_nop 0
	global_load_lds_dwordx4 v136, s[74:75]
	v_lshl_add_u64 v[222:223], s[48:49], 0, v[130:131]
	s_mov_b32 m0, s31
	s_nop 0
	global_load_lds_dwordx4 v130, s[48:49]
	s_mov_b32 m0, s50
	s_nop 0
	global_load_lds_dwordx4 v134, s[48:49]
	s_waitcnt vmcnt(8)
	s_bitcmp1_b32 s16, 0
	s_cbranch_scc1 .Lnl_646_1
	s_waitcnt lgkmcnt(0)
; #define PG8_STAGE(bufoff, gbase, voff) do { _Pragma("unroll") for (int _i = 0; _i < 2; ++_i) \
;         __builtin_amdgcn_global_load_lds((const unsigned*)((const char*)(gbase) + (voff)[_i]), (PG8_LAS unsigned*)(lds + (bufoff) + ldsw + _i * 8192), 16, 0, 0); } while (0)
; #define PG8_LDA(dst, b, h) do { _Pragma("unroll") for (int m = 0; m < 4; ++m) _Pragma("unroll") for (int k = 0; k < 2; ++k) dst[m][k] = *(const PG8_LAS bf16x8*)(lds + PG8_SA(b, h) + aoff + m * 2048 + k * 1024); } while (0)
; #define PG8_LDB(dst, b, h) do { _Pragma("unroll") for (int n = 0; n < 2; ++n) _Pragma("unroll") for (int k = 0; k < 2; ++k) dst[n][k] = *(const PG8_LAS bf16x8*)(lds + PG8_SB(b, h) + boff + n * 2048 + k * 1024); } while (0)
; #define PG8_MMA(ai, bj, At, Bt) do { __builtin_amdgcn_s_setprio(1); _Pragma("unroll") for (int m = 0; m < 4; ++m) _Pragma("unroll") for (int n = 0; n < 2; ++n) _Pragma("unroll") for (int k = 0; k < 2; ++k) \
;         acc[ai][bj][m][n] = __builtin_amdgcn_mfma_f32_16x16x32_bf16(Bt[n][k], At[m][k], acc[ai][bj][m][n], 0, 0, 0); __builtin_amdgcn_s_setprio(0); } while (0)
; #define PG8_WAIT_V(n) asm volatile("s_waitcnt vmcnt(" #n ")" ::: "memory")
; template <class Epi, class Sched, bool ALIGN_EPI = false, bool SP2 = false>
; __device__ __forceinline__ void gemm_phase(PG8_LAS unsigned char* lds, const Gemm g, const Sched& S, const Epi& E) {
;     ...
;             PG8_LDB(B0, 0, 0); PG8_LDB(B1, 0, 1); PG8_SCHED; PG8_LDA(At, 0, 0); PG8_STAGE(PG8_SA(1, 1), a1 + hstep, voffA);
;             PG8_WAIT_V(8); PG8_WAIT_L(0); PG8_BAR; PG8_MMA(0, 0, At, B0); PG8_MMA(0, 1, At, B1); PG8_BAR; PG8_SCHED;
;             PG8_LDA(At, 0, 1); PG8_STAGE(PG8_SB(0, 0), b2, voffB); PG8_STAGE(PG8_SB(0, 1), b2 + hstep, voffB); PG8_STAGE(PG8_SA(0, 0), a2, voffA);
;             PG8_WAIT_V(8); PG8_WAIT_L(0); PG8_BAR; PG8_MMA(1, 0, At, B0); PG8_MMA(1, 1, At, B1); PG8_BAR; PG8_SCHED;
;             PG8_LDB(B0, 1, 0); PG8_LDB(B1, 1, 1); PG8_SCHED; PG8_LDA(At, 1, 0); PG8_STAGE(PG8_SA(0, 1), a2 + hstep, voffA);
;             PG8_WAIT_V(8); PG8_WAIT_L(0); PG8_BAR; PG8_MMA(0, 0, At, B0); PG8_MMA(0, 1, At, B1); PG8_BAR; PG8_SCHED;
;             PG8_LDA(At, 1, 1); PG8_STAGE(PG8_SB(1, 0), b3, voffB); PG8_STAGE(PG8_SB(1, 1), b3 + hstep, voffB); PG8_STAGE(PG8_SA(1, 0), a3, voffA);
;             PG8_WAIT_V(8); PG8_WAIT_L(0); PG8_BAR; PG8_MMA(1, 0, At, B0); PG8_MMA(1, 1, At, B1); PG8_BAR; PG8_SCHED;
.Lnl_646_1:
	s_barrier
	s_waitcnt lgkmcnt(0)
	v_mfma_f32_16x16x32_bf16 v[62:65], v[148:151], v[184:187], 0
	v_mfma_f32_16x16x32_bf16 v[58:61], v[160:163], v[184:187], 0
	v_mfma_f32_16x16x32_bf16 v[46:49], v[148:151], v[192:195], 0
	v_mfma_f32_16x16x32_bf16 v[42:45], v[160:163], v[192:195], 0
	v_mfma_f32_16x16x32_bf16 v[30:33], v[148:151], v[200:203], 0
	v_mfma_f32_16x16x32_bf16 v[26:29], v[160:163], v[200:203], 0
	v_mfma_f32_16x16x32_bf16 v[14:17], v[148:151], v[212:215], 0
	v_mfma_f32_16x16x32_bf16 v[10:13], v[160:163], v[212:215], 0
	v_mfma_f32_16x16x32_bf16 v[62:65], v[156:159], v[188:191], v[62:65]
	v_mfma_f32_16x16x32_bf16 v[58:61], v[164:167], v[188:191], v[58:61]
	v_mfma_f32_16x16x32_bf16 v[46:49], v[156:159], v[196:199], v[46:49]
	v_mfma_f32_16x16x32_bf16 v[42:45], v[164:167], v[196:199], v[42:45]
	v_mfma_f32_16x16x32_bf16 v[30:33], v[156:159], v[208:211], v[30:33]
	v_mfma_f32_16x16x32_bf16 v[26:29], v[164:167], v[208:211], v[26:29]
	v_mfma_f32_16x16x32_bf16 v[14:17], v[156:159], v[216:219], v[14:17]
	v_mfma_f32_16x16x32_bf16 v[10:13], v[164:167], v[216:219], v[10:13]
	v_mfma_f32_16x16x32_bf16 v[54:57], v[168:171], v[184:187], 0
	v_mfma_f32_16x16x32_bf16 v[50:53], v[176:179], v[184:187], 0
	v_mfma_f32_16x16x32_bf16 v[38:41], v[168:171], v[192:195], 0
	v_mfma_f32_16x16x32_bf16 v[34:37], v[176:179], v[192:195], 0
	v_mfma_f32_16x16x32_bf16 v[22:25], v[168:171], v[200:203], 0
	v_mfma_f32_16x16x32_bf16 v[18:21], v[176:179], v[200:203], 0
	v_mfma_f32_16x16x32_bf16 v[6:9], v[168:171], v[212:215], 0
	v_mfma_f32_16x16x32_bf16 v[2:5], v[176:179], v[212:215], 0
	v_mfma_f32_16x16x32_bf16 v[54:57], v[172:175], v[188:191], v[54:57]
	v_mfma_f32_16x16x32_bf16 v[50:53], v[180:183], v[188:191], v[50:53]
	v_mfma_f32_16x16x32_bf16 v[38:41], v[172:175], v[196:199], v[38:41]
	v_mfma_f32_16x16x32_bf16 v[34:37], v[180:183], v[196:199], v[34:37]
	v_mfma_f32_16x16x32_bf16 v[22:25], v[172:175], v[208:211], v[22:25]
	v_mfma_f32_16x16x32_bf16 v[18:21], v[180:183], v[208:211], v[18:21]
	v_mfma_f32_16x16x32_bf16 v[6:9], v[172:175], v[216:219], v[6:9]
	v_mfma_f32_16x16x32_bf16 v[2:5], v[180:183], v[216:219], v[2:5]
	s_barrier
	s_add_i32 s74, 0, 0x18000
	s_add_i32 s75, 0, 0x1c000
	v_add_u32_e32 v164, s74, v139
	v_add_u32_e32 v180, s75, v139
	ds_read_b128 v[148:151], v164
	ds_read_b128 v[156:159], v164 offset:1024
	ds_read_b128 v[160:163], v164 offset:2048
	ds_read_b128 v[164:167], v164 offset:3072
	ds_read_b128 v[168:171], v180
	ds_read_b128 v[172:175], v180 offset:1024
	ds_read_b128 v[176:179], v180 offset:2048
	ds_read_b128 v[180:183], v180 offset:3072
	s_add_u32 s48, s48, 0x40000
	s_addc_u32 s49, s49, 0
	s_mov_b32 m0, s51
	ds_read_b128 v[184:187], v154 offset:32768
	ds_read_b128 v[188:191], v154 offset:33792
	ds_read_b128 v[192:195], v154 offset:34816
	ds_read_b128 v[196:199], v154 offset:35840
	ds_read_b128 v[200:203], v154 offset:36864
	ds_read_b128 v[208:211], v154 offset:37888
	ds_read_b128 v[212:215], v154 offset:38912
	ds_read_b128 v[216:219], v154 offset:39936
	global_load_lds_dwordx4 v130, s[48:49]
	s_mov_b32 m0, s60
	s_nop 0
	global_load_lds_dwordx4 v134, s[48:49]
	s_waitcnt vmcnt(8)
	s_bitcmp1_b32 s16, 0
	s_cbranch_scc1 .Lnl_646_2
	s_waitcnt lgkmcnt(0)
.Lnl_646_2:
	s_barrier
	s_waitcnt lgkmcnt(0)
	v_mfma_f32_16x16x32_bf16 v[126:129], v[148:151], v[184:187], v[126:129]
	v_mfma_f32_16x16x32_bf16 v[122:125], v[160:163], v[184:187], v[122:125]
	v_mfma_f32_16x16x32_bf16 v[110:113], v[148:151], v[192:195], v[110:113]
	v_mfma_f32_16x16x32_bf16 v[106:109], v[160:163], v[192:195], v[106:109]
	v_mfma_f32_16x16x32_bf16 v[94:97], v[148:151], v[200:203], v[94:97]
	v_mfma_f32_16x16x32_bf16 v[90:93], v[160:163], v[200:203], v[90:93]
	v_mfma_f32_16x16x32_bf16 v[78:81], v[148:151], v[212:215], v[78:81]
	v_mfma_f32_16x16x32_bf16 v[74:77], v[160:163], v[212:215], v[74:77]
	v_mfma_f32_16x16x32_bf16 v[126:129], v[156:159], v[188:191], v[126:129]
	v_mfma_f32_16x16x32_bf16 v[122:125], v[164:167], v[188:191], v[122:125]
	v_mfma_f32_16x16x32_bf16 v[110:113], v[156:159], v[196:199], v[110:113]
	v_mfma_f32_16x16x32_bf16 v[106:109], v[164:167], v[196:199], v[106:109]
	v_mfma_f32_16x16x32_bf16 v[94:97], v[156:159], v[208:211], v[94:97]
	v_mfma_f32_16x16x32_bf16 v[90:93], v[164:167], v[208:211], v[90:93]
	v_mfma_f32_16x16x32_bf16 v[78:81], v[156:159], v[216:219], v[78:81]
	v_mfma_f32_16x16x32_bf16 v[74:77], v[164:167], v[216:219], v[74:77]
	v_mfma_f32_16x16x32_bf16 v[118:121], v[168:171], v[184:187], v[118:121]
	v_mfma_f32_16x16x32_bf16 v[114:117], v[176:179], v[184:187], v[114:117]
	v_mfma_f32_16x16x32_bf16 v[102:105], v[168:171], v[192:195], v[102:105]
	v_mfma_f32_16x16x32_bf16 v[98:101], v[176:179], v[192:195], v[98:101]
	v_mfma_f32_16x16x32_bf16 v[86:89], v[168:171], v[200:203], v[86:89]
	v_mfma_f32_16x16x32_bf16 v[82:85], v[176:179], v[200:203], v[82:85]
	v_mfma_f32_16x16x32_bf16 v[70:73], v[168:171], v[212:215], v[70:73]
	v_mfma_f32_16x16x32_bf16 v[66:69], v[176:179], v[212:215], v[66:69]
	v_mfma_f32_16x16x32_bf16 v[118:121], v[172:175], v[188:191], v[118:121]
	v_mfma_f32_16x16x32_bf16 v[114:117], v[180:183], v[188:191], v[114:117]
	v_mfma_f32_16x16x32_bf16 v[102:105], v[172:175], v[196:199], v[102:105]
	v_mfma_f32_16x16x32_bf16 v[98:101], v[180:183], v[196:199], v[98:101]
	v_mfma_f32_16x16x32_bf16 v[86:89], v[172:175], v[208:211], v[86:89]
	v_mfma_f32_16x16x32_bf16 v[82:85], v[180:183], v[208:211], v[82:85]
	v_mfma_f32_16x16x32_bf16 v[70:73], v[172:175], v[216:219], v[70:73]
	v_mfma_f32_16x16x32_bf16 v[66:69], v[180:183], v[216:219], v[66:69]
	s_barrier
	s_add_i32 s48, s74, s30
	s_mov_b32 m0, s48
	ds_read_b128 v[184:187], v154 offset:49152
	ds_read_b128 v[188:191], v154 offset:50176
	ds_read_b128 v[192:195], v154 offset:51200
	ds_read_b128 v[196:199], v154 offset:52224
	ds_read_b128 v[200:203], v154 offset:53248
	ds_read_b128 v[208:211], v154 offset:54272
	ds_read_b128 v[212:215], v154 offset:55296
	ds_read_b128 v[216:219], v154 offset:56320
	s_add_u32 s98, s46, s14
	s_addc_u32 s99, s47, s15
	global_load_lds_dwordx4 v132, s[98:99]
	s_add_i32 m0, s48, 0x2000
	s_add_u32 s46, s46, 0x40080
	v_lshl_add_u64 v[204:205], v[220:221], 0, s[14:15]
	s_addc_u32 s47, s47, 0
	s_add_i32 s48, s75, s30
	global_load_lds_dwordx4 v[204:205], off
	s_mov_b32 m0, s48
	s_nop 0
	global_load_lds_dwordx4 v132, s[46:47]
	s_add_i32 m0, s48, 0x2000
	s_nop 0
	global_load_lds_dwordx4 v136, s[46:47]
	v_lshl_add_u64 v[204:205], v[222:223], 0, s[14:15]
	s_mov_b32 m0, s62
	s_nop 0
	global_load_lds_dwordx4 v[204:205], off
	v_lshl_add_u64 v[204:205], v[224:225], 0, s[14:15]
	s_mov_b32 m0, s63
	s_nop 0
	global_load_lds_dwordx4 v[204:205], off
	s_waitcnt vmcnt(8)
	s_bitcmp1_b32 s16, 0
	s_cbranch_scc1 .Lnl_646_3
	s_waitcnt lgkmcnt(0)
; #define PG8_STAGE(bufoff, gbase, voff) do { _Pragma("unroll") for (int _i = 0; _i < 2; ++_i) \
;         __builtin_amdgcn_global_load_lds((const unsigned*)((const char*)(gbase) + (voff)[_i]), (PG8_LAS unsigned*)(lds + (bufoff) + ldsw + _i * 8192), 16, 0, 0); } while (0)
; #define PG8_LDA(dst, b, h) do { _Pragma("unroll") for (int m = 0; m < 4; ++m) _Pragma("unroll") for (int k = 0; k < 2; ++k) dst[m][k] = *(const PG8_LAS bf16x8*)(lds + PG8_SA(b, h) + aoff + m * 2048 + k * 1024); } while (0)
; #define PG8_LDB(dst, b, h) do { _Pragma("unroll") for (int n = 0; n < 2; ++n) _Pragma("unroll") for (int k = 0; k < 2; ++k) dst[n][k] = *(const PG8_LAS bf16x8*)(lds + PG8_SB(b, h) + boff + n * 2048 + k * 1024); } while (0)
; #define PG8_SCHED __builtin_amdgcn_sched_barrier(0)
; template <class Epi, class Sched, bool ALIGN_EPI = false, bool SP2 = false>
; __device__ __forceinline__ void gemm_phase(PG8_LAS unsigned char* lds, const Gemm g, const Sched& S, const Epi& E) {
;     ...
;         for (int t = 0; t < nt; t += 2) {
;             const bool last = (t == nt - 2);
;             const char* a1 = cA + (size_t)(t + 1) * kstep;
;             const char* a2 = last ? nA : cA + (size_t)(t + 2) * kstep; const char* b2 = last ? nB : cB + (size_t)(t + 2) * kstep;
;             const char* a3 = a2 + kstep; const char* b3 = b2 + kstep;
;             if (last && has_next) S.a_ready(nxt);
;             if constexpr (SP2) {
;             PG8_LDB(B0, 0, 0); PG8_LDB(B1, 0, 1); PG8_SCHED; PG8_LDA(At, 0, 0); PG8_STAGE(PG8_SA(1, 1), a1 + hstep, voffA);
.Lnl_646_3:
	s_barrier
	s_waitcnt lgkmcnt(0)
	v_mfma_f32_16x16x32_bf16 v[62:65], v[148:151], v[184:187], v[62:65]
	v_mfma_f32_16x16x32_bf16 v[58:61], v[160:163], v[184:187], v[58:61]
	v_mfma_f32_16x16x32_bf16 v[46:49], v[148:151], v[192:195], v[46:49]
	v_mfma_f32_16x16x32_bf16 v[42:45], v[160:163], v[192:195], v[42:45]
	v_mfma_f32_16x16x32_bf16 v[30:33], v[148:151], v[200:203], v[30:33]
	v_mfma_f32_16x16x32_bf16 v[26:29], v[160:163], v[200:203], v[26:29]
	v_mfma_f32_16x16x32_bf16 v[14:17], v[148:151], v[212:215], v[14:17]
	v_mfma_f32_16x16x32_bf16 v[10:13], v[160:163], v[212:215], v[10:13]
	v_mfma_f32_16x16x32_bf16 v[62:65], v[156:159], v[188:191], v[62:65]
	v_mfma_f32_16x16x32_bf16 v[58:61], v[164:167], v[188:191], v[58:61]
	v_mfma_f32_16x16x32_bf16 v[46:49], v[156:159], v[196:199], v[46:49]
	v_mfma_f32_16x16x32_bf16 v[42:45], v[164:167], v[196:199], v[42:45]
	v_mfma_f32_16x16x32_bf16 v[30:33], v[156:159], v[208:211], v[30:33]
	v_mfma_f32_16x16x32_bf16 v[26:29], v[164:167], v[208:211], v[26:29]
	v_mfma_f32_16x16x32_bf16 v[14:17], v[156:159], v[216:219], v[14:17]
	v_mfma_f32_16x16x32_bf16 v[10:13], v[164:167], v[216:219], v[10:13]
	v_mfma_f32_16x16x32_bf16 v[54:57], v[168:171], v[184:187], v[54:57]
	v_mfma_f32_16x16x32_bf16 v[50:53], v[176:179], v[184:187], v[50:53]
	v_mfma_f32_16x16x32_bf16 v[38:41], v[168:171], v[192:195], v[38:41]
	v_mfma_f32_16x16x32_bf16 v[34:37], v[176:179], v[192:195], v[34:37]
	v_mfma_f32_16x16x32_bf16 v[22:25], v[168:171], v[200:203], v[22:25]
	v_mfma_f32_16x16x32_bf16 v[18:21], v[176:179], v[200:203], v[18:21]
	v_mfma_f32_16x16x32_bf16 v[6:9], v[168:171], v[212:215], v[6:9]
	v_mfma_f32_16x16x32_bf16 v[2:5], v[176:179], v[212:215], v[2:5]
	v_mfma_f32_16x16x32_bf16 v[54:57], v[172:175], v[188:191], v[54:57]
	v_mfma_f32_16x16x32_bf16 v[50:53], v[180:183], v[188:191], v[50:53]
	v_mfma_f32_16x16x32_bf16 v[38:41], v[172:175], v[196:199], v[38:41]
	v_mfma_f32_16x16x32_bf16 v[34:37], v[180:183], v[196:199], v[34:37]
	v_mfma_f32_16x16x32_bf16 v[22:25], v[172:175], v[208:211], v[22:25]
	v_mfma_f32_16x16x32_bf16 v[18:21], v[180:183], v[208:211], v[18:21]
	v_mfma_f32_16x16x32_bf16 v[6:9], v[172:175], v[216:219], v[6:9]
	v_mfma_f32_16x16x32_bf16 v[2:5], v[180:183], v[216:219], v[2:5]
	s_add_i32 s73, s73, 2
	s_add_u32 s44, s44, 0x100
	s_addc_u32 s45, s45, 0
	s_add_u32 s71, s71, 0x100
	s_addc_u32 s72, s72, 0
	s_cmp_gt_u32 s73, 13
	s_barrier
.LBB0_646:
	ds_read_b128 v[148:151], v152
	ds_read_b128 v[156:159], v152 offset:1024
	ds_read_b128 v[160:163], v152 offset:2048
	ds_read_b128 v[164:167], v152 offset:3072
	ds_read_b128 v[168:171], v153
	ds_read_b128 v[172:175], v153 offset:1024
	ds_read_b128 v[176:179], v153 offset:2048
	ds_read_b128 v[180:183], v153 offset:3072
	s_add_u32 s46, s44, 0xfffc0080
	s_addc_u32 s47, s45, -1
	s_cmp_eq_u32 s73, 12
	s_cselect_b32 s49, s21, s47
	s_cselect_b32 s48, s27, s46
	s_cselect_b32 s47, s19, s72
	s_cselect_b32 s46, s33, s71
	v_lshl_add_u64 v[204:205], s[44:45], 0, v[140:141]
	s_add_i32 m0, s31, 0xc000
	ds_read_b128 v[184:187], v154
	ds_read_b128 v[188:191], v154 offset:1024
	ds_read_b128 v[192:195], v154 offset:2048
	ds_read_b128 v[196:199], v154 offset:3072
	ds_read_b128 v[200:203], v154 offset:4096
	ds_read_b128 v[208:211], v154 offset:5120
	ds_read_b128 v[212:215], v154 offset:6144
	ds_read_b128 v[216:219], v154 offset:7168
	global_load_lds_dwordx4 v[204:205], off
	v_lshl_add_u64 v[204:205], s[44:45], 0, v[142:143]
	s_add_i32 m0, s31, 0xe000
	s_nop 0
	global_load_lds_dwordx4 v[204:205], off
	s_waitcnt vmcnt(8)
	s_bitcmp1_b32 s16, 0
	s_cbranch_scc1 .Lnl_646_4
	s_waitcnt lgkmcnt(0)
; #define PG8_STAGE(bufoff, gbase, voff) do { _Pragma("unroll") for (int _i = 0; _i < 2; ++_i) \
;         __builtin_amdgcn_global_load_lds((const unsigned*)((const char*)(gbase) + (voff)[_i]), (PG8_LAS unsigned*)(lds + (bufoff) + ldsw + _i * 8192), 16, 0, 0); } while (0)
; #define PG8_LDA(dst, b, h) do { _Pragma("unroll") for (int m = 0; m < 4; ++m) _Pragma("unroll") for (int k = 0; k < 2; ++k) dst[m][k] = *(const PG8_LAS bf16x8*)(lds + PG8_SA(b, h) + aoff + m * 2048 + k * 1024); } while (0)
; #define PG8_LDB(dst, b, h) do { _Pragma("unroll") for (int n = 0; n < 2; ++n) _Pragma("unroll") for (int k = 0; k < 2; ++k) dst[n][k] = *(const PG8_LAS bf16x8*)(lds + PG8_SB(b, h) + boff + n * 2048 + k * 1024); } while (0)
; #define PG8_MMA(ai, bj, At, Bt) do { __builtin_amdgcn_s_setprio(1); _Pragma("unroll") for (int m = 0; m < 4; ++m) _Pragma("unroll") for (int n = 0; n < 2; ++n) _Pragma("unroll") for (int k = 0; k < 2; ++k) \
;         acc[ai][bj][m][n] = __builtin_amdgcn_mfma_f32_16x16x32_bf16(Bt[n][k], At[m][k], acc[ai][bj][m][n], 0, 0, 0); __builtin_amdgcn_s_setprio(0); } while (0)
; #define PG8_WAIT_V(n) asm volatile("s_waitcnt vmcnt(" #n ")" ::: "memory")
; template <class Epi, class Sched, bool ALIGN_EPI = false, bool SP2 = false>
; __device__ __forceinline__ void gemm_phase(PG8_LAS unsigned char* lds, const Gemm g, const Sched& S, const Epi& E) {
;     ...
;             PG8_LDB(B0, 0, 0); PG8_LDB(B1, 0, 1); PG8_SCHED; PG8_LDA(At, 0, 0); PG8_STAGE(PG8_SA(1, 1), a1 + hstep, voffA);
;             PG8_WAIT_V(8); PG8_WAIT_L(0); PG8_BAR; PG8_MMA(0, 0, At, B0); PG8_MMA(0, 1, At, B1); PG8_BAR; PG8_SCHED;
;             PG8_LDA(At, 0, 1); PG8_STAGE(PG8_SB(0, 0), b2, voffB); PG8_STAGE(PG8_SB(0, 1), b2 + hstep, voffB); PG8_STAGE(PG8_SA(0, 0), a2, voffA);
;             PG8_WAIT_V(8); PG8_WAIT_L(0); PG8_BAR; PG8_MMA(1, 0, At, B0); PG8_MMA(1, 1, At, B1); PG8_BAR; PG8_SCHED;
;             PG8_LDB(B0, 1, 0); PG8_LDB(B1, 1, 1); PG8_SCHED; PG8_LDA(At, 1, 0); PG8_STAGE(PG8_SA(0, 1), a2 + hstep, voffA);
;             PG8_WAIT_V(8); PG8_WAIT_L(0); PG8_BAR; PG8_MMA(0, 0, At, B0); PG8_MMA(0, 1, At, B1); PG8_BAR; PG8_SCHED;
;             PG8_LDA(At, 1, 1); PG8_STAGE(PG8_SB(1, 0), b3, voffB); PG8_STAGE(PG8_SB(1, 1), b3 + hstep, voffB); PG8_STAGE(PG8_SA(1, 0), a3, voffA);
;             PG8_WAIT_V(8); PG8_WAIT_L(0); PG8_BAR; PG8_MMA(1, 0, At, B0); PG8_MMA(1, 1, At, B1); PG8_BAR; PG8_SCHED;
.Lnl_646_4:
	s_barrier
	s_waitcnt lgkmcnt(0)
	v_mfma_f32_16x16x32_bf16 v[126:129], v[148:151], v[184:187], v[126:129]
	v_mfma_f32_16x16x32_bf16 v[122:125], v[160:163], v[184:187], v[122:125]
	v_mfma_f32_16x16x32_bf16 v[110:113], v[148:151], v[192:195], v[110:113]
	v_mfma_f32_16x16x32_bf16 v[106:109], v[160:163], v[192:195], v[106:109]
	v_mfma_f32_16x16x32_bf16 v[94:97], v[148:151], v[200:203], v[94:97]
	v_mfma_f32_16x16x32_bf16 v[90:93], v[160:163], v[200:203], v[90:93]
	v_mfma_f32_16x16x32_bf16 v[78:81], v[148:151], v[212:215], v[78:81]
	v_mfma_f32_16x16x32_bf16 v[74:77], v[160:163], v[212:215], v[74:77]
	v_mfma_f32_16x16x32_bf16 v[126:129], v[156:159], v[188:191], v[126:129]
	v_mfma_f32_16x16x32_bf16 v[122:125], v[164:167], v[188:191], v[122:125]
	v_mfma_f32_16x16x32_bf16 v[110:113], v[156:159], v[196:199], v[110:113]
	v_mfma_f32_16x16x32_bf16 v[106:109], v[164:167], v[196:199], v[106:109]
	v_mfma_f32_16x16x32_bf16 v[94:97], v[156:159], v[208:211], v[94:97]
	v_mfma_f32_16x16x32_bf16 v[90:93], v[164:167], v[208:211], v[90:93]
	v_mfma_f32_16x16x32_bf16 v[78:81], v[156:159], v[216:219], v[78:81]
	v_mfma_f32_16x16x32_bf16 v[74:77], v[164:167], v[216:219], v[74:77]
	v_mfma_f32_16x16x32_bf16 v[118:121], v[168:171], v[184:187], v[118:121]
	v_mfma_f32_16x16x32_bf16 v[114:117], v[176:179], v[184:187], v[114:117]
	v_mfma_f32_16x16x32_bf16 v[102:105], v[168:171], v[192:195], v[102:105]
	v_mfma_f32_16x16x32_bf16 v[98:101], v[176:179], v[192:195], v[98:101]
	v_mfma_f32_16x16x32_bf16 v[86:89], v[168:171], v[200:203], v[86:89]
	v_mfma_f32_16x16x32_bf16 v[82:85], v[176:179], v[200:203], v[82:85]
	v_mfma_f32_16x16x32_bf16 v[70:73], v[168:171], v[212:215], v[70:73]
	v_mfma_f32_16x16x32_bf16 v[66:69], v[176:179], v[212:215], v[66:69]
	v_mfma_f32_16x16x32_bf16 v[118:121], v[172:175], v[188:191], v[118:121]
	v_mfma_f32_16x16x32_bf16 v[114:117], v[180:183], v[188:191], v[114:117]
	v_mfma_f32_16x16x32_bf16 v[102:105], v[172:175], v[196:199], v[102:105]
	v_mfma_f32_16x16x32_bf16 v[98:101], v[180:183], v[196:199], v[98:101]
	v_mfma_f32_16x16x32_bf16 v[86:89], v[172:175], v[208:211], v[86:89]
	v_mfma_f32_16x16x32_bf16 v[82:85], v[180:183], v[208:211], v[82:85]
	v_mfma_f32_16x16x32_bf16 v[70:73], v[172:175], v[216:219], v[70:73]
	v_mfma_f32_16x16x32_bf16 v[66:69], v[180:183], v[216:219], v[66:69]
	s_barrier
	s_add_i32 s74, s68, s30
	s_mov_b32 m0, s74
	ds_read_b128 v[184:187], v154 offset:16384
	ds_read_b128 v[188:191], v154 offset:17408
	ds_read_b128 v[192:195], v154 offset:18432
	ds_read_b128 v[196:199], v154 offset:19456
	ds_read_b128 v[200:203], v154 offset:20480
	ds_read_b128 v[208:211], v154 offset:21504
	ds_read_b128 v[212:215], v154 offset:22528
	ds_read_b128 v[216:219], v154 offset:23552
	global_load_lds_dwordx4 v132, s[46:47]
	s_add_i32 m0, s74, 0x2000
	s_add_u32 s74, s46, 0x40000
	v_lshl_add_u64 v[220:221], s[46:47], 0, v[136:137]
	s_addc_u32 s75, s47, 0
	s_add_i32 s76, s69, s30
	global_load_lds_dwordx4 v136, s[46:47]
	s_mov_b32 m0, s76
	v_lshl_add_u64 v[224:225], s[48:49], 0, v[134:135]
	global_load_lds_dwordx4 v132, s[74:75]
	s_add_i32 m0, s76, 0x2000
	s_nop 0
	global_load_lds_dwordx4 v136, s[74:75]
	v_lshl_add_u64 v[222:223], s[48:49], 0, v[130:131]
	s_mov_b32 m0, s31
	s_nop 0
	global_load_lds_dwordx4 v130, s[48:49]
	s_mov_b32 m0, s50
	s_nop 0
	global_load_lds_dwordx4 v134, s[48:49]
	s_waitcnt vmcnt(8)
	s_bitcmp1_b32 s16, 0
	s_cbranch_scc1 .Lnl_646_5
	s_waitcnt lgkmcnt(0)
.Lnl_646_5:
	s_barrier
	s_waitcnt lgkmcnt(0)
	v_mfma_f32_16x16x32_bf16 v[62:65], v[148:151], v[184:187], v[62:65]
	v_mfma_f32_16x16x32_bf16 v[58:61], v[160:163], v[184:187], v[58:61]
	v_mfma_f32_16x16x32_bf16 v[46:49], v[148:151], v[192:195], v[46:49]
	v_mfma_f32_16x16x32_bf16 v[42:45], v[160:163], v[192:195], v[42:45]
	v_mfma_f32_16x16x32_bf16 v[30:33], v[148:151], v[200:203], v[30:33]
	v_mfma_f32_16x16x32_bf16 v[26:29], v[160:163], v[200:203], v[26:29]
	v_mfma_f32_16x16x32_bf16 v[14:17], v[148:151], v[212:215], v[14:17]
	v_mfma_f32_16x16x32_bf16 v[10:13], v[160:163], v[212:215], v[10:13]
	v_mfma_f32_16x16x32_bf16 v[62:65], v[156:159], v[188:191], v[62:65]
	v_mfma_f32_16x16x32_bf16 v[58:61], v[164:167], v[188:191], v[58:61]
	v_mfma_f32_16x16x32_bf16 v[46:49], v[156:159], v[196:199], v[46:49]
	v_mfma_f32_16x16x32_bf16 v[42:45], v[164:167], v[196:199], v[42:45]
	v_mfma_f32_16x16x32_bf16 v[30:33], v[156:159], v[208:211], v[30:33]
	v_mfma_f32_16x16x32_bf16 v[26:29], v[164:167], v[208:211], v[26:29]
	v_mfma_f32_16x16x32_bf16 v[14:17], v[156:159], v[216:219], v[14:17]
	v_mfma_f32_16x16x32_bf16 v[10:13], v[164:167], v[216:219], v[10:13]
	v_mfma_f32_16x16x32_bf16 v[54:57], v[168:171], v[184:187], v[54:57]
	v_mfma_f32_16x16x32_bf16 v[50:53], v[176:179], v[184:187], v[50:53]
	v_mfma_f32_16x16x32_bf16 v[38:41], v[168:171], v[192:195], v[38:41]
	v_mfma_f32_16x16x32_bf16 v[34:37], v[176:179], v[192:195], v[34:37]
	v_mfma_f32_16x16x32_bf16 v[22:25], v[168:171], v[200:203], v[22:25]
	v_mfma_f32_16x16x32_bf16 v[18:21], v[176:179], v[200:203], v[18:21]
	v_mfma_f32_16x16x32_bf16 v[6:9], v[168:171], v[212:215], v[6:9]
	v_mfma_f32_16x16x32_bf16 v[2:5], v[176:179], v[212:215], v[2:5]
	v_mfma_f32_16x16x32_bf16 v[54:57], v[172:175], v[188:191], v[54:57]
	v_mfma_f32_16x16x32_bf16 v[50:53], v[180:183], v[188:191], v[50:53]
	v_mfma_f32_16x16x32_bf16 v[38:41], v[172:175], v[196:199], v[38:41]
	v_mfma_f32_16x16x32_bf16 v[34:37], v[180:183], v[196:199], v[34:37]
	v_mfma_f32_16x16x32_bf16 v[22:25], v[172:175], v[208:211], v[22:25]
	v_mfma_f32_16x16x32_bf16 v[18:21], v[180:183], v[208:211], v[18:21]
	v_mfma_f32_16x16x32_bf16 v[6:9], v[172:175], v[216:219], v[6:9]
	v_mfma_f32_16x16x32_bf16 v[2:5], v[180:183], v[216:219], v[2:5]
	s_barrier
	s_add_i32 s74, 0, 0x18000
	s_add_i32 s75, 0, 0x1c000
	v_add_u32_e32 v164, s74, v139
	v_add_u32_e32 v180, s75, v139
	ds_read_b128 v[148:151], v164
	ds_read_b128 v[156:159], v164 offset:1024
	ds_read_b128 v[160:163], v164 offset:2048
	ds_read_b128 v[164:167], v164 offset:3072
	ds_read_b128 v[168:171], v180
	ds_read_b128 v[172:175], v180 offset:1024
	ds_read_b128 v[176:179], v180 offset:2048
	ds_read_b128 v[180:183], v180 offset:3072
	s_add_u32 s48, s48, 0x40000
	s_addc_u32 s49, s49, 0
	s_mov_b32 m0, s51
	ds_read_b128 v[184:187], v154 offset:32768
	ds_read_b128 v[188:191], v154 offset:33792
	ds_read_b128 v[192:195], v154 offset:34816
	ds_read_b128 v[196:199], v154 offset:35840
	ds_read_b128 v[200:203], v154 offset:36864
	ds_read_b128 v[208:211], v154 offset:37888
	ds_read_b128 v[212:215], v154 offset:38912
	ds_read_b128 v[216:219], v154 offset:39936
	global_load_lds_dwordx4 v130, s[48:49]
	s_mov_b32 m0, s60
	s_nop 0
	global_load_lds_dwordx4 v134, s[48:49]
	s_waitcnt vmcnt(8)
	s_bitcmp1_b32 s16, 0
	s_cbranch_scc1 .Lnl_646_6
	s_waitcnt lgkmcnt(0)

; #define PG8_MMA(ai, bj, At, Bt) do { __builtin_amdgcn_s_setprio(1); _Pragma("unroll") for (int m = 0; m < 4; ++m) _Pragma("unroll") for (int n = 0; n < 2; ++n) _Pragma("unroll") for (int k = 0; k < 2; ++k) \
;         acc[ai][bj][m][n] = __builtin_amdgcn_mfma_f32_16x16x32_bf16(Bt[n][k], At[m][k], acc[ai][bj][m][n], 0, 0, 0); __builtin_amdgcn_s_setprio(0); } while (0)
; #define PG8_WAIT_V(n) asm volatile("s_waitcnt vmcnt(" #n ")" ::: "memory")
; #define PG8_WAIT_L(n) asm volatile("s_waitcnt lgkmcnt(" #n ")" ::: "memory")
; #define PG8_BAR __builtin_amdgcn_s_barrier()
; #define PG8_SCHED __builtin_amdgcn_sched_barrier(0)
; template <class Epi, class Sched, bool ALIGN_EPI = false, bool SP2 = false>
; __device__ __forceinline__ void gemm_phase(PG8_LAS unsigned char* lds, const Gemm g, const Sched& S, const Epi& E) {
;     ...
;             PG8_WAIT_V(8); PG8_WAIT_L(0); PG8_BAR; PG8_MMA(1, 0, At, B0); PG8_MMA(1, 1, At, B1); PG8_BAR; PG8_SCHED;
;     ...
;         if constexpr (ALIGN_EPI) { if (wr == 0) PG8_BAR; }
.Lnl_646_7:
	s_barrier
	s_waitcnt lgkmcnt(0)
	v_mfma_f32_16x16x32_bf16 v[62:65], v[148:151], v[184:187], v[62:65]
	v_mfma_f32_16x16x32_bf16 v[58:61], v[160:163], v[184:187], v[58:61]
	v_mfma_f32_16x16x32_bf16 v[46:49], v[148:151], v[192:195], v[46:49]
	v_mfma_f32_16x16x32_bf16 v[42:45], v[160:163], v[192:195], v[42:45]
	v_mfma_f32_16x16x32_bf16 v[30:33], v[148:151], v[200:203], v[30:33]
	v_mfma_f32_16x16x32_bf16 v[26:29], v[160:163], v[200:203], v[26:29]
	v_mfma_f32_16x16x32_bf16 v[14:17], v[148:151], v[212:215], v[14:17]
	v_mfma_f32_16x16x32_bf16 v[10:13], v[160:163], v[212:215], v[10:13]
	v_mfma_f32_16x16x32_bf16 v[62:65], v[156:159], v[188:191], v[62:65]
	v_mfma_f32_16x16x32_bf16 v[58:61], v[164:167], v[188:191], v[58:61]
	v_mfma_f32_16x16x32_bf16 v[46:49], v[156:159], v[196:199], v[46:49]
	v_mfma_f32_16x16x32_bf16 v[42:45], v[164:167], v[196:199], v[42:45]
	v_mfma_f32_16x16x32_bf16 v[30:33], v[156:159], v[208:211], v[30:33]
	v_mfma_f32_16x16x32_bf16 v[26:29], v[164:167], v[208:211], v[26:29]
	v_mfma_f32_16x16x32_bf16 v[14:17], v[156:159], v[216:219], v[14:17]
	v_mfma_f32_16x16x32_bf16 v[10:13], v[164:167], v[216:219], v[10:13]
	v_mfma_f32_16x16x32_bf16 v[54:57], v[168:171], v[184:187], v[54:57]
	v_mfma_f32_16x16x32_bf16 v[50:53], v[176:179], v[184:187], v[50:53]
	v_mfma_f32_16x16x32_bf16 v[38:41], v[168:171], v[192:195], v[38:41]
	v_mfma_f32_16x16x32_bf16 v[34:37], v[176:179], v[192:195], v[34:37]
	v_mfma_f32_16x16x32_bf16 v[22:25], v[168:171], v[200:203], v[22:25]
	v_mfma_f32_16x16x32_bf16 v[18:21], v[176:179], v[200:203], v[18:21]
	v_mfma_f32_16x16x32_bf16 v[6:9], v[168:171], v[212:215], v[6:9]
	v_mfma_f32_16x16x32_bf16 v[2:5], v[176:179], v[212:215], v[2:5]
	v_mfma_f32_16x16x32_bf16 v[54:57], v[172:175], v[188:191], v[54:57]
	v_mfma_f32_16x16x32_bf16 v[50:53], v[180:183], v[188:191], v[50:53]
	v_mfma_f32_16x16x32_bf16 v[38:41], v[172:175], v[196:199], v[38:41]
	v_mfma_f32_16x16x32_bf16 v[34:37], v[180:183], v[196:199], v[34:37]
	v_mfma_f32_16x16x32_bf16 v[22:25], v[172:175], v[208:211], v[22:25]
	v_mfma_f32_16x16x32_bf16 v[18:21], v[180:183], v[208:211], v[18:21]
	v_mfma_f32_16x16x32_bf16 v[6:9], v[172:175], v[216:219], v[6:9]
	v_mfma_f32_16x16x32_bf16 v[2:5], v[180:183], v[216:219], v[2:5]
	s_add_i32 s73, s73, 2
	s_add_u32 s44, s44, 0x100
	s_addc_u32 s45, s45, 0
	s_add_u32 s71, s71, 0x100
	s_addc_u32 s72, s72, 0
	s_cmp_gt_u32 s73, 13
	s_barrier
	s_cbranch_scc0 .LBB0_646
	s_and_b64 vcc, exec, s[16:17]
	s_cbranch_vccz .LBB0_649
	s_barrier

; #define PG8_STAGE(bufoff, gbase, voff) do { _Pragma("unroll") for (int _i = 0; _i < 2; ++_i) \
;         __builtin_amdgcn_global_load_lds((const unsigned*)((const char*)(gbase) + (voff)[_i]), (PG8_LAS unsigned*)(lds + (bufoff) + ldsw + _i * 8192), 16, 0, 0); } while (0)
; #define PG8_LDA(dst, b, h) do { _Pragma("unroll") for (int m = 0; m < 4; ++m) _Pragma("unroll") for (int k = 0; k < 2; ++k) dst[m][k] = *(const PG8_LAS bf16x8*)(lds + PG8_SA(b, h) + aoff + m * 2048 + k * 1024); } while (0)
; #define PG8_LDB(dst, b, h) do { _Pragma("unroll") for (int n = 0; n < 2; ++n) _Pragma("unroll") for (int k = 0; k < 2; ++k) dst[n][k] = *(const PG8_LAS bf16x8*)(lds + PG8_SB(b, h) + boff + n * 2048 + k * 1024); } while (0)
; #define PG8_MMA(ai, bj, At, Bt) do { __builtin_amdgcn_s_setprio(1); _Pragma("unroll") for (int m = 0; m < 4; ++m) _Pragma("unroll") for (int n = 0; n < 2; ++n) _Pragma("unroll") for (int k = 0; k < 2; ++k) \
;         acc[ai][bj][m][n] = __builtin_amdgcn_mfma_f32_16x16x32_bf16(Bt[n][k], At[m][k], acc[ai][bj][m][n], 0, 0, 0); __builtin_amdgcn_s_setprio(0); } while (0)
; #define PG8_WAIT_V(n) asm volatile("s_waitcnt vmcnt(" #n ")" ::: "memory")
; #define PG8_WAIT_L(n) asm volatile("s_waitcnt lgkmcnt(" #n ")" ::: "memory")
; #define PG8_BAR __builtin_amdgcn_s_barrier()
; #define PG8_SCHED __builtin_amdgcn_sched_barrier(0)
; template <class Epi, class Sched, bool ALIGN_EPI = false, bool SP2 = false>
; __device__ __forceinline__ void gemm_phase(PG8_LAS unsigned char* lds, const Gemm g, const Sched& S, const Epi& E) {
;     ...
;             PG8_LDB(B0, 0, 0); PG8_LDB(B1, 0, 1); PG8_SCHED; PG8_LDA(At, 0, 0); PG8_STAGE(PG8_SA(1, 1), a1 + hstep, voffA);
;             PG8_WAIT_V(8); PG8_WAIT_L(0); PG8_BAR; PG8_MMA(0, 0, At, B0); PG8_MMA(0, 1, At, B1); PG8_BAR; PG8_SCHED;
;             PG8_LDA(At, 0, 1); PG8_STAGE(PG8_SB(0, 0), b2, voffB); PG8_STAGE(PG8_SB(0, 1), b2 + hstep, voffB); PG8_STAGE(PG8_SA(0, 0), a2, voffA);
.Lpw_740_0:
	s_bitcmp1_b32 s14, 0
	s_cbranch_scc1 .Lnl_740_0
	s_waitcnt lgkmcnt(0)
.Lnl_740_0:
	s_barrier
	s_waitcnt lgkmcnt(0)
	v_mfma_f32_16x16x32_bf16 v[126:129], v[156:159], v[188:191], 0
	v_mfma_f32_16x16x32_bf16 v[122:125], v[164:167], v[188:191], 0
	v_mfma_f32_16x16x32_bf16 v[110:113], v[156:159], v[196:199], 0
	v_mfma_f32_16x16x32_bf16 v[106:109], v[164:167], v[196:199], 0
	v_mfma_f32_16x16x32_bf16 v[94:97], v[156:159], v[208:211], 0
	v_mfma_f32_16x16x32_bf16 v[90:93], v[164:167], v[208:211], 0
	v_mfma_f32_16x16x32_bf16 v[78:81], v[156:159], v[216:219], 0
	v_mfma_f32_16x16x32_bf16 v[74:77], v[164:167], v[216:219], 0
	v_mfma_f32_16x16x32_bf16 v[126:129], v[160:163], v[192:195], v[126:129]
	v_mfma_f32_16x16x32_bf16 v[122:125], v[168:171], v[192:195], v[122:125]
	v_mfma_f32_16x16x32_bf16 v[110:113], v[160:163], v[200:203], v[110:113]
	v_mfma_f32_16x16x32_bf16 v[106:109], v[168:171], v[200:203], v[106:109]
	v_mfma_f32_16x16x32_bf16 v[94:97], v[160:163], v[212:215], v[94:97]
	v_mfma_f32_16x16x32_bf16 v[90:93], v[168:171], v[212:215], v[90:93]
	v_mfma_f32_16x16x32_bf16 v[78:81], v[160:163], v[220:223], v[78:81]
	v_mfma_f32_16x16x32_bf16 v[74:77], v[168:171], v[220:223], v[74:77]
	v_mfma_f32_16x16x32_bf16 v[118:121], v[172:175], v[188:191], 0
	v_mfma_f32_16x16x32_bf16 v[114:117], v[180:183], v[188:191], 0
	v_mfma_f32_16x16x32_bf16 v[102:105], v[172:175], v[196:199], 0
	v_mfma_f32_16x16x32_bf16 v[98:101], v[180:183], v[196:199], 0
	v_mfma_f32_16x16x32_bf16 v[86:89], v[172:175], v[208:211], 0
	v_mfma_f32_16x16x32_bf16 v[82:85], v[180:183], v[208:211], 0
	v_mfma_f32_16x16x32_bf16 v[70:73], v[172:175], v[216:219], 0
	v_mfma_f32_16x16x32_bf16 v[66:69], v[180:183], v[216:219], 0
	v_mfma_f32_16x16x32_bf16 v[118:121], v[176:179], v[192:195], v[118:121]
	v_mfma_f32_16x16x32_bf16 v[114:117], v[184:187], v[192:195], v[114:117]
	v_mfma_f32_16x16x32_bf16 v[102:105], v[176:179], v[200:203], v[102:105]
	v_mfma_f32_16x16x32_bf16 v[98:101], v[184:187], v[200:203], v[98:101]
	v_mfma_f32_16x16x32_bf16 v[86:89], v[176:179], v[212:215], v[86:89]
	v_mfma_f32_16x16x32_bf16 v[82:85], v[184:187], v[212:215], v[82:85]
	v_mfma_f32_16x16x32_bf16 v[70:73], v[176:179], v[220:223], v[70:73]
	v_mfma_f32_16x16x32_bf16 v[66:69], v[184:187], v[220:223], v[66:69]
	s_barrier
	s_add_i32 s72, s66, s47
	s_mov_b32 m0, s72
	ds_read_b128 v[188:191], v154 offset:16384
	ds_read_b128 v[192:195], v154 offset:17408
	ds_read_b128 v[196:199], v154 offset:18432
	ds_read_b128 v[200:203], v154 offset:19456
	ds_read_b128 v[208:211], v154 offset:20480
	ds_read_b128 v[212:215], v154 offset:21504
	ds_read_b128 v[216:219], v154 offset:22528
	ds_read_b128 v[220:223], v154 offset:23552
	global_load_lds_dwordx4 v132, s[40:41]
	s_add_i32 m0, s72, 0x2000
	s_add_u32 s72, s40, 0x40000
	v_lshl_add_u64 v[204:205], s[40:41], 0, v[136:137]
	s_addc_u32 s73, s41, 0
	s_add_i32 s74, s67, s47
	global_load_lds_dwordx4 v136, s[40:41]
	s_mov_b32 m0, s74
	v_lshl_add_u64 v[226:227], s[44:45], 0, v[134:135]
	global_load_lds_dwordx4 v132, s[72:73]
	s_add_i32 m0, s74, 0x2000
	s_nop 0
	global_load_lds_dwordx4 v136, s[72:73]
	v_lshl_add_u64 v[224:225], s[44:45], 0, v[130:131]
	s_mov_b32 m0, s48
	s_nop 0
	global_load_lds_dwordx4 v130, s[44:45]
	s_mov_b32 m0, s49
	s_nop 0
	global_load_lds_dwordx4 v134, s[44:45]
	s_waitcnt vmcnt(16)
	s_cmp_gt_u32 s69, 1
	s_cbranch_scc1 .Lpw_740_1
	s_waitcnt vmcnt(8)

; #define PG8_STAGE(bufoff, gbase, voff) do { _Pragma("unroll") for (int _i = 0; _i < 2; ++_i) \
;         __builtin_amdgcn_global_load_lds((const unsigned*)((const char*)(gbase) + (voff)[_i]), (PG8_LAS unsigned*)(lds + (bufoff) + ldsw + _i * 8192), 16, 0, 0); } while (0)
; #define PG8_LDA(dst, b, h) do { _Pragma("unroll") for (int m = 0; m < 4; ++m) _Pragma("unroll") for (int k = 0; k < 2; ++k) dst[m][k] = *(const PG8_LAS bf16x8*)(lds + PG8_SA(b, h) + aoff + m * 2048 + k * 1024); } while (0)
; #define PG8_LDB(dst, b, h) do { _Pragma("unroll") for (int n = 0; n < 2; ++n) _Pragma("unroll") for (int k = 0; k < 2; ++k) dst[n][k] = *(const PG8_LAS bf16x8*)(lds + PG8_SB(b, h) + boff + n * 2048 + k * 1024); } while (0)
; #define PG8_MMA(ai, bj, At, Bt) do { __builtin_amdgcn_s_setprio(1); _Pragma("unroll") for (int m = 0; m < 4; ++m) _Pragma("unroll") for (int n = 0; n < 2; ++n) _Pragma("unroll") for (int k = 0; k < 2; ++k) \
;         acc[ai][bj][m][n] = __builtin_amdgcn_mfma_f32_16x16x32_bf16(Bt[n][k], At[m][k], acc[ai][bj][m][n], 0, 0, 0); __builtin_amdgcn_s_setprio(0); } while (0)
; #define PG8_WAIT_V(n) asm volatile("s_waitcnt vmcnt(" #n ")" ::: "memory")
; template <class Epi, class Sched, bool ALIGN_EPI = false, bool SP2 = false>
; __device__ __forceinline__ void gemm_phase(PG8_LAS unsigned char* lds, const Gemm g, const Sched& S, const Epi& E) {
;     ...
;             PG8_LDB(B0, 0, 0); PG8_LDB(B1, 0, 1); PG8_SCHED; PG8_LDA(At, 0, 0); PG8_STAGE(PG8_SA(1, 1), a1 + hstep, voffA);
;             PG8_WAIT_V(8); PG8_WAIT_L(0); PG8_BAR; PG8_MMA(0, 0, At, B0); PG8_MMA(0, 1, At, B1); PG8_BAR; PG8_SCHED;
;             PG8_LDA(At, 0, 1); PG8_STAGE(PG8_SB(0, 0), b2, voffB); PG8_STAGE(PG8_SB(0, 1), b2 + hstep, voffB); PG8_STAGE(PG8_SA(0, 0), a2, voffA);
;             PG8_WAIT_V(8); PG8_WAIT_L(0); PG8_BAR; PG8_MMA(1, 0, At, B0); PG8_MMA(1, 1, At, B1); PG8_BAR; PG8_SCHED;
;             PG8_LDB(B0, 1, 0); PG8_LDB(B1, 1, 1); PG8_SCHED; PG8_LDA(At, 1, 0); PG8_STAGE(PG8_SA(0, 1), a2 + hstep, voffA);
;             PG8_WAIT_V(8); PG8_WAIT_L(0); PG8_BAR; PG8_MMA(0, 0, At, B0); PG8_MMA(0, 1, At, B1); PG8_BAR; PG8_SCHED;
;             PG8_LDA(At, 1, 1); PG8_STAGE(PG8_SB(1, 0), b3, voffB); PG8_STAGE(PG8_SB(1, 1), b3 + hstep, voffB); PG8_STAGE(PG8_SA(1, 0), a3, voffA);
;             PG8_WAIT_V(8); PG8_WAIT_L(0); PG8_BAR; PG8_MMA(1, 0, At, B0); PG8_MMA(1, 1, At, B1); PG8_BAR; PG8_SCHED;
.Lnl_740_1:
	s_barrier
	s_waitcnt lgkmcnt(0)
	v_mfma_f32_16x16x32_bf16 v[62:65], v[156:159], v[188:191], 0
	v_mfma_f32_16x16x32_bf16 v[58:61], v[164:167], v[188:191], 0
	v_mfma_f32_16x16x32_bf16 v[46:49], v[156:159], v[196:199], 0
	v_mfma_f32_16x16x32_bf16 v[42:45], v[164:167], v[196:199], 0
	v_mfma_f32_16x16x32_bf16 v[30:33], v[156:159], v[208:211], 0
	v_mfma_f32_16x16x32_bf16 v[26:29], v[164:167], v[208:211], 0
	v_mfma_f32_16x16x32_bf16 v[14:17], v[156:159], v[216:219], 0
	v_mfma_f32_16x16x32_bf16 v[10:13], v[164:167], v[216:219], 0
	v_mfma_f32_16x16x32_bf16 v[62:65], v[160:163], v[192:195], v[62:65]
	v_mfma_f32_16x16x32_bf16 v[58:61], v[168:171], v[192:195], v[58:61]
	v_mfma_f32_16x16x32_bf16 v[46:49], v[160:163], v[200:203], v[46:49]
	v_mfma_f32_16x16x32_bf16 v[42:45], v[168:171], v[200:203], v[42:45]
	v_mfma_f32_16x16x32_bf16 v[30:33], v[160:163], v[212:215], v[30:33]
	v_mfma_f32_16x16x32_bf16 v[26:29], v[168:171], v[212:215], v[26:29]
	v_mfma_f32_16x16x32_bf16 v[14:17], v[160:163], v[220:223], v[14:17]
	v_mfma_f32_16x16x32_bf16 v[10:13], v[168:171], v[220:223], v[10:13]
	v_mfma_f32_16x16x32_bf16 v[54:57], v[172:175], v[188:191], 0
	v_mfma_f32_16x16x32_bf16 v[50:53], v[180:183], v[188:191], 0
	v_mfma_f32_16x16x32_bf16 v[38:41], v[172:175], v[196:199], 0
	v_mfma_f32_16x16x32_bf16 v[34:37], v[180:183], v[196:199], 0
	v_mfma_f32_16x16x32_bf16 v[22:25], v[172:175], v[208:211], 0
	v_mfma_f32_16x16x32_bf16 v[18:21], v[180:183], v[208:211], 0
	v_mfma_f32_16x16x32_bf16 v[6:9], v[172:175], v[216:219], 0
	v_mfma_f32_16x16x32_bf16 v[2:5], v[180:183], v[216:219], 0
	v_mfma_f32_16x16x32_bf16 v[54:57], v[176:179], v[192:195], v[54:57]
	v_mfma_f32_16x16x32_bf16 v[50:53], v[184:187], v[192:195], v[50:53]
	v_mfma_f32_16x16x32_bf16 v[38:41], v[176:179], v[200:203], v[38:41]
	v_mfma_f32_16x16x32_bf16 v[34:37], v[184:187], v[200:203], v[34:37]
	v_mfma_f32_16x16x32_bf16 v[22:25], v[176:179], v[212:215], v[22:25]
	v_mfma_f32_16x16x32_bf16 v[18:21], v[184:187], v[212:215], v[18:21]
	v_mfma_f32_16x16x32_bf16 v[6:9], v[176:179], v[220:223], v[6:9]
	v_mfma_f32_16x16x32_bf16 v[2:5], v[184:187], v[220:223], v[2:5]
	s_barrier
	s_add_i32 s72, 0, 0x18000
	v_add_u32_e32 v150, s72, v151
	s_add_i32 s73, 0, 0x1c000
	ds_read_b128 v[156:159], v150
	ds_read_b128 v[160:163], v150 offset:1024
	ds_read_b128 v[164:167], v150 offset:2048
	ds_read_b128 v[168:171], v150 offset:3072
	v_add_u32_e32 v150, s73, v151
	ds_read_b128 v[172:175], v150
	ds_read_b128 v[176:179], v150 offset:1024
	ds_read_b128 v[180:183], v150 offset:2048
	ds_read_b128 v[184:187], v150 offset:3072
	s_add_u32 s44, s44, 0x40000
	s_addc_u32 s45, s45, 0
	s_mov_b32 m0, s50
	ds_read_b128 v[188:191], v154 offset:32768
	ds_read_b128 v[192:195], v154 offset:33792
	ds_read_b128 v[196:199], v154 offset:34816
	ds_read_b128 v[200:203], v154 offset:35840
	ds_read_b128 v[208:211], v154 offset:36864
	ds_read_b128 v[212:215], v154 offset:37888
	ds_read_b128 v[216:219], v154 offset:38912
	ds_read_b128 v[220:223], v154 offset:39936
	global_load_lds_dwordx4 v130, s[44:45]
	s_mov_b32 m0, s51
	s_nop 0
	global_load_lds_dwordx4 v134, s[44:45]
	s_waitcnt vmcnt(8)
	s_bitcmp1_b32 s14, 0
	s_cbranch_scc1 .Lnl_740_2
	s_waitcnt lgkmcnt(0)
.Lnl_740_2:
	s_barrier
	s_waitcnt lgkmcnt(0)
	v_mfma_f32_16x16x32_bf16 v[126:129], v[156:159], v[188:191], v[126:129]
	v_mfma_f32_16x16x32_bf16 v[122:125], v[164:167], v[188:191], v[122:125]
	v_mfma_f32_16x16x32_bf16 v[110:113], v[156:159], v[196:199], v[110:113]
	v_mfma_f32_16x16x32_bf16 v[106:109], v[164:167], v[196:199], v[106:109]
	v_mfma_f32_16x16x32_bf16 v[94:97], v[156:159], v[208:211], v[94:97]
	v_mfma_f32_16x16x32_bf16 v[90:93], v[164:167], v[208:211], v[90:93]
	v_mfma_f32_16x16x32_bf16 v[78:81], v[156:159], v[216:219], v[78:81]
	v_mfma_f32_16x16x32_bf16 v[74:77], v[164:167], v[216:219], v[74:77]
	v_mfma_f32_16x16x32_bf16 v[126:129], v[160:163], v[192:195], v[126:129]
	v_mfma_f32_16x16x32_bf16 v[122:125], v[168:171], v[192:195], v[122:125]
	v_mfma_f32_16x16x32_bf16 v[110:113], v[160:163], v[200:203], v[110:113]
	v_mfma_f32_16x16x32_bf16 v[106:109], v[168:171], v[200:203], v[106:109]
	v_mfma_f32_16x16x32_bf16 v[94:97], v[160:163], v[212:215], v[94:97]
	v_mfma_f32_16x16x32_bf16 v[90:93], v[168:171], v[212:215], v[90:93]
	v_mfma_f32_16x16x32_bf16 v[78:81], v[160:163], v[220:223], v[78:81]
	v_mfma_f32_16x16x32_bf16 v[74:77], v[168:171], v[220:223], v[74:77]
	v_mfma_f32_16x16x32_bf16 v[118:121], v[172:175], v[188:191], v[118:121]
	v_mfma_f32_16x16x32_bf16 v[114:117], v[180:183], v[188:191], v[114:117]
	v_mfma_f32_16x16x32_bf16 v[102:105], v[172:175], v[196:199], v[102:105]
	v_mfma_f32_16x16x32_bf16 v[98:101], v[180:183], v[196:199], v[98:101]
	v_mfma_f32_16x16x32_bf16 v[86:89], v[172:175], v[208:211], v[86:89]
	v_mfma_f32_16x16x32_bf16 v[82:85], v[180:183], v[208:211], v[82:85]
	v_mfma_f32_16x16x32_bf16 v[70:73], v[172:175], v[216:219], v[70:73]
	v_mfma_f32_16x16x32_bf16 v[66:69], v[180:183], v[216:219], v[66:69]
	v_mfma_f32_16x16x32_bf16 v[118:121], v[176:179], v[192:195], v[118:121]
	v_mfma_f32_16x16x32_bf16 v[114:117], v[184:187], v[192:195], v[114:117]
	v_mfma_f32_16x16x32_bf16 v[102:105], v[176:179], v[200:203], v[102:105]
	v_mfma_f32_16x16x32_bf16 v[98:101], v[184:187], v[200:203], v[98:101]
	v_mfma_f32_16x16x32_bf16 v[86:89], v[176:179], v[212:215], v[86:89]
	v_mfma_f32_16x16x32_bf16 v[82:85], v[184:187], v[212:215], v[82:85]
	v_mfma_f32_16x16x32_bf16 v[70:73], v[176:179], v[220:223], v[70:73]
	v_mfma_f32_16x16x32_bf16 v[66:69], v[184:187], v[220:223], v[66:69]
	s_barrier
	s_add_i32 s44, s72, s47
	s_mov_b32 m0, s44
	ds_read_b128 v[188:191], v154 offset:49152
	ds_read_b128 v[192:195], v154 offset:50176
	ds_read_b128 v[196:199], v154 offset:51200
	ds_read_b128 v[200:203], v154 offset:52224
	ds_read_b128 v[208:211], v154 offset:53248
	ds_read_b128 v[212:215], v154 offset:54272
	ds_read_b128 v[216:219], v154 offset:55296
	ds_read_b128 v[220:223], v154 offset:56320
	s_add_u32 s98, s40, s12
	s_addc_u32 s99, s41, s13
	global_load_lds_dwordx4 v132, s[98:99]
	s_add_i32 m0, s44, 0x2000
	s_add_u32 s40, s40, 0x40080
	v_lshl_add_u64 v[148:149], v[204:205], 0, s[12:13]
	s_addc_u32 s41, s41, 0
	s_add_i32 s44, s73, s47
	global_load_lds_dwordx4 v[148:149], off
	s_mov_b32 m0, s44
	s_nop 0
	global_load_lds_dwordx4 v132, s[40:41]
	s_add_i32 m0, s44, 0x2000
	s_nop 0
	global_load_lds_dwordx4 v136, s[40:41]
	v_lshl_add_u64 v[148:149], v[224:225], 0, s[12:13]
	s_mov_b32 m0, s61
	s_nop 0
	global_load_lds_dwordx4 v[148:149], off
	v_lshl_add_u64 v[148:149], v[226:227], 0, s[12:13]
	s_mov_b32 m0, s62
	s_nop 0
	global_load_lds_dwordx4 v[148:149], off
	s_waitcnt vmcnt(8)
	s_bitcmp1_b32 s14, 0
	s_cbranch_scc1 .Lnl_740_3
	s_waitcnt lgkmcnt(0)
; #define PG8_STAGE(bufoff, gbase, voff) do { _Pragma("unroll") for (int _i = 0; _i < 2; ++_i) \
;         __builtin_amdgcn_global_load_lds((const unsigned*)((const char*)(gbase) + (voff)[_i]), (PG8_LAS unsigned*)(lds + (bufoff) + ldsw + _i * 8192), 16, 0, 0); } while (0)
; #define PG8_LDA(dst, b, h) do { _Pragma("unroll") for (int m = 0; m < 4; ++m) _Pragma("unroll") for (int k = 0; k < 2; ++k) dst[m][k] = *(const PG8_LAS bf16x8*)(lds + PG8_SA(b, h) + aoff + m * 2048 + k * 1024); } while (0)
; #define PG8_LDB(dst, b, h) do { _Pragma("unroll") for (int n = 0; n < 2; ++n) _Pragma("unroll") for (int k = 0; k < 2; ++k) dst[n][k] = *(const PG8_LAS bf16x8*)(lds + PG8_SB(b, h) + boff + n * 2048 + k * 1024); } while (0)
; #define PG8_SCHED __builtin_amdgcn_sched_barrier(0)
; template <class Epi, class Sched, bool ALIGN_EPI = false, bool SP2 = false>
; __device__ __forceinline__ void gemm_phase(PG8_LAS unsigned char* lds, const Gemm g, const Sched& S, const Epi& E) {
;     ...
;         for (int t = 0; t < nt; t += 2) {
;             const bool last = (t == nt - 2);
;             const char* a1 = cA + (size_t)(t + 1) * kstep;
;             const char* a2 = last ? nA : cA + (size_t)(t + 2) * kstep; const char* b2 = last ? nB : cB + (size_t)(t + 2) * kstep;
;             const char* a3 = a2 + kstep; const char* b3 = b2 + kstep;
;             if (last && has_next) S.a_ready(nxt);
;             if constexpr (SP2) {
;             PG8_LDB(B0, 0, 0); PG8_LDB(B1, 0, 1); PG8_SCHED; PG8_LDA(At, 0, 0); PG8_STAGE(PG8_SA(1, 1), a1 + hstep, voffA);
.Lnl_740_3:
	s_barrier
	s_waitcnt lgkmcnt(0)
	v_mfma_f32_16x16x32_bf16 v[62:65], v[156:159], v[188:191], v[62:65]
	v_mfma_f32_16x16x32_bf16 v[58:61], v[164:167], v[188:191], v[58:61]
	v_mfma_f32_16x16x32_bf16 v[46:49], v[156:159], v[196:199], v[46:49]
	v_mfma_f32_16x16x32_bf16 v[42:45], v[164:167], v[196:199], v[42:45]
	v_mfma_f32_16x16x32_bf16 v[30:33], v[156:159], v[208:211], v[30:33]
	v_mfma_f32_16x16x32_bf16 v[26:29], v[164:167], v[208:211], v[26:29]
	v_mfma_f32_16x16x32_bf16 v[14:17], v[156:159], v[216:219], v[14:17]
	v_mfma_f32_16x16x32_bf16 v[10:13], v[164:167], v[216:219], v[10:13]
	v_mfma_f32_16x16x32_bf16 v[62:65], v[160:163], v[192:195], v[62:65]
	v_mfma_f32_16x16x32_bf16 v[58:61], v[168:171], v[192:195], v[58:61]
	v_mfma_f32_16x16x32_bf16 v[46:49], v[160:163], v[200:203], v[46:49]
	v_mfma_f32_16x16x32_bf16 v[42:45], v[168:171], v[200:203], v[42:45]
	v_mfma_f32_16x16x32_bf16 v[30:33], v[160:163], v[212:215], v[30:33]
	v_mfma_f32_16x16x32_bf16 v[26:29], v[168:171], v[212:215], v[26:29]
	v_mfma_f32_16x16x32_bf16 v[14:17], v[160:163], v[220:223], v[14:17]
	v_mfma_f32_16x16x32_bf16 v[10:13], v[168:171], v[220:223], v[10:13]
	v_mfma_f32_16x16x32_bf16 v[54:57], v[172:175], v[188:191], v[54:57]
	v_mfma_f32_16x16x32_bf16 v[50:53], v[180:183], v[188:191], v[50:53]
	v_mfma_f32_16x16x32_bf16 v[38:41], v[172:175], v[196:199], v[38:41]
	v_mfma_f32_16x16x32_bf16 v[34:37], v[180:183], v[196:199], v[34:37]
	v_mfma_f32_16x16x32_bf16 v[22:25], v[172:175], v[208:211], v[22:25]
	v_mfma_f32_16x16x32_bf16 v[18:21], v[180:183], v[208:211], v[18:21]
	v_mfma_f32_16x16x32_bf16 v[6:9], v[172:175], v[216:219], v[6:9]
	v_mfma_f32_16x16x32_bf16 v[2:5], v[180:183], v[216:219], v[2:5]
	v_mfma_f32_16x16x32_bf16 v[54:57], v[176:179], v[192:195], v[54:57]
	v_mfma_f32_16x16x32_bf16 v[50:53], v[184:187], v[192:195], v[50:53]
	v_mfma_f32_16x16x32_bf16 v[38:41], v[176:179], v[200:203], v[38:41]
	v_mfma_f32_16x16x32_bf16 v[34:37], v[184:187], v[200:203], v[34:37]
	v_mfma_f32_16x16x32_bf16 v[22:25], v[176:179], v[212:215], v[22:25]
	v_mfma_f32_16x16x32_bf16 v[18:21], v[184:187], v[212:215], v[18:21]
	v_mfma_f32_16x16x32_bf16 v[6:9], v[176:179], v[220:223], v[6:9]
	v_mfma_f32_16x16x32_bf16 v[2:5], v[184:187], v[220:223], v[2:5]
	s_add_i32 s71, s71, 2
	s_add_u32 s30, s30, 0x100
	s_addc_u32 s31, s31, 0
	s_add_u32 s33, s33, 0x100
	s_addc_u32 s70, s70, 0
	s_cmp_gt_u32 s71, 13
	s_barrier
.LBB0_740:
	ds_read_b128 v[156:159], v152
	ds_read_b128 v[160:163], v152 offset:1024
	ds_read_b128 v[164:167], v152 offset:2048
	ds_read_b128 v[168:171], v152 offset:3072
	ds_read_b128 v[172:175], v153
	ds_read_b128 v[176:179], v153 offset:1024
	ds_read_b128 v[180:183], v153 offset:2048
	ds_read_b128 v[184:187], v153 offset:3072
	s_add_u32 s40, s30, 0xfffc0080
	s_addc_u32 s41, s31, -1
	s_cmp_eq_u32 s71, 12
	s_cselect_b32 s45, s19, s41
	s_cselect_b32 s44, s25, s40
	s_cselect_b32 s41, s17, s70
	s_cselect_b32 s40, s27, s33
	v_lshl_add_u64 v[148:149], s[30:31], 0, v[140:141]
	s_add_i32 m0, s48, 0xc000
	ds_read_b128 v[188:191], v154
	ds_read_b128 v[192:195], v154 offset:1024
	ds_read_b128 v[196:199], v154 offset:2048
	ds_read_b128 v[200:203], v154 offset:3072
	ds_read_b128 v[208:211], v154 offset:4096
	ds_read_b128 v[212:215], v154 offset:5120
	ds_read_b128 v[216:219], v154 offset:6144
	ds_read_b128 v[220:223], v154 offset:7168
	global_load_lds_dwordx4 v[148:149], off
	v_lshl_add_u64 v[148:149], s[30:31], 0, v[142:143]
	s_add_i32 m0, s48, 0xe000
	s_nop 0
	global_load_lds_dwordx4 v[148:149], off
	s_waitcnt vmcnt(8)
	s_bitcmp1_b32 s14, 0
	s_cbranch_scc1 .Lnl_740_4
	s_waitcnt lgkmcnt(0)
; #define PG8_STAGE(bufoff, gbase, voff) do { _Pragma("unroll") for (int _i = 0; _i < 2; ++_i) \
;         __builtin_amdgcn_global_load_lds((const unsigned*)((const char*)(gbase) + (voff)[_i]), (PG8_LAS unsigned*)(lds + (bufoff) + ldsw + _i * 8192), 16, 0, 0); } while (0)
; #define PG8_LDA(dst, b, h) do { _Pragma("unroll") for (int m = 0; m < 4; ++m) _Pragma("unroll") for (int k = 0; k < 2; ++k) dst[m][k] = *(const PG8_LAS bf16x8*)(lds + PG8_SA(b, h) + aoff + m * 2048 + k * 1024); } while (0)
; #define PG8_LDB(dst, b, h) do { _Pragma("unroll") for (int n = 0; n < 2; ++n) _Pragma("unroll") for (int k = 0; k < 2; ++k) dst[n][k] = *(const PG8_LAS bf16x8*)(lds + PG8_SB(b, h) + boff + n * 2048 + k * 1024); } while (0)
; #define PG8_MMA(ai, bj, At, Bt) do { __builtin_amdgcn_s_setprio(1); _Pragma("unroll") for (int m = 0; m < 4; ++m) _Pragma("unroll") for (int n = 0; n < 2; ++n) _Pragma("unroll") for (int k = 0; k < 2; ++k) \
;         acc[ai][bj][m][n] = __builtin_amdgcn_mfma_f32_16x16x32_bf16(Bt[n][k], At[m][k], acc[ai][bj][m][n], 0, 0, 0); __builtin_amdgcn_s_setprio(0); } while (0)
; #define PG8_WAIT_V(n) asm volatile("s_waitcnt vmcnt(" #n ")" ::: "memory")
; template <class Epi, class Sched, bool ALIGN_EPI = false, bool SP2 = false>
; __device__ __forceinline__ void gemm_phase(PG8_LAS unsigned char* lds, const Gemm g, const Sched& S, const Epi& E) {
;     ...
;             PG8_LDB(B0, 0, 0); PG8_LDB(B1, 0, 1); PG8_SCHED; PG8_LDA(At, 0, 0); PG8_STAGE(PG8_SA(1, 1), a1 + hstep, voffA);
;             PG8_WAIT_V(8); PG8_WAIT_L(0); PG8_BAR; PG8_MMA(0, 0, At, B0); PG8_MMA(0, 1, At, B1); PG8_BAR; PG8_SCHED;
;             PG8_LDA(At, 0, 1); PG8_STAGE(PG8_SB(0, 0), b2, voffB); PG8_STAGE(PG8_SB(0, 1), b2 + hstep, voffB); PG8_STAGE(PG8_SA(0, 0), a2, voffA);
;             PG8_WAIT_V(8); PG8_WAIT_L(0); PG8_BAR; PG8_MMA(1, 0, At, B0); PG8_MMA(1, 1, At, B1); PG8_BAR; PG8_SCHED;
;             PG8_LDB(B0, 1, 0); PG8_LDB(B1, 1, 1); PG8_SCHED; PG8_LDA(At, 1, 0); PG8_STAGE(PG8_SA(0, 1), a2 + hstep, voffA);
;             PG8_WAIT_V(8); PG8_WAIT_L(0); PG8_BAR; PG8_MMA(0, 0, At, B0); PG8_MMA(0, 1, At, B1); PG8_BAR; PG8_SCHED;
;             PG8_LDA(At, 1, 1); PG8_STAGE(PG8_SB(1, 0), b3, voffB); PG8_STAGE(PG8_SB(1, 1), b3 + hstep, voffB); PG8_STAGE(PG8_SA(1, 0), a3, voffA);
;             PG8_WAIT_V(8); PG8_WAIT_L(0); PG8_BAR; PG8_MMA(1, 0, At, B0); PG8_MMA(1, 1, At, B1); PG8_BAR; PG8_SCHED;
.Lnl_740_4:
	s_barrier
	s_waitcnt lgkmcnt(0)
	v_mfma_f32_16x16x32_bf16 v[126:129], v[156:159], v[188:191], v[126:129]
	v_mfma_f32_16x16x32_bf16 v[122:125], v[164:167], v[188:191], v[122:125]
	v_mfma_f32_16x16x32_bf16 v[110:113], v[156:159], v[196:199], v[110:113]
	v_mfma_f32_16x16x32_bf16 v[106:109], v[164:167], v[196:199], v[106:109]
	v_mfma_f32_16x16x32_bf16 v[94:97], v[156:159], v[208:211], v[94:97]
	v_mfma_f32_16x16x32_bf16 v[90:93], v[164:167], v[208:211], v[90:93]
	v_mfma_f32_16x16x32_bf16 v[78:81], v[156:159], v[216:219], v[78:81]
	v_mfma_f32_16x16x32_bf16 v[74:77], v[164:167], v[216:219], v[74:77]
	v_mfma_f32_16x16x32_bf16 v[126:129], v[160:163], v[192:195], v[126:129]
	v_mfma_f32_16x16x32_bf16 v[122:125], v[168:171], v[192:195], v[122:125]
	v_mfma_f32_16x16x32_bf16 v[110:113], v[160:163], v[200:203], v[110:113]
	v_mfma_f32_16x16x32_bf16 v[106:109], v[168:171], v[200:203], v[106:109]
	v_mfma_f32_16x16x32_bf16 v[94:97], v[160:163], v[212:215], v[94:97]
	v_mfma_f32_16x16x32_bf16 v[90:93], v[168:171], v[212:215], v[90:93]
	v_mfma_f32_16x16x32_bf16 v[78:81], v[160:163], v[220:223], v[78:81]
	v_mfma_f32_16x16x32_bf16 v[74:77], v[168:171], v[220:223], v[74:77]
	v_mfma_f32_16x16x32_bf16 v[118:121], v[172:175], v[188:191], v[118:121]
	v_mfma_f32_16x16x32_bf16 v[114:117], v[180:183], v[188:191], v[114:117]
	v_mfma_f32_16x16x32_bf16 v[102:105], v[172:175], v[196:199], v[102:105]
	v_mfma_f32_16x16x32_bf16 v[98:101], v[180:183], v[196:199], v[98:101]
	v_mfma_f32_16x16x32_bf16 v[86:89], v[172:175], v[208:211], v[86:89]
	v_mfma_f32_16x16x32_bf16 v[82:85], v[180:183], v[208:211], v[82:85]
	v_mfma_f32_16x16x32_bf16 v[70:73], v[172:175], v[216:219], v[70:73]
	v_mfma_f32_16x16x32_bf16 v[66:69], v[180:183], v[216:219], v[66:69]
	v_mfma_f32_16x16x32_bf16 v[118:121], v[176:179], v[192:195], v[118:121]
	v_mfma_f32_16x16x32_bf16 v[114:117], v[184:187], v[192:195], v[114:117]
	v_mfma_f32_16x16x32_bf16 v[102:105], v[176:179], v[200:203], v[102:105]
	v_mfma_f32_16x16x32_bf16 v[98:101], v[184:187], v[200:203], v[98:101]
	v_mfma_f32_16x16x32_bf16 v[86:89], v[176:179], v[212:215], v[86:89]
	v_mfma_f32_16x16x32_bf16 v[82:85], v[184:187], v[212:215], v[82:85]
	v_mfma_f32_16x16x32_bf16 v[70:73], v[176:179], v[220:223], v[70:73]
	v_mfma_f32_16x16x32_bf16 v[66:69], v[184:187], v[220:223], v[66:69]
	s_barrier
	s_add_i32 s72, s66, s47
	s_mov_b32 m0, s72
	ds_read_b128 v[188:191], v154 offset:16384
	ds_read_b128 v[192:195], v154 offset:17408
	ds_read_b128 v[196:199], v154 offset:18432
	ds_read_b128 v[200:203], v154 offset:19456
	ds_read_b128 v[208:211], v154 offset:20480
	ds_read_b128 v[212:215], v154 offset:21504
	ds_read_b128 v[216:219], v154 offset:22528
	ds_read_b128 v[220:223], v154 offset:23552
	global_load_lds_dwordx4 v132, s[40:41]
	s_add_i32 m0, s72, 0x2000
	s_add_u32 s72, s40, 0x40000
	v_lshl_add_u64 v[204:205], s[40:41], 0, v[136:137]
	s_addc_u32 s73, s41, 0
	s_add_i32 s74, s67, s47
	global_load_lds_dwordx4 v136, s[40:41]
	s_mov_b32 m0, s74
	v_lshl_add_u64 v[226:227], s[44:45], 0, v[134:135]
	global_load_lds_dwordx4 v132, s[72:73]
	s_add_i32 m0, s74, 0x2000
	s_nop 0
	global_load_lds_dwordx4 v136, s[72:73]
	v_lshl_add_u64 v[224:225], s[44:45], 0, v[130:131]
	s_mov_b32 m0, s48
	s_nop 0
	global_load_lds_dwordx4 v130, s[44:45]
	s_mov_b32 m0, s49
	s_nop 0
	global_load_lds_dwordx4 v134, s[44:45]
	s_waitcnt vmcnt(8)
	s_bitcmp1_b32 s14, 0
	s_cbranch_scc1 .Lnl_740_5
	s_waitcnt lgkmcnt(0)
.Lnl_740_5:
	s_barrier
	s_waitcnt lgkmcnt(0)
	v_mfma_f32_16x16x32_bf16 v[62:65], v[156:159], v[188:191], v[62:65]
	v_mfma_f32_16x16x32_bf16 v[58:61], v[164:167], v[188:191], v[58:61]
	v_mfma_f32_16x16x32_bf16 v[46:49], v[156:159], v[196:199], v[46:49]
	v_mfma_f32_16x16x32_bf16 v[42:45], v[164:167], v[196:199], v[42:45]
	v_mfma_f32_16x16x32_bf16 v[30:33], v[156:159], v[208:211], v[30:33]
	v_mfma_f32_16x16x32_bf16 v[26:29], v[164:167], v[208:211], v[26:29]
	v_mfma_f32_16x16x32_bf16 v[14:17], v[156:159], v[216:219], v[14:17]
	v_mfma_f32_16x16x32_bf16 v[10:13], v[164:167], v[216:219], v[10:13]
	v_mfma_f32_16x16x32_bf16 v[62:65], v[160:163], v[192:195], v[62:65]
	v_mfma_f32_16x16x32_bf16 v[58:61], v[168:171], v[192:195], v[58:61]
	v_mfma_f32_16x16x32_bf16 v[46:49], v[160:163], v[200:203], v[46:49]
	v_mfma_f32_16x16x32_bf16 v[42:45], v[168:171], v[200:203], v[42:45]
	v_mfma_f32_16x16x32_bf16 v[30:33], v[160:163], v[212:215], v[30:33]
	v_mfma_f32_16x16x32_bf16 v[26:29], v[168:171], v[212:215], v[26:29]
	v_mfma_f32_16x16x32_bf16 v[14:17], v[160:163], v[220:223], v[14:17]
	v_mfma_f32_16x16x32_bf16 v[10:13], v[168:171], v[220:223], v[10:13]
	v_mfma_f32_16x16x32_bf16 v[54:57], v[172:175], v[188:191], v[54:57]
	v_mfma_f32_16x16x32_bf16 v[50:53], v[180:183], v[188:191], v[50:53]
	v_mfma_f32_16x16x32_bf16 v[38:41], v[172:175], v[196:199], v[38:41]
	v_mfma_f32_16x16x32_bf16 v[34:37], v[180:183], v[196:199], v[34:37]
	v_mfma_f32_16x16x32_bf16 v[22:25], v[172:175], v[208:211], v[22:25]
	v_mfma_f32_16x16x32_bf16 v[18:21], v[180:183], v[208:211], v[18:21]
	v_mfma_f32_16x16x32_bf16 v[6:9], v[172:175], v[216:219], v[6:9]
	v_mfma_f32_16x16x32_bf16 v[2:5], v[180:183], v[216:219], v[2:5]
	v_mfma_f32_16x16x32_bf16 v[54:57], v[176:179], v[192:195], v[54:57]
	v_mfma_f32_16x16x32_bf16 v[50:53], v[184:187], v[192:195], v[50:53]
	v_mfma_f32_16x16x32_bf16 v[38:41], v[176:179], v[200:203], v[38:41]
	v_mfma_f32_16x16x32_bf16 v[34:37], v[184:187], v[200:203], v[34:37]
	v_mfma_f32_16x16x32_bf16 v[22:25], v[176:179], v[212:215], v[22:25]
	v_mfma_f32_16x16x32_bf16 v[18:21], v[184:187], v[212:215], v[18:21]
	v_mfma_f32_16x16x32_bf16 v[6:9], v[176:179], v[220:223], v[6:9]
	v_mfma_f32_16x16x32_bf16 v[2:5], v[184:187], v[220:223], v[2:5]
	s_barrier
	s_add_i32 s72, 0, 0x18000
	v_add_u32_e32 v150, s72, v151
	s_add_i32 s73, 0, 0x1c000
	ds_read_b128 v[156:159], v150
	ds_read_b128 v[160:163], v150 offset:1024
	ds_read_b128 v[164:167], v150 offset:2048
	ds_read_b128 v[168:171], v150 offset:3072
	v_add_u32_e32 v150, s73, v151
	ds_read_b128 v[172:175], v150
	ds_read_b128 v[176:179], v150 offset:1024
	ds_read_b128 v[180:183], v150 offset:2048
	ds_read_b128 v[184:187], v150 offset:3072
	s_add_u32 s44, s44, 0x40000
	s_addc_u32 s45, s45, 0
	s_mov_b32 m0, s50
	ds_read_b128 v[188:191], v154 offset:32768
	ds_read_b128 v[192:195], v154 offset:33792
	ds_read_b128 v[196:199], v154 offset:34816
	ds_read_b128 v[200:203], v154 offset:35840
	ds_read_b128 v[208:211], v154 offset:36864
	ds_read_b128 v[212:215], v154 offset:37888
	ds_read_b128 v[216:219], v154 offset:38912
	ds_read_b128 v[220:223], v154 offset:39936
	global_load_lds_dwordx4 v130, s[44:45]
	s_mov_b32 m0, s51
	s_nop 0
	global_load_lds_dwordx4 v134, s[44:45]
	s_waitcnt vmcnt(8)
	s_bitcmp1_b32 s14, 0
	s_cbranch_scc1 .Lnl_740_6
	s_waitcnt lgkmcnt(0)

; #define PG8_MMA(ai, bj, At, Bt) do { __builtin_amdgcn_s_setprio(1); _Pragma("unroll") for (int m = 0; m < 4; ++m) _Pragma("unroll") for (int n = 0; n < 2; ++n) _Pragma("unroll") for (int k = 0; k < 2; ++k) \
;         acc[ai][bj][m][n] = __builtin_amdgcn_mfma_f32_16x16x32_bf16(Bt[n][k], At[m][k], acc[ai][bj][m][n], 0, 0, 0); __builtin_amdgcn_s_setprio(0); } while (0)
; #define PG8_WAIT_V(n) asm volatile("s_waitcnt vmcnt(" #n ")" ::: "memory")
; #define PG8_WAIT_L(n) asm volatile("s_waitcnt lgkmcnt(" #n ")" ::: "memory")
; #define PG8_BAR __builtin_amdgcn_s_barrier()
; #define PG8_SCHED __builtin_amdgcn_sched_barrier(0)
; template <class Epi, class Sched, bool ALIGN_EPI = false, bool SP2 = false>
; __device__ __forceinline__ void gemm_phase(PG8_LAS unsigned char* lds, const Gemm g, const Sched& S, const Epi& E) {
;     ...
;             PG8_WAIT_V(8); PG8_WAIT_L(0); PG8_BAR; PG8_MMA(1, 0, At, B0); PG8_MMA(1, 1, At, B1); PG8_BAR; PG8_SCHED;
;     ...
;         if constexpr (ALIGN_EPI) { if (wr == 0) PG8_BAR; }
.Lnl_740_7:
	s_barrier
	s_waitcnt lgkmcnt(0)
	v_mfma_f32_16x16x32_bf16 v[62:65], v[156:159], v[188:191], v[62:65]
	v_mfma_f32_16x16x32_bf16 v[58:61], v[164:167], v[188:191], v[58:61]
	v_mfma_f32_16x16x32_bf16 v[46:49], v[156:159], v[196:199], v[46:49]
	v_mfma_f32_16x16x32_bf16 v[42:45], v[164:167], v[196:199], v[42:45]
	v_mfma_f32_16x16x32_bf16 v[30:33], v[156:159], v[208:211], v[30:33]
	v_mfma_f32_16x16x32_bf16 v[26:29], v[164:167], v[208:211], v[26:29]
	v_mfma_f32_16x16x32_bf16 v[14:17], v[156:159], v[216:219], v[14:17]
	v_mfma_f32_16x16x32_bf16 v[10:13], v[164:167], v[216:219], v[10:13]
	v_mfma_f32_16x16x32_bf16 v[62:65], v[160:163], v[192:195], v[62:65]
	v_mfma_f32_16x16x32_bf16 v[58:61], v[168:171], v[192:195], v[58:61]
	v_mfma_f32_16x16x32_bf16 v[46:49], v[160:163], v[200:203], v[46:49]
	v_mfma_f32_16x16x32_bf16 v[42:45], v[168:171], v[200:203], v[42:45]
	v_mfma_f32_16x16x32_bf16 v[30:33], v[160:163], v[212:215], v[30:33]
	v_mfma_f32_16x16x32_bf16 v[26:29], v[168:171], v[212:215], v[26:29]
	v_mfma_f32_16x16x32_bf16 v[14:17], v[160:163], v[220:223], v[14:17]
	v_mfma_f32_16x16x32_bf16 v[10:13], v[168:171], v[220:223], v[10:13]
	v_mfma_f32_16x16x32_bf16 v[54:57], v[172:175], v[188:191], v[54:57]
	v_mfma_f32_16x16x32_bf16 v[50:53], v[180:183], v[188:191], v[50:53]
	v_mfma_f32_16x16x32_bf16 v[38:41], v[172:175], v[196:199], v[38:41]
	v_mfma_f32_16x16x32_bf16 v[34:37], v[180:183], v[196:199], v[34:37]
	v_mfma_f32_16x16x32_bf16 v[22:25], v[172:175], v[208:211], v[22:25]
	v_mfma_f32_16x16x32_bf16 v[18:21], v[180:183], v[208:211], v[18:21]
	v_mfma_f32_16x16x32_bf16 v[6:9], v[172:175], v[216:219], v[6:9]
	v_mfma_f32_16x16x32_bf16 v[2:5], v[180:183], v[216:219], v[2:5]
	v_mfma_f32_16x16x32_bf16 v[54:57], v[176:179], v[192:195], v[54:57]
	v_mfma_f32_16x16x32_bf16 v[50:53], v[184:187], v[192:195], v[50:53]
	v_mfma_f32_16x16x32_bf16 v[38:41], v[176:179], v[200:203], v[38:41]
	v_mfma_f32_16x16x32_bf16 v[34:37], v[184:187], v[200:203], v[34:37]
	v_mfma_f32_16x16x32_bf16 v[22:25], v[176:179], v[212:215], v[22:25]
	v_mfma_f32_16x16x32_bf16 v[18:21], v[184:187], v[212:215], v[18:21]
	v_mfma_f32_16x16x32_bf16 v[6:9], v[176:179], v[220:223], v[6:9]
	v_mfma_f32_16x16x32_bf16 v[2:5], v[184:187], v[220:223], v[2:5]
	s_add_i32 s71, s71, 2
	s_add_u32 s30, s30, 0x100
	s_addc_u32 s31, s31, 0
	s_add_u32 s33, s33, 0x100
	s_addc_u32 s70, s70, 0
	s_cmp_gt_u32 s71, 13
	s_barrier
	s_cbranch_scc0 .LBB0_740
	s_and_b64 vcc, exec, s[14:15]
	s_cbranch_vccz .LBB0_743
	s_barrier

; #define PG8_STAGE(bufoff, gbase, voff) do { _Pragma("unroll") for (int _i = 0; _i < 2; ++_i) \
;         __builtin_amdgcn_global_load_lds((const unsigned*)((const char*)(gbase) + (voff)[_i]), (PG8_LAS unsigned*)(lds + (bufoff) + ldsw + _i * 8192), 16, 0, 0); } while (0)
; #define PG8_LDA(dst, b, h) do { _Pragma("unroll") for (int m = 0; m < 4; ++m) _Pragma("unroll") for (int k = 0; k < 2; ++k) dst[m][k] = *(const PG8_LAS bf16x8*)(lds + PG8_SA(b, h) + aoff + m * 2048 + k * 1024); } while (0)
; #define PG8_LDB(dst, b, h) do { _Pragma("unroll") for (int n = 0; n < 2; ++n) _Pragma("unroll") for (int k = 0; k < 2; ++k) dst[n][k] = *(const PG8_LAS bf16x8*)(lds + PG8_SB(b, h) + boff + n * 2048 + k * 1024); } while (0)
; #define PG8_MMA(ai, bj, At, Bt) do { __builtin_amdgcn_s_setprio(1); _Pragma("unroll") for (int m = 0; m < 4; ++m) _Pragma("unroll") for (int n = 0; n < 2; ++n) _Pragma("unroll") for (int k = 0; k < 2; ++k) \
;         acc[ai][bj][m][n] = __builtin_amdgcn_mfma_f32_16x16x32_bf16(Bt[n][k], At[m][k], acc[ai][bj][m][n], 0, 0, 0); __builtin_amdgcn_s_setprio(0); } while (0)
; #define PG8_WAIT_V(n) asm volatile("s_waitcnt vmcnt(" #n ")" ::: "memory")
; #define PG8_WAIT_L(n) asm volatile("s_waitcnt lgkmcnt(" #n ")" ::: "memory")
; #define PG8_BAR __builtin_amdgcn_s_barrier()
; #define PG8_SCHED __builtin_amdgcn_sched_barrier(0)
; template <class Epi, class Sched, bool ALIGN_EPI = false, bool SP2 = false>
; __device__ __forceinline__ void gemm_phase(PG8_LAS unsigned char* lds, const Gemm g, const Sched& S, const Epi& E) {
;     ...
;         for (int t = 0; t < nt; t += 2) {
;             const bool last = (t == nt - 2);
;             const char* a1 = cA + (size_t)(t + 1) * kstep;
;             const char* a2 = last ? nA : cA + (size_t)(t + 2) * kstep; const char* b2 = last ? nB : cB + (size_t)(t + 2) * kstep;
;             const char* a3 = a2 + kstep; const char* b3 = b2 + kstep;
;             if (last && has_next) S.a_ready(nxt);
;             if constexpr (SP2) {
;             PG8_LDB(B0, 0, 0); PG8_LDB(B1, 0, 1); PG8_SCHED; PG8_LDA(At, 0, 0); PG8_STAGE(PG8_SA(1, 1), a1 + hstep, voffA);
;             PG8_WAIT_V(8); PG8_WAIT_L(0); PG8_BAR; PG8_MMA(0, 0, At, B0); PG8_MMA(0, 1, At, B1); PG8_BAR; PG8_SCHED;
;             PG8_LDA(At, 0, 1); PG8_STAGE(PG8_SB(0, 0), b2, voffB); PG8_STAGE(PG8_SB(0, 1), b2 + hstep, voffB); PG8_STAGE(PG8_SA(0, 0), a2, voffA);
.LBB0_860:
	s_add_u32 s24, s24, 0xb0080
	s_addc_u32 s25, s25, 0
	s_add_u32 s51, s26, 0x100
	s_addc_u32 s52, s27, 0
	s_mov_b32 s53, -2
	ds_read_b128 v[146:149], v153
	ds_read_b128 v[156:159], v153 offset:1024
	ds_read_b128 v[160:163], v153 offset:2048
	ds_read_b128 v[164:167], v153 offset:3072
	ds_read_b128 v[168:171], v154
	ds_read_b128 v[172:175], v154 offset:1024
	ds_read_b128 v[176:179], v154 offset:2048
	ds_read_b128 v[180:183], v154 offset:3072
	s_add_u32 s26, s24, 0xfff50080
	s_addc_u32 s27, s25, -1
	s_cmp_eq_u32 s53, 40
	s_cselect_b32 s29, s5, s27
	s_cselect_b32 s28, s4, s26
	s_cselect_b32 s27, s23, s52
	s_cselect_b32 s26, s22, s51
	v_lshl_add_u64 v[150:151], s[24:25], 0, v[138:139]
	s_add_i32 m0, s33, 0xc000
	ds_read_b128 v[184:187], v155
	ds_read_b128 v[188:191], v155 offset:1024
	ds_read_b128 v[192:195], v155 offset:2048
	ds_read_b128 v[196:199], v155 offset:3072
	ds_read_b128 v[200:203], v155 offset:4096
	ds_read_b128 v[204:207], v155 offset:5120
	ds_read_b128 v[208:211], v155 offset:6144
	ds_read_b128 v[212:215], v155 offset:7168
	global_load_lds_dwordx4 v[150:151], off
	v_lshl_add_u64 v[150:151], s[24:25], 0, v[140:141]
	s_add_i32 m0, s33, 0xe000
	s_nop 0
	global_load_lds_dwordx4 v[150:151], off
	s_waitcnt vmcnt(8)
	s_bitcmp1_b32 s12, 0
	s_cbranch_scc1 .Lnl_861_0
	s_waitcnt lgkmcnt(0)
.Lnl_861_0:
	s_barrier
	s_waitcnt lgkmcnt(0)
	v_mfma_f32_16x16x32_bf16 v[124:127], v[146:149], v[184:187], 0
	v_mfma_f32_16x16x32_bf16 v[120:123], v[160:163], v[184:187], 0
	v_mfma_f32_16x16x32_bf16 v[108:111], v[146:149], v[192:195], 0
	v_mfma_f32_16x16x32_bf16 v[104:107], v[160:163], v[192:195], 0
	v_mfma_f32_16x16x32_bf16 v[92:95], v[146:149], v[200:203], 0
	v_mfma_f32_16x16x32_bf16 v[88:91], v[160:163], v[200:203], 0
	v_mfma_f32_16x16x32_bf16 v[76:79], v[146:149], v[208:211], 0
	v_mfma_f32_16x16x32_bf16 v[72:75], v[160:163], v[208:211], 0
	v_mfma_f32_16x16x32_bf16 v[124:127], v[156:159], v[188:191], v[124:127]
	v_mfma_f32_16x16x32_bf16 v[120:123], v[164:167], v[188:191], v[120:123]
	v_mfma_f32_16x16x32_bf16 v[108:111], v[156:159], v[196:199], v[108:111]
	v_mfma_f32_16x16x32_bf16 v[104:107], v[164:167], v[196:199], v[104:107]
	v_mfma_f32_16x16x32_bf16 v[92:95], v[156:159], v[204:207], v[92:95]
	v_mfma_f32_16x16x32_bf16 v[88:91], v[164:167], v[204:207], v[88:91]
	v_mfma_f32_16x16x32_bf16 v[76:79], v[156:159], v[212:215], v[76:79]
	v_mfma_f32_16x16x32_bf16 v[72:75], v[164:167], v[212:215], v[72:75]
	v_mfma_f32_16x16x32_bf16 v[116:119], v[168:171], v[184:187], 0
	v_mfma_f32_16x16x32_bf16 v[112:115], v[176:179], v[184:187], 0
	v_mfma_f32_16x16x32_bf16 v[100:103], v[168:171], v[192:195], 0
	v_mfma_f32_16x16x32_bf16 v[96:99], v[176:179], v[192:195], 0
	v_mfma_f32_16x16x32_bf16 v[84:87], v[168:171], v[200:203], 0
	v_mfma_f32_16x16x32_bf16 v[80:83], v[176:179], v[200:203], 0
	v_mfma_f32_16x16x32_bf16 v[68:71], v[168:171], v[208:211], 0
	v_mfma_f32_16x16x32_bf16 v[64:67], v[176:179], v[208:211], 0
	v_mfma_f32_16x16x32_bf16 v[116:119], v[172:175], v[188:191], v[116:119]
	v_mfma_f32_16x16x32_bf16 v[112:115], v[180:183], v[188:191], v[112:115]
	v_mfma_f32_16x16x32_bf16 v[100:103], v[172:175], v[196:199], v[100:103]
	v_mfma_f32_16x16x32_bf16 v[96:99], v[180:183], v[196:199], v[96:99]
	v_mfma_f32_16x16x32_bf16 v[84:87], v[172:175], v[204:207], v[84:87]
	v_mfma_f32_16x16x32_bf16 v[80:83], v[180:183], v[204:207], v[80:83]
	v_mfma_f32_16x16x32_bf16 v[68:71], v[172:175], v[212:215], v[68:71]
	v_mfma_f32_16x16x32_bf16 v[64:67], v[180:183], v[212:215], v[64:67]
	s_barrier
	s_add_i32 s56, s45, s31
	s_mov_b32 m0, s56
	ds_read_b128 v[184:187], v155 offset:16384
	ds_read_b128 v[188:191], v155 offset:17408
	ds_read_b128 v[192:195], v155 offset:18432
	ds_read_b128 v[196:199], v155 offset:19456
	ds_read_b128 v[200:203], v155 offset:20480
	ds_read_b128 v[204:207], v155 offset:21504
	ds_read_b128 v[208:211], v155 offset:22528
	ds_read_b128 v[212:215], v155 offset:23552
	global_load_lds_dwordx4 v130, s[26:27]
	s_add_i32 m0, s56, 0x2000
	s_add_u32 s56, s26, 0xb0000
	v_lshl_add_u64 v[216:217], s[26:27], 0, v[134:135]
	s_addc_u32 s57, s27, 0
	s_add_i32 s58, s46, s31
	global_load_lds_dwordx4 v134, s[26:27]
	s_mov_b32 m0, s58
	v_lshl_add_u64 v[220:221], s[28:29], 0, v[132:133]
	global_load_lds_dwordx4 v130, s[56:57]
	s_add_i32 m0, s58, 0x2000
	s_nop 0
	global_load_lds_dwordx4 v134, s[56:57]
	v_lshl_add_u64 v[218:219], s[28:29], 0, v[128:129]
	s_mov_b32 m0, s33
	s_nop 0
	global_load_lds_dwordx4 v128, s[28:29]
	s_mov_b32 m0, s36
	s_nop 0
	global_load_lds_dwordx4 v132, s[28:29]
	s_waitcnt vmcnt(8)
	s_bitcmp1_b32 s12, 0
	s_cbranch_scc1 .Lnl_861_1
	s_waitcnt lgkmcnt(0)
; #define PG8_STAGE(bufoff, gbase, voff) do { _Pragma("unroll") for (int _i = 0; _i < 2; ++_i) \
;         __builtin_amdgcn_global_load_lds((const unsigned*)((const char*)(gbase) + (voff)[_i]), (PG8_LAS unsigned*)(lds + (bufoff) + ldsw + _i * 8192), 16, 0, 0); } while (0)
; #define PG8_LDA(dst, b, h) do { _Pragma("unroll") for (int m = 0; m < 4; ++m) _Pragma("unroll") for (int k = 0; k < 2; ++k) dst[m][k] = *(const PG8_LAS bf16x8*)(lds + PG8_SA(b, h) + aoff + m * 2048 + k * 1024); } while (0)
; #define PG8_LDB(dst, b, h) do { _Pragma("unroll") for (int n = 0; n < 2; ++n) _Pragma("unroll") for (int k = 0; k < 2; ++k) dst[n][k] = *(const PG8_LAS bf16x8*)(lds + PG8_SB(b, h) + boff + n * 2048 + k * 1024); } while (0)
; #define PG8_MMA(ai, bj, At, Bt) do { __builtin_amdgcn_s_setprio(1); _Pragma("unroll") for (int m = 0; m < 4; ++m) _Pragma("unroll") for (int n = 0; n < 2; ++n) _Pragma("unroll") for (int k = 0; k < 2; ++k) \
;         acc[ai][bj][m][n] = __builtin_amdgcn_mfma_f32_16x16x32_bf16(Bt[n][k], At[m][k], acc[ai][bj][m][n], 0, 0, 0); __builtin_amdgcn_s_setprio(0); } while (0)
; #define PG8_WAIT_V(n) asm volatile("s_waitcnt vmcnt(" #n ")" ::: "memory")
; template <class Epi, class Sched, bool ALIGN_EPI = false, bool SP2 = false>
; __device__ __forceinline__ void gemm_phase(PG8_LAS unsigned char* lds, const Gemm g, const Sched& S, const Epi& E) {
;     ...
;             PG8_LDB(B0, 0, 0); PG8_LDB(B1, 0, 1); PG8_SCHED; PG8_LDA(At, 0, 0); PG8_STAGE(PG8_SA(1, 1), a1 + hstep, voffA);
;             PG8_WAIT_V(8); PG8_WAIT_L(0); PG8_BAR; PG8_MMA(0, 0, At, B0); PG8_MMA(0, 1, At, B1); PG8_BAR; PG8_SCHED;
;             PG8_LDA(At, 0, 1); PG8_STAGE(PG8_SB(0, 0), b2, voffB); PG8_STAGE(PG8_SB(0, 1), b2 + hstep, voffB); PG8_STAGE(PG8_SA(0, 0), a2, voffA);
;             PG8_WAIT_V(8); PG8_WAIT_L(0); PG8_BAR; PG8_MMA(1, 0, At, B0); PG8_MMA(1, 1, At, B1); PG8_BAR; PG8_SCHED;
;             PG8_LDB(B0, 1, 0); PG8_LDB(B1, 1, 1); PG8_SCHED; PG8_LDA(At, 1, 0); PG8_STAGE(PG8_SA(0, 1), a2 + hstep, voffA);
;             PG8_WAIT_V(8); PG8_WAIT_L(0); PG8_BAR; PG8_MMA(0, 0, At, B0); PG8_MMA(0, 1, At, B1); PG8_BAR; PG8_SCHED;
;             PG8_LDA(At, 1, 1); PG8_STAGE(PG8_SB(1, 0), b3, voffB); PG8_STAGE(PG8_SB(1, 1), b3 + hstep, voffB); PG8_STAGE(PG8_SA(1, 0), a3, voffA);
;             PG8_WAIT_V(8); PG8_WAIT_L(0); PG8_BAR; PG8_MMA(1, 0, At, B0); PG8_MMA(1, 1, At, B1); PG8_BAR; PG8_SCHED;
.Lnl_861_1:
	s_barrier
	s_waitcnt lgkmcnt(0)
	v_mfma_f32_16x16x32_bf16 v[60:63], v[146:149], v[184:187], 0
	v_mfma_f32_16x16x32_bf16 v[56:59], v[160:163], v[184:187], 0
	v_mfma_f32_16x16x32_bf16 v[44:47], v[146:149], v[192:195], 0
	v_mfma_f32_16x16x32_bf16 v[40:43], v[160:163], v[192:195], 0
	v_mfma_f32_16x16x32_bf16 v[28:31], v[146:149], v[200:203], 0
	v_mfma_f32_16x16x32_bf16 v[24:27], v[160:163], v[200:203], 0
	v_mfma_f32_16x16x32_bf16 v[12:15], v[146:149], v[208:211], 0
	v_mfma_f32_16x16x32_bf16 v[8:11], v[160:163], v[208:211], 0
	v_mfma_f32_16x16x32_bf16 v[60:63], v[156:159], v[188:191], v[60:63]
	v_mfma_f32_16x16x32_bf16 v[56:59], v[164:167], v[188:191], v[56:59]
	v_mfma_f32_16x16x32_bf16 v[44:47], v[156:159], v[196:199], v[44:47]
	v_mfma_f32_16x16x32_bf16 v[40:43], v[164:167], v[196:199], v[40:43]
	v_mfma_f32_16x16x32_bf16 v[28:31], v[156:159], v[204:207], v[28:31]
	v_mfma_f32_16x16x32_bf16 v[24:27], v[164:167], v[204:207], v[24:27]
	v_mfma_f32_16x16x32_bf16 v[12:15], v[156:159], v[212:215], v[12:15]
	v_mfma_f32_16x16x32_bf16 v[8:11], v[164:167], v[212:215], v[8:11]
	v_mfma_f32_16x16x32_bf16 v[52:55], v[168:171], v[184:187], 0
	v_mfma_f32_16x16x32_bf16 v[48:51], v[176:179], v[184:187], 0
	v_mfma_f32_16x16x32_bf16 v[36:39], v[168:171], v[192:195], 0
	v_mfma_f32_16x16x32_bf16 v[32:35], v[176:179], v[192:195], 0
	v_mfma_f32_16x16x32_bf16 v[20:23], v[168:171], v[200:203], 0
	v_mfma_f32_16x16x32_bf16 v[16:19], v[176:179], v[200:203], 0
	v_mfma_f32_16x16x32_bf16 v[4:7], v[168:171], v[208:211], 0
	v_mfma_f32_16x16x32_bf16 v[0:3], v[176:179], v[208:211], 0
	v_mfma_f32_16x16x32_bf16 v[52:55], v[172:175], v[188:191], v[52:55]
	v_mfma_f32_16x16x32_bf16 v[48:51], v[180:183], v[188:191], v[48:51]
	v_mfma_f32_16x16x32_bf16 v[36:39], v[172:175], v[196:199], v[36:39]
	v_mfma_f32_16x16x32_bf16 v[32:35], v[180:183], v[196:199], v[32:35]
	v_mfma_f32_16x16x32_bf16 v[20:23], v[172:175], v[204:207], v[20:23]
	v_mfma_f32_16x16x32_bf16 v[16:19], v[180:183], v[204:207], v[16:19]
	v_mfma_f32_16x16x32_bf16 v[4:7], v[172:175], v[212:215], v[4:7]
	v_mfma_f32_16x16x32_bf16 v[0:3], v[180:183], v[212:215], v[0:3]
	s_barrier
	s_add_i32 s56, 0, 0x18000
	s_add_i32 s57, 0, 0x1c000
	v_add_u32_e32 v164, s56, v152
	v_add_u32_e32 v180, s57, v152
	ds_read_b128 v[146:149], v164
	ds_read_b128 v[156:159], v164 offset:1024
	ds_read_b128 v[160:163], v164 offset:2048
	ds_read_b128 v[164:167], v164 offset:3072
	ds_read_b128 v[168:171], v180
	ds_read_b128 v[172:175], v180 offset:1024
	ds_read_b128 v[176:179], v180 offset:2048
	ds_read_b128 v[180:183], v180 offset:3072
	s_add_u32 s28, s28, 0xb0000
	s_addc_u32 s29, s29, 0
	s_mov_b32 m0, s37
	ds_read_b128 v[184:187], v155 offset:32768
	ds_read_b128 v[188:191], v155 offset:33792
	ds_read_b128 v[192:195], v155 offset:34816
	ds_read_b128 v[196:199], v155 offset:35840
	ds_read_b128 v[200:203], v155 offset:36864
	ds_read_b128 v[204:207], v155 offset:37888
	ds_read_b128 v[208:211], v155 offset:38912
	ds_read_b128 v[212:215], v155 offset:39936
	global_load_lds_dwordx4 v128, s[28:29]
	s_mov_b32 m0, s38
	s_nop 0
	global_load_lds_dwordx4 v132, s[28:29]
	s_waitcnt vmcnt(8)
	s_bitcmp1_b32 s12, 0
	s_cbranch_scc1 .Lnl_861_2
	s_waitcnt lgkmcnt(0)
.Lnl_861_2:
	s_barrier
	s_waitcnt lgkmcnt(0)
	v_mfma_f32_16x16x32_bf16 v[124:127], v[146:149], v[184:187], v[124:127]
	v_mfma_f32_16x16x32_bf16 v[120:123], v[160:163], v[184:187], v[120:123]
	v_mfma_f32_16x16x32_bf16 v[108:111], v[146:149], v[192:195], v[108:111]
	v_mfma_f32_16x16x32_bf16 v[104:107], v[160:163], v[192:195], v[104:107]
	v_mfma_f32_16x16x32_bf16 v[92:95], v[146:149], v[200:203], v[92:95]
	v_mfma_f32_16x16x32_bf16 v[88:91], v[160:163], v[200:203], v[88:91]
	v_mfma_f32_16x16x32_bf16 v[76:79], v[146:149], v[208:211], v[76:79]
	v_mfma_f32_16x16x32_bf16 v[72:75], v[160:163], v[208:211], v[72:75]
	v_mfma_f32_16x16x32_bf16 v[124:127], v[156:159], v[188:191], v[124:127]
	v_mfma_f32_16x16x32_bf16 v[120:123], v[164:167], v[188:191], v[120:123]
	v_mfma_f32_16x16x32_bf16 v[108:111], v[156:159], v[196:199], v[108:111]
	v_mfma_f32_16x16x32_bf16 v[104:107], v[164:167], v[196:199], v[104:107]
	v_mfma_f32_16x16x32_bf16 v[92:95], v[156:159], v[204:207], v[92:95]
	v_mfma_f32_16x16x32_bf16 v[88:91], v[164:167], v[204:207], v[88:91]
	v_mfma_f32_16x16x32_bf16 v[76:79], v[156:159], v[212:215], v[76:79]
	v_mfma_f32_16x16x32_bf16 v[72:75], v[164:167], v[212:215], v[72:75]
	v_mfma_f32_16x16x32_bf16 v[116:119], v[168:171], v[184:187], v[116:119]
	v_mfma_f32_16x16x32_bf16 v[112:115], v[176:179], v[184:187], v[112:115]
	v_mfma_f32_16x16x32_bf16 v[100:103], v[168:171], v[192:195], v[100:103]
	v_mfma_f32_16x16x32_bf16 v[96:99], v[176:179], v[192:195], v[96:99]
	v_mfma_f32_16x16x32_bf16 v[84:87], v[168:171], v[200:203], v[84:87]
	v_mfma_f32_16x16x32_bf16 v[80:83], v[176:179], v[200:203], v[80:83]
	v_mfma_f32_16x16x32_bf16 v[68:71], v[168:171], v[208:211], v[68:71]
	v_mfma_f32_16x16x32_bf16 v[64:67], v[176:179], v[208:211], v[64:67]
	v_mfma_f32_16x16x32_bf16 v[116:119], v[172:175], v[188:191], v[116:119]
	v_mfma_f32_16x16x32_bf16 v[112:115], v[180:183], v[188:191], v[112:115]
	v_mfma_f32_16x16x32_bf16 v[100:103], v[172:175], v[196:199], v[100:103]
	v_mfma_f32_16x16x32_bf16 v[96:99], v[180:183], v[196:199], v[96:99]
	v_mfma_f32_16x16x32_bf16 v[84:87], v[172:175], v[204:207], v[84:87]
	v_mfma_f32_16x16x32_bf16 v[80:83], v[180:183], v[204:207], v[80:83]
	v_mfma_f32_16x16x32_bf16 v[68:71], v[172:175], v[212:215], v[68:71]
	v_mfma_f32_16x16x32_bf16 v[64:67], v[180:183], v[212:215], v[64:67]
	s_barrier
	s_add_i32 s28, s56, s31
	s_mov_b32 m0, s28
	ds_read_b128 v[184:187], v155 offset:49152
	ds_read_b128 v[188:191], v155 offset:50176
	ds_read_b128 v[192:195], v155 offset:51200
	ds_read_b128 v[196:199], v155 offset:52224
	ds_read_b128 v[200:203], v155 offset:53248
	ds_read_b128 v[204:207], v155 offset:54272
	ds_read_b128 v[208:211], v155 offset:55296
	ds_read_b128 v[212:215], v155 offset:56320
	s_add_u32 s98, s26, s10
	s_addc_u32 s99, s27, s11
	global_load_lds_dwordx4 v130, s[98:99]
	s_add_i32 m0, s28, 0x2000
	s_add_u32 s26, s26, 0xb0080
	v_lshl_add_u64 v[150:151], v[216:217], 0, s[10:11]
	s_addc_u32 s27, s27, 0
	s_add_i32 s28, s57, s31
	global_load_lds_dwordx4 v[150:151], off
	s_mov_b32 m0, s28
	s_nop 0
	global_load_lds_dwordx4 v130, s[26:27]
	s_add_i32 m0, s28, 0x2000
	s_nop 0
	global_load_lds_dwordx4 v134, s[26:27]
	v_lshl_add_u64 v[150:151], v[218:219], 0, s[10:11]
	s_mov_b32 m0, s40
	s_nop 0
	global_load_lds_dwordx4 v[150:151], off
	v_lshl_add_u64 v[150:151], v[220:221], 0, s[10:11]
	s_mov_b32 m0, s41
	s_nop 0
	global_load_lds_dwordx4 v[150:151], off
	s_waitcnt vmcnt(8)
	s_bitcmp1_b32 s12, 0
	s_cbranch_scc1 .Lnl_861_3
	s_waitcnt lgkmcnt(0)
; #define PG8_STAGE(bufoff, gbase, voff) do { _Pragma("unroll") for (int _i = 0; _i < 2; ++_i) \
;         __builtin_amdgcn_global_load_lds((const unsigned*)((const char*)(gbase) + (voff)[_i]), (PG8_LAS unsigned*)(lds + (bufoff) + ldsw + _i * 8192), 16, 0, 0); } while (0)
; #define PG8_LDA(dst, b, h) do { _Pragma("unroll") for (int m = 0; m < 4; ++m) _Pragma("unroll") for (int k = 0; k < 2; ++k) dst[m][k] = *(const PG8_LAS bf16x8*)(lds + PG8_SA(b, h) + aoff + m * 2048 + k * 1024); } while (0)
; #define PG8_LDB(dst, b, h) do { _Pragma("unroll") for (int n = 0; n < 2; ++n) _Pragma("unroll") for (int k = 0; k < 2; ++k) dst[n][k] = *(const PG8_LAS bf16x8*)(lds + PG8_SB(b, h) + boff + n * 2048 + k * 1024); } while (0)
; #define PG8_SCHED __builtin_amdgcn_sched_barrier(0)
; template <class Epi, class Sched, bool ALIGN_EPI = false, bool SP2 = false>
; __device__ __forceinline__ void gemm_phase(PG8_LAS unsigned char* lds, const Gemm g, const Sched& S, const Epi& E) {
;     ...
;         for (int t = 0; t < nt; t += 2) {
;             const bool last = (t == nt - 2);
;             const char* a1 = cA + (size_t)(t + 1) * kstep;
;             const char* a2 = last ? nA : cA + (size_t)(t + 2) * kstep; const char* b2 = last ? nB : cB + (size_t)(t + 2) * kstep;
;             const char* a3 = a2 + kstep; const char* b3 = b2 + kstep;
;             if (last && has_next) S.a_ready(nxt);
;             if constexpr (SP2) {
;             PG8_LDB(B0, 0, 0); PG8_LDB(B1, 0, 1); PG8_SCHED; PG8_LDA(At, 0, 0); PG8_STAGE(PG8_SA(1, 1), a1 + hstep, voffA);
.Lnl_861_3:
	s_barrier
	s_waitcnt lgkmcnt(0)
	v_mfma_f32_16x16x32_bf16 v[60:63], v[146:149], v[184:187], v[60:63]
	v_mfma_f32_16x16x32_bf16 v[56:59], v[160:163], v[184:187], v[56:59]
	v_mfma_f32_16x16x32_bf16 v[44:47], v[146:149], v[192:195], v[44:47]
	v_mfma_f32_16x16x32_bf16 v[40:43], v[160:163], v[192:195], v[40:43]
	v_mfma_f32_16x16x32_bf16 v[28:31], v[146:149], v[200:203], v[28:31]
	v_mfma_f32_16x16x32_bf16 v[24:27], v[160:163], v[200:203], v[24:27]
	v_mfma_f32_16x16x32_bf16 v[12:15], v[146:149], v[208:211], v[12:15]
	v_mfma_f32_16x16x32_bf16 v[8:11], v[160:163], v[208:211], v[8:11]
	v_mfma_f32_16x16x32_bf16 v[60:63], v[156:159], v[188:191], v[60:63]
	v_mfma_f32_16x16x32_bf16 v[56:59], v[164:167], v[188:191], v[56:59]
	v_mfma_f32_16x16x32_bf16 v[44:47], v[156:159], v[196:199], v[44:47]
	v_mfma_f32_16x16x32_bf16 v[40:43], v[164:167], v[196:199], v[40:43]
	v_mfma_f32_16x16x32_bf16 v[28:31], v[156:159], v[204:207], v[28:31]
	v_mfma_f32_16x16x32_bf16 v[24:27], v[164:167], v[204:207], v[24:27]
	v_mfma_f32_16x16x32_bf16 v[12:15], v[156:159], v[212:215], v[12:15]
	v_mfma_f32_16x16x32_bf16 v[8:11], v[164:167], v[212:215], v[8:11]
	v_mfma_f32_16x16x32_bf16 v[52:55], v[168:171], v[184:187], v[52:55]
	v_mfma_f32_16x16x32_bf16 v[48:51], v[176:179], v[184:187], v[48:51]
	v_mfma_f32_16x16x32_bf16 v[36:39], v[168:171], v[192:195], v[36:39]
	v_mfma_f32_16x16x32_bf16 v[32:35], v[176:179], v[192:195], v[32:35]
	v_mfma_f32_16x16x32_bf16 v[20:23], v[168:171], v[200:203], v[20:23]
	v_mfma_f32_16x16x32_bf16 v[16:19], v[176:179], v[200:203], v[16:19]
	v_mfma_f32_16x16x32_bf16 v[4:7], v[168:171], v[208:211], v[4:7]
	v_mfma_f32_16x16x32_bf16 v[0:3], v[176:179], v[208:211], v[0:3]
	v_mfma_f32_16x16x32_bf16 v[52:55], v[172:175], v[188:191], v[52:55]
	v_mfma_f32_16x16x32_bf16 v[48:51], v[180:183], v[188:191], v[48:51]
	v_mfma_f32_16x16x32_bf16 v[36:39], v[172:175], v[196:199], v[36:39]
	v_mfma_f32_16x16x32_bf16 v[32:35], v[180:183], v[196:199], v[32:35]
	v_mfma_f32_16x16x32_bf16 v[20:23], v[172:175], v[204:207], v[20:23]
	v_mfma_f32_16x16x32_bf16 v[16:19], v[180:183], v[204:207], v[16:19]
	v_mfma_f32_16x16x32_bf16 v[4:7], v[172:175], v[212:215], v[4:7]
	v_mfma_f32_16x16x32_bf16 v[0:3], v[180:183], v[212:215], v[0:3]
	s_add_i32 s53, s53, 2
	s_add_u32 s24, s24, 0x100
	s_addc_u32 s25, s25, 0
	s_add_u32 s51, s51, 0x100
	s_addc_u32 s52, s52, 0
	s_cmp_gt_u32 s53, 41
	s_barrier
.LBB0_861:
	ds_read_b128 v[146:149], v153
	ds_read_b128 v[156:159], v153 offset:1024
	ds_read_b128 v[160:163], v153 offset:2048
	ds_read_b128 v[164:167], v153 offset:3072
	ds_read_b128 v[168:171], v154
	ds_read_b128 v[172:175], v154 offset:1024
	ds_read_b128 v[176:179], v154 offset:2048
	ds_read_b128 v[180:183], v154 offset:3072
	s_add_u32 s26, s24, 0xfff50080
	s_addc_u32 s27, s25, -1
	s_cmp_eq_u32 s53, 40
	s_cselect_b32 s29, s5, s27
	s_cselect_b32 s28, s4, s26
	s_cselect_b32 s27, s23, s52
	s_cselect_b32 s26, s22, s51
	v_lshl_add_u64 v[150:151], s[24:25], 0, v[138:139]
	s_add_i32 m0, s33, 0xc000
	ds_read_b128 v[184:187], v155
	ds_read_b128 v[188:191], v155 offset:1024
	ds_read_b128 v[192:195], v155 offset:2048
	ds_read_b128 v[196:199], v155 offset:3072
	ds_read_b128 v[200:203], v155 offset:4096
	ds_read_b128 v[204:207], v155 offset:5120
	ds_read_b128 v[208:211], v155 offset:6144
	ds_read_b128 v[212:215], v155 offset:7168
	global_load_lds_dwordx4 v[150:151], off
	v_lshl_add_u64 v[150:151], s[24:25], 0, v[140:141]
	s_add_i32 m0, s33, 0xe000
	s_nop 0
	global_load_lds_dwordx4 v[150:151], off
	s_waitcnt vmcnt(8)
	s_bitcmp1_b32 s12, 0
	s_cbranch_scc1 .Lnl_861_4
	s_waitcnt lgkmcnt(0)
; #define PG8_STAGE(bufoff, gbase, voff) do { _Pragma("unroll") for (int _i = 0; _i < 2; ++_i) \
;         __builtin_amdgcn_global_load_lds((const unsigned*)((const char*)(gbase) + (voff)[_i]), (PG8_LAS unsigned*)(lds + (bufoff) + ldsw + _i * 8192), 16, 0, 0); } while (0)
; #define PG8_LDA(dst, b, h) do { _Pragma("unroll") for (int m = 0; m < 4; ++m) _Pragma("unroll") for (int k = 0; k < 2; ++k) dst[m][k] = *(const PG8_LAS bf16x8*)(lds + PG8_SA(b, h) + aoff + m * 2048 + k * 1024); } while (0)
; #define PG8_LDB(dst, b, h) do { _Pragma("unroll") for (int n = 0; n < 2; ++n) _Pragma("unroll") for (int k = 0; k < 2; ++k) dst[n][k] = *(const PG8_LAS bf16x8*)(lds + PG8_SB(b, h) + boff + n * 2048 + k * 1024); } while (0)
; #define PG8_MMA(ai, bj, At, Bt) do { __builtin_amdgcn_s_setprio(1); _Pragma("unroll") for (int m = 0; m < 4; ++m) _Pragma("unroll") for (int n = 0; n < 2; ++n) _Pragma("unroll") for (int k = 0; k < 2; ++k) \
;         acc[ai][bj][m][n] = __builtin_amdgcn_mfma_f32_16x16x32_bf16(Bt[n][k], At[m][k], acc[ai][bj][m][n], 0, 0, 0); __builtin_amdgcn_s_setprio(0); } while (0)
; #define PG8_WAIT_V(n) asm volatile("s_waitcnt vmcnt(" #n ")" ::: "memory")
; template <class Epi, class Sched, bool ALIGN_EPI = false, bool SP2 = false>
; __device__ __forceinline__ void gemm_phase(PG8_LAS unsigned char* lds, const Gemm g, const Sched& S, const Epi& E) {
;     ...
;             PG8_LDB(B0, 0, 0); PG8_LDB(B1, 0, 1); PG8_SCHED; PG8_LDA(At, 0, 0); PG8_STAGE(PG8_SA(1, 1), a1 + hstep, voffA);
;             PG8_WAIT_V(8); PG8_WAIT_L(0); PG8_BAR; PG8_MMA(0, 0, At, B0); PG8_MMA(0, 1, At, B1); PG8_BAR; PG8_SCHED;
;             PG8_LDA(At, 0, 1); PG8_STAGE(PG8_SB(0, 0), b2, voffB); PG8_STAGE(PG8_SB(0, 1), b2 + hstep, voffB); PG8_STAGE(PG8_SA(0, 0), a2, voffA);
;             PG8_WAIT_V(8); PG8_WAIT_L(0); PG8_BAR; PG8_MMA(1, 0, At, B0); PG8_MMA(1, 1, At, B1); PG8_BAR; PG8_SCHED;
;             PG8_LDB(B0, 1, 0); PG8_LDB(B1, 1, 1); PG8_SCHED; PG8_LDA(At, 1, 0); PG8_STAGE(PG8_SA(0, 1), a2 + hstep, voffA);
;             PG8_WAIT_V(8); PG8_WAIT_L(0); PG8_BAR; PG8_MMA(0, 0, At, B0); PG8_MMA(0, 1, At, B1); PG8_BAR; PG8_SCHED;
;             PG8_LDA(At, 1, 1); PG8_STAGE(PG8_SB(1, 0), b3, voffB); PG8_STAGE(PG8_SB(1, 1), b3 + hstep, voffB); PG8_STAGE(PG8_SA(1, 0), a3, voffA);
;             PG8_WAIT_V(8); PG8_WAIT_L(0); PG8_BAR; PG8_MMA(1, 0, At, B0); PG8_MMA(1, 1, At, B1); PG8_BAR; PG8_SCHED;
.Lnl_861_4:
	s_barrier
	s_waitcnt lgkmcnt(0)
	v_mfma_f32_16x16x32_bf16 v[124:127], v[146:149], v[184:187], v[124:127]
	v_mfma_f32_16x16x32_bf16 v[120:123], v[160:163], v[184:187], v[120:123]
	v_mfma_f32_16x16x32_bf16 v[108:111], v[146:149], v[192:195], v[108:111]
	v_mfma_f32_16x16x32_bf16 v[104:107], v[160:163], v[192:195], v[104:107]
	v_mfma_f32_16x16x32_bf16 v[92:95], v[146:149], v[200:203], v[92:95]
	v_mfma_f32_16x16x32_bf16 v[88:91], v[160:163], v[200:203], v[88:91]
	v_mfma_f32_16x16x32_bf16 v[76:79], v[146:149], v[208:211], v[76:79]
	v_mfma_f32_16x16x32_bf16 v[72:75], v[160:163], v[208:211], v[72:75]
	v_mfma_f32_16x16x32_bf16 v[124:127], v[156:159], v[188:191], v[124:127]
	v_mfma_f32_16x16x32_bf16 v[120:123], v[164:167], v[188:191], v[120:123]
	v_mfma_f32_16x16x32_bf16 v[108:111], v[156:159], v[196:199], v[108:111]
	v_mfma_f32_16x16x32_bf16 v[104:107], v[164:167], v[196:199], v[104:107]
	v_mfma_f32_16x16x32_bf16 v[92:95], v[156:159], v[204:207], v[92:95]
	v_mfma_f32_16x16x32_bf16 v[88:91], v[164:167], v[204:207], v[88:91]
	v_mfma_f32_16x16x32_bf16 v[76:79], v[156:159], v[212:215], v[76:79]
	v_mfma_f32_16x16x32_bf16 v[72:75], v[164:167], v[212:215], v[72:75]
	v_mfma_f32_16x16x32_bf16 v[116:119], v[168:171], v[184:187], v[116:119]
	v_mfma_f32_16x16x32_bf16 v[112:115], v[176:179], v[184:187], v[112:115]
	v_mfma_f32_16x16x32_bf16 v[100:103], v[168:171], v[192:195], v[100:103]
	v_mfma_f32_16x16x32_bf16 v[96:99], v[176:179], v[192:195], v[96:99]
	v_mfma_f32_16x16x32_bf16 v[84:87], v[168:171], v[200:203], v[84:87]
	v_mfma_f32_16x16x32_bf16 v[80:83], v[176:179], v[200:203], v[80:83]
	v_mfma_f32_16x16x32_bf16 v[68:71], v[168:171], v[208:211], v[68:71]
	v_mfma_f32_16x16x32_bf16 v[64:67], v[176:179], v[208:211], v[64:67]
	v_mfma_f32_16x16x32_bf16 v[116:119], v[172:175], v[188:191], v[116:119]
	v_mfma_f32_16x16x32_bf16 v[112:115], v[180:183], v[188:191], v[112:115]
	v_mfma_f32_16x16x32_bf16 v[100:103], v[172:175], v[196:199], v[100:103]
	v_mfma_f32_16x16x32_bf16 v[96:99], v[180:183], v[196:199], v[96:99]
	v_mfma_f32_16x16x32_bf16 v[84:87], v[172:175], v[204:207], v[84:87]
	v_mfma_f32_16x16x32_bf16 v[80:83], v[180:183], v[204:207], v[80:83]
	v_mfma_f32_16x16x32_bf16 v[68:71], v[172:175], v[212:215], v[68:71]
	v_mfma_f32_16x16x32_bf16 v[64:67], v[180:183], v[212:215], v[64:67]
	s_barrier
	s_add_i32 s56, s45, s31
	s_mov_b32 m0, s56
	ds_read_b128 v[184:187], v155 offset:16384
	ds_read_b128 v[188:191], v155 offset:17408
	ds_read_b128 v[192:195], v155 offset:18432
	ds_read_b128 v[196:199], v155 offset:19456
	ds_read_b128 v[200:203], v155 offset:20480
	ds_read_b128 v[204:207], v155 offset:21504
	ds_read_b128 v[208:211], v155 offset:22528
	ds_read_b128 v[212:215], v155 offset:23552
	global_load_lds_dwordx4 v130, s[26:27]
	s_add_i32 m0, s56, 0x2000
	s_add_u32 s56, s26, 0xb0000
	v_lshl_add_u64 v[216:217], s[26:27], 0, v[134:135]
	s_addc_u32 s57, s27, 0
	s_add_i32 s58, s46, s31
	global_load_lds_dwordx4 v134, s[26:27]
	s_mov_b32 m0, s58
	v_lshl_add_u64 v[220:221], s[28:29], 0, v[132:133]
	global_load_lds_dwordx4 v130, s[56:57]
	s_add_i32 m0, s58, 0x2000
	s_nop 0
	global_load_lds_dwordx4 v134, s[56:57]
	v_lshl_add_u64 v[218:219], s[28:29], 0, v[128:129]
	s_mov_b32 m0, s33
	s_nop 0
	global_load_lds_dwordx4 v128, s[28:29]
	s_mov_b32 m0, s36
	s_nop 0
	global_load_lds_dwordx4 v132, s[28:29]
	s_waitcnt vmcnt(8)
	s_bitcmp1_b32 s12, 0
	s_cbranch_scc1 .Lnl_861_5
	s_waitcnt lgkmcnt(0)
.Lnl_861_5:
	s_barrier
	s_waitcnt lgkmcnt(0)
	v_mfma_f32_16x16x32_bf16 v[60:63], v[146:149], v[184:187], v[60:63]
	v_mfma_f32_16x16x32_bf16 v[56:59], v[160:163], v[184:187], v[56:59]
	v_mfma_f32_16x16x32_bf16 v[44:47], v[146:149], v[192:195], v[44:47]
	v_mfma_f32_16x16x32_bf16 v[40:43], v[160:163], v[192:195], v[40:43]
	v_mfma_f32_16x16x32_bf16 v[28:31], v[146:149], v[200:203], v[28:31]
	v_mfma_f32_16x16x32_bf16 v[24:27], v[160:163], v[200:203], v[24:27]
	v_mfma_f32_16x16x32_bf16 v[12:15], v[146:149], v[208:211], v[12:15]
	v_mfma_f32_16x16x32_bf16 v[8:11], v[160:163], v[208:211], v[8:11]
	v_mfma_f32_16x16x32_bf16 v[60:63], v[156:159], v[188:191], v[60:63]
	v_mfma_f32_16x16x32_bf16 v[56:59], v[164:167], v[188:191], v[56:59]
	v_mfma_f32_16x16x32_bf16 v[44:47], v[156:159], v[196:199], v[44:47]
	v_mfma_f32_16x16x32_bf16 v[40:43], v[164:167], v[196:199], v[40:43]
	v_mfma_f32_16x16x32_bf16 v[28:31], v[156:159], v[204:207], v[28:31]
	v_mfma_f32_16x16x32_bf16 v[24:27], v[164:167], v[204:207], v[24:27]
	v_mfma_f32_16x16x32_bf16 v[12:15], v[156:159], v[212:215], v[12:15]
	v_mfma_f32_16x16x32_bf16 v[8:11], v[164:167], v[212:215], v[8:11]
	v_mfma_f32_16x16x32_bf16 v[52:55], v[168:171], v[184:187], v[52:55]
	v_mfma_f32_16x16x32_bf16 v[48:51], v[176:179], v[184:187], v[48:51]
	v_mfma_f32_16x16x32_bf16 v[36:39], v[168:171], v[192:195], v[36:39]
	v_mfma_f32_16x16x32_bf16 v[32:35], v[176:179], v[192:195], v[32:35]
	v_mfma_f32_16x16x32_bf16 v[20:23], v[168:171], v[200:203], v[20:23]
	v_mfma_f32_16x16x32_bf16 v[16:19], v[176:179], v[200:203], v[16:19]
	v_mfma_f32_16x16x32_bf16 v[4:7], v[168:171], v[208:211], v[4:7]
	v_mfma_f32_16x16x32_bf16 v[0:3], v[176:179], v[208:211], v[0:3]
	v_mfma_f32_16x16x32_bf16 v[52:55], v[172:175], v[188:191], v[52:55]
	v_mfma_f32_16x16x32_bf16 v[48:51], v[180:183], v[188:191], v[48:51]
	v_mfma_f32_16x16x32_bf16 v[36:39], v[172:175], v[196:199], v[36:39]
	v_mfma_f32_16x16x32_bf16 v[32:35], v[180:183], v[196:199], v[32:35]
	v_mfma_f32_16x16x32_bf16 v[20:23], v[172:175], v[204:207], v[20:23]
	v_mfma_f32_16x16x32_bf16 v[16:19], v[180:183], v[204:207], v[16:19]
	v_mfma_f32_16x16x32_bf16 v[4:7], v[172:175], v[212:215], v[4:7]
	v_mfma_f32_16x16x32_bf16 v[0:3], v[180:183], v[212:215], v[0:3]
	s_barrier
	s_add_i32 s56, 0, 0x18000
	s_add_i32 s57, 0, 0x1c000
	v_add_u32_e32 v164, s56, v152
	v_add_u32_e32 v180, s57, v152
	ds_read_b128 v[146:149], v164
	ds_read_b128 v[156:159], v164 offset:1024
	ds_read_b128 v[160:163], v164 offset:2048
	ds_read_b128 v[164:167], v164 offset:3072
	ds_read_b128 v[168:171], v180
	ds_read_b128 v[172:175], v180 offset:1024
	ds_read_b128 v[176:179], v180 offset:2048
	ds_read_b128 v[180:183], v180 offset:3072
	s_add_u32 s28, s28, 0xb0000
	s_addc_u32 s29, s29, 0
	s_mov_b32 m0, s37
	ds_read_b128 v[184:187], v155 offset:32768
	ds_read_b128 v[188:191], v155 offset:33792
	ds_read_b128 v[192:195], v155 offset:34816
	ds_read_b128 v[196:199], v155 offset:35840
	ds_read_b128 v[200:203], v155 offset:36864
	ds_read_b128 v[204:207], v155 offset:37888
	ds_read_b128 v[208:211], v155 offset:38912
	ds_read_b128 v[212:215], v155 offset:39936
	global_load_lds_dwordx4 v128, s[28:29]
	s_mov_b32 m0, s38
	s_nop 0
	global_load_lds_dwordx4 v132, s[28:29]
	s_waitcnt vmcnt(8)
	s_bitcmp1_b32 s12, 0
	s_cbranch_scc1 .Lnl_861_6
	s_waitcnt lgkmcnt(0)

; #define PG8_MMA(ai, bj, At, Bt) do { __builtin_amdgcn_s_setprio(1); _Pragma("unroll") for (int m = 0; m < 4; ++m) _Pragma("unroll") for (int n = 0; n < 2; ++n) _Pragma("unroll") for (int k = 0; k < 2; ++k) \
;         acc[ai][bj][m][n] = __builtin_amdgcn_mfma_f32_16x16x32_bf16(Bt[n][k], At[m][k], acc[ai][bj][m][n], 0, 0, 0); __builtin_amdgcn_s_setprio(0); } while (0)
; #define PG8_WAIT_V(n) asm volatile("s_waitcnt vmcnt(" #n ")" ::: "memory")
; #define PG8_WAIT_L(n) asm volatile("s_waitcnt lgkmcnt(" #n ")" ::: "memory")
; #define PG8_BAR __builtin_amdgcn_s_barrier()
; #define PG8_SCHED __builtin_amdgcn_sched_barrier(0)
; template <class Epi, class Sched, bool ALIGN_EPI = false, bool SP2 = false>
; __device__ __forceinline__ void gemm_phase(PG8_LAS unsigned char* lds, const Gemm g, const Sched& S, const Epi& E) {
;     ...
;             PG8_WAIT_V(8); PG8_WAIT_L(0); PG8_BAR; PG8_MMA(1, 0, At, B0); PG8_MMA(1, 1, At, B1); PG8_BAR; PG8_SCHED;
;     ...
;         if constexpr (ALIGN_EPI) { if (wr == 0) PG8_BAR; }
.Lnl_861_7:
	s_barrier
	s_waitcnt lgkmcnt(0)
	v_mfma_f32_16x16x32_bf16 v[60:63], v[146:149], v[184:187], v[60:63]
	v_mfma_f32_16x16x32_bf16 v[56:59], v[160:163], v[184:187], v[56:59]
	v_mfma_f32_16x16x32_bf16 v[44:47], v[146:149], v[192:195], v[44:47]
	v_mfma_f32_16x16x32_bf16 v[40:43], v[160:163], v[192:195], v[40:43]
	v_mfma_f32_16x16x32_bf16 v[28:31], v[146:149], v[200:203], v[28:31]
	v_mfma_f32_16x16x32_bf16 v[24:27], v[160:163], v[200:203], v[24:27]
	v_mfma_f32_16x16x32_bf16 v[12:15], v[146:149], v[208:211], v[12:15]
	v_mfma_f32_16x16x32_bf16 v[8:11], v[160:163], v[208:211], v[8:11]
	v_mfma_f32_16x16x32_bf16 v[60:63], v[156:159], v[188:191], v[60:63]
	v_mfma_f32_16x16x32_bf16 v[56:59], v[164:167], v[188:191], v[56:59]
	v_mfma_f32_16x16x32_bf16 v[44:47], v[156:159], v[196:199], v[44:47]
	v_mfma_f32_16x16x32_bf16 v[40:43], v[164:167], v[196:199], v[40:43]
	v_mfma_f32_16x16x32_bf16 v[28:31], v[156:159], v[204:207], v[28:31]
	v_mfma_f32_16x16x32_bf16 v[24:27], v[164:167], v[204:207], v[24:27]
	v_mfma_f32_16x16x32_bf16 v[12:15], v[156:159], v[212:215], v[12:15]
	v_mfma_f32_16x16x32_bf16 v[8:11], v[164:167], v[212:215], v[8:11]
	v_mfma_f32_16x16x32_bf16 v[52:55], v[168:171], v[184:187], v[52:55]
	v_mfma_f32_16x16x32_bf16 v[48:51], v[176:179], v[184:187], v[48:51]
	v_mfma_f32_16x16x32_bf16 v[36:39], v[168:171], v[192:195], v[36:39]
	v_mfma_f32_16x16x32_bf16 v[32:35], v[176:179], v[192:195], v[32:35]
	v_mfma_f32_16x16x32_bf16 v[20:23], v[168:171], v[200:203], v[20:23]
	v_mfma_f32_16x16x32_bf16 v[16:19], v[176:179], v[200:203], v[16:19]
	v_mfma_f32_16x16x32_bf16 v[4:7], v[168:171], v[208:211], v[4:7]
	v_mfma_f32_16x16x32_bf16 v[0:3], v[176:179], v[208:211], v[0:3]
	v_mfma_f32_16x16x32_bf16 v[52:55], v[172:175], v[188:191], v[52:55]
	v_mfma_f32_16x16x32_bf16 v[48:51], v[180:183], v[188:191], v[48:51]
	v_mfma_f32_16x16x32_bf16 v[36:39], v[172:175], v[196:199], v[36:39]
	v_mfma_f32_16x16x32_bf16 v[32:35], v[180:183], v[196:199], v[32:35]
	v_mfma_f32_16x16x32_bf16 v[20:23], v[172:175], v[204:207], v[20:23]
	v_mfma_f32_16x16x32_bf16 v[16:19], v[180:183], v[204:207], v[16:19]
	v_mfma_f32_16x16x32_bf16 v[4:7], v[172:175], v[212:215], v[4:7]
	v_mfma_f32_16x16x32_bf16 v[0:3], v[180:183], v[212:215], v[0:3]
	s_add_i32 s53, s53, 2
	s_add_u32 s24, s24, 0x100
	s_addc_u32 s25, s25, 0
	s_add_u32 s51, s51, 0x100
	s_addc_u32 s52, s52, 0
	s_cmp_gt_u32 s53, 41
	s_barrier
	s_cbranch_scc0 .LBB0_861
	s_and_b64 vcc, exec, s[12:13]
	s_cbranch_vccz .LBB0_864
	s_barrier
